# GEMM K-loops: B-operand ds_read base formed once per unit, reads use offset immediates (no per-segment v_add_u32)
# speedup vs baseline: 1.0023x; 1.0010x over previous
.LBB0_251:
	s_ashr_i32 s13, s12, 31
	s_lshl_b64 s[14:15], s[12:13], 19
	s_add_u32 s14, s29, s14
	s_addc_u32 s15, s38, s15
	s_and_b64 s[16:17], s[4:5], exec
	s_cselect_b32 s13, s15, s23
	s_cselect_b32 s19, s14, s22
	s_ashr_i32 s11, s10, 31
	s_lshl_b64 s[16:17], s[10:11], 19
	s_add_u32 s16, s39, s16
	s_addc_u32 s17, s40, s17
	s_and_b64 s[24:25], s[4:5], exec
	s_cselect_b32 s11, s17, s21
	s_cselect_b32 s61, s16, s20
	s_add_u32 s62, s20, 0x100
	s_addc_u32 s63, s21, 0
	s_add_u32 s20, s22, 0x40080
	s_addc_u32 s21, s23, 0
	s_mov_b32 s68, -2
	v_add_u32_e32 v175, 0x10000, v167
	s_add_u32 s22, s20, 0xfffc0080
	s_addc_u32 s23, s21, -1
	s_add_i32 s64, 0, 0x10000
	s_cmp_eq_u32 s68, 12
	s_cselect_b32 s25, s13, s23
	s_cselect_b32 s24, s19, s22
	s_cselect_b32 s23, s11, s63
	s_cselect_b32 s22, s61, s62
	s_lshl_b32 s74, s18, 8
	v_add_u32_e32 v178, s74, v168
	v_ashrrev_i32_e32 v179, 31, v178
	v_lshlrev_b64 v[178:179], 6, v[178:179]
	v_lshl_add_u64 v[178:179], s[70:71], 0, v[178:179]
	s_and_saveexec_b64 s[78:79], s[2:3]
	global_load_dwordx4 v[238:241], v[178:179], off
	global_load_dwordx4 v[242:245], v[178:179], off offset:16
	global_load_dwordx4 v[246:249], v[178:179], off offset:32
	global_load_dwordx4 v[250:253], v[178:179], off offset:48
	s_mov_b64 exec, s[78:79]
	s_add_i32 s69, 0, 0x14000
	ds_read_b128 v[48:51], v175
	ds_read_b128 v[56:59], v175 offset:1024
	ds_read_b128 v[136:139], v175 offset:2048
	ds_read_b128 v[140:143], v175 offset:3072
	ds_read_b128 v[156:159], v175 offset:16384
	ds_read_b128 v[160:163], v175 offset:17408
	ds_read_b128 v[182:185], v175 offset:18432
	ds_read_b128 v[186:189], v175 offset:19456
	s_add_i32 m0, s49, 0xc000
	ds_read_b128 v[190:193], v172
	ds_read_b128 v[194:197], v172 offset:1024
	ds_read_b128 v[198:201], v172 offset:2048
	ds_read_b128 v[202:205], v172 offset:3072
	ds_read_b128 v[206:209], v172 offset:4096
	ds_read_b128 v[210:213], v172 offset:5120
	ds_read_b128 v[228:231], v172 offset:6144
	ds_read_b128 v[232:235], v172 offset:7168
	global_load_lds_dwordx4 v154, s[20:21]
	s_add_i32 m0, s49, 0xe000
	s_nop 0
	global_load_lds_dwordx4 v152, s[20:21]
	s_waitcnt vmcnt(12) lgkmcnt(0)
	s_barrier
	s_setprio 1
	v_mfma_f32_16x16x32_bf16 v[132:135], v[48:51], v[190:193], 0
	v_mfma_f32_16x16x32_bf16 v[124:127], v[136:139], v[190:193], 0
	v_mfma_f32_16x16x32_bf16 v[116:119], v[48:51], v[198:201], 0
	v_mfma_f32_16x16x32_bf16 v[112:115], v[136:139], v[198:201], 0
	v_mfma_f32_16x16x32_bf16 v[100:103], v[48:51], v[206:209], 0
	v_mfma_f32_16x16x32_bf16 v[96:99], v[136:139], v[206:209], 0
	v_mfma_f32_16x16x32_bf16 v[84:87], v[48:51], v[228:231], 0
	v_mfma_f32_16x16x32_bf16 v[80:83], v[136:139], v[228:231], 0
	v_mfma_f32_16x16x32_bf16 v[132:135], v[56:59], v[194:197], v[132:135]
	v_mfma_f32_16x16x32_bf16 v[124:127], v[140:143], v[194:197], v[124:127]
	v_mfma_f32_16x16x32_bf16 v[116:119], v[56:59], v[202:205], v[116:119]
	v_mfma_f32_16x16x32_bf16 v[112:115], v[140:143], v[202:205], v[112:115]
	v_mfma_f32_16x16x32_bf16 v[100:103], v[56:59], v[210:213], v[100:103]
	v_mfma_f32_16x16x32_bf16 v[96:99], v[140:143], v[210:213], v[96:99]
	v_mfma_f32_16x16x32_bf16 v[84:87], v[56:59], v[232:235], v[84:87]
	v_mfma_f32_16x16x32_bf16 v[80:83], v[140:143], v[232:235], v[80:83]
	v_mfma_f32_16x16x32_bf16 v[128:131], v[156:159], v[190:193], 0
	v_mfma_f32_16x16x32_bf16 v[120:123], v[182:185], v[190:193], 0
	v_mfma_f32_16x16x32_bf16 v[108:111], v[156:159], v[198:201], 0
	v_mfma_f32_16x16x32_bf16 v[104:107], v[182:185], v[198:201], 0
	v_mfma_f32_16x16x32_bf16 v[92:95], v[156:159], v[206:209], 0
	v_mfma_f32_16x16x32_bf16 v[88:91], v[182:185], v[206:209], 0
	v_mfma_f32_16x16x32_bf16 v[76:79], v[156:159], v[228:231], 0
	v_mfma_f32_16x16x32_bf16 v[72:75], v[182:185], v[228:231], 0
	v_mfma_f32_16x16x32_bf16 v[128:131], v[160:163], v[194:197], v[128:131]
	v_mfma_f32_16x16x32_bf16 v[120:123], v[186:189], v[194:197], v[120:123]
	v_mfma_f32_16x16x32_bf16 v[108:111], v[160:163], v[202:205], v[108:111]
	v_mfma_f32_16x16x32_bf16 v[104:107], v[186:189], v[202:205], v[104:107]
	s_setprio 2
	s_barrier
	v_mfma_f32_16x16x32_bf16 v[92:95], v[160:163], v[210:213], v[92:95]
	v_mfma_f32_16x16x32_bf16 v[88:91], v[186:189], v[210:213], v[88:91]
	v_mfma_f32_16x16x32_bf16 v[76:79], v[160:163], v[232:235], v[76:79]
	v_mfma_f32_16x16x32_bf16 v[72:75], v[186:189], v[232:235], v[72:75]
	s_setprio 0
	s_add_i32 s64, s64, s41
	s_add_u32 s94, s22, s34
	s_addc_u32 s95, s23, s35
	s_mov_b32 m0, s64
	ds_read_b128 v[190:193], v172 offset:16384
	ds_read_b128 v[194:197], v172 offset:17408
	ds_read_b128 v[198:201], v172 offset:18432
	ds_read_b128 v[202:205], v172 offset:19456
	ds_read_b128 v[206:209], v172 offset:20480
	ds_read_b128 v[210:213], v172 offset:21504
	ds_read_b128 v[228:231], v172 offset:22528
	ds_read_b128 v[232:235], v172 offset:23552
	global_load_lds_dwordx4 v148, s[22:23]
	s_add_i32 m0, s64, 0x2000
	s_add_u32 s64, s22, 0x40000
	s_addc_u32 s65, s23, 0
	s_add_i32 s69, s69, s41
	global_load_lds_dwordx4 v144, s[22:23]
	s_mov_b32 m0, s69
	s_nop 0
	global_load_lds_dwordx4 v148, s[64:65]
	s_add_i32 m0, s69, 0x2000
	s_nop 0
	global_load_lds_dwordx4 v144, s[64:65]
	s_add_u32 s98, s24, s34
	s_addc_u32 s99, s25, s35
	s_mov_b32 m0, s49
	s_nop 0
	global_load_lds_dwordx4 v150, s[24:25]
	s_waitcnt vmcnt(7) lgkmcnt(0)
	s_barrier
	s_setprio 1
	v_mfma_f32_16x16x32_bf16 v[68:71], v[48:51], v[190:193], 0
	v_mfma_f32_16x16x32_bf16 v[64:67], v[136:139], v[190:193], 0
	v_mfma_f32_16x16x32_bf16 v[44:47], v[48:51], v[198:201], 0
	v_mfma_f32_16x16x32_bf16 v[40:43], v[136:139], v[198:201], 0
	v_mfma_f32_16x16x32_bf16 v[28:31], v[48:51], v[206:209], 0
	v_mfma_f32_16x16x32_bf16 v[24:27], v[136:139], v[206:209], 0
	v_mfma_f32_16x16x32_bf16 v[12:15], v[48:51], v[228:231], 0
	v_mfma_f32_16x16x32_bf16 v[8:11], v[136:139], v[228:231], 0
	v_mfma_f32_16x16x32_bf16 v[68:71], v[56:59], v[194:197], v[68:71]
	v_mfma_f32_16x16x32_bf16 v[64:67], v[140:143], v[194:197], v[64:67]
	v_mfma_f32_16x16x32_bf16 v[44:47], v[56:59], v[202:205], v[44:47]
	v_mfma_f32_16x16x32_bf16 v[40:43], v[140:143], v[202:205], v[40:43]
	v_mfma_f32_16x16x32_bf16 v[28:31], v[56:59], v[210:213], v[28:31]
	v_mfma_f32_16x16x32_bf16 v[24:27], v[140:143], v[210:213], v[24:27]
	v_mfma_f32_16x16x32_bf16 v[12:15], v[56:59], v[232:235], v[12:15]
	v_mfma_f32_16x16x32_bf16 v[8:11], v[140:143], v[232:235], v[8:11]
	v_mfma_f32_16x16x32_bf16 v[52:55], v[182:185], v[190:193], 0
	v_mfma_f32_16x16x32_bf16 v[36:39], v[156:159], v[198:201], 0
	v_mfma_f32_16x16x32_bf16 v[32:35], v[182:185], v[198:201], 0
	v_mfma_f32_16x16x32_bf16 v[20:23], v[156:159], v[206:209], 0
	v_mfma_f32_16x16x32_bf16 v[16:19], v[182:185], v[206:209], 0
	v_mfma_f32_16x16x32_bf16 v[4:7], v[156:159], v[228:231], 0
	v_mfma_f32_16x16x32_bf16 v[0:3], v[182:185], v[228:231], 0
	v_mfma_f32_16x16x32_bf16 v[48:51], v[156:159], v[190:193], 0
	v_mfma_f32_16x16x32_bf16 v[52:55], v[186:189], v[194:197], v[52:55]
	v_mfma_f32_16x16x32_bf16 v[36:39], v[160:163], v[202:205], v[36:39]
	v_mfma_f32_16x16x32_bf16 v[32:35], v[186:189], v[202:205], v[32:35]
	v_mfma_f32_16x16x32_bf16 v[20:23], v[160:163], v[210:213], v[20:23]
	s_setprio 2
	s_barrier
	v_mfma_f32_16x16x32_bf16 v[16:19], v[186:189], v[210:213], v[16:19]
	v_mfma_f32_16x16x32_bf16 v[4:7], v[160:163], v[232:235], v[4:7]
	v_mfma_f32_16x16x32_bf16 v[0:3], v[186:189], v[232:235], v[0:3]
	v_mfma_f32_16x16x32_bf16 v[48:51], v[160:163], v[194:197], v[48:51]
	s_setprio 0
	s_mov_b32 m0, s50
	s_nop 0
	global_load_lds_dwordx4 v146, s[24:25]
	s_and_saveexec_b64 s[78:79], s[2:3]
	v_add_f32_e32 v238, v238, v239
	v_add_f32_e32 v240, v240, v241
	v_add_f32_e32 v242, v242, v243
	v_add_f32_e32 v244, v244, v245
	v_add_f32_e32 v246, v246, v247
	v_add_f32_e32 v248, v248, v249
	v_add_f32_e32 v250, v250, v251
	v_add_f32_e32 v252, v252, v253
	v_add_f32_e32 v238, v238, v240
	v_add_f32_e32 v242, v242, v244
	v_add_f32_e32 v246, v246, v248
	v_add_f32_e32 v250, v250, v252
	v_add_f32_e32 v238, v238, v242
	v_add_f32_e32 v246, v246, v250
	v_add_f32_e32 v238, v238, v246
	v_fmamk_f32 v238, v238, 0x3a800000, v216
	v_rsq_f32_e32 v238, v238
	s_nop 0
	ds_write_b32 v169, v238
	s_mov_b64 exec, s[78:79]
	s_add_i32 s64, 0, 0x18000
	s_add_i32 s65, 0, 0x1c000
	ds_read_b128 v[56:59], v175 offset:32768
	ds_read_b128 v[60:63], v175 offset:33792
	ds_read_b128 v[136:139], v175 offset:34816
	ds_read_b128 v[140:143], v175 offset:35840
	ds_read_b128 v[156:159], v175 offset:49152
	ds_read_b128 v[160:163], v175 offset:50176
	ds_read_b128 v[182:185], v175 offset:51200
	ds_read_b128 v[186:189], v175 offset:52224
	s_add_u32 s24, s24, 0x40000
	s_addc_u32 s25, s25, 0
	s_mov_b32 m0, s51
	ds_read_b128 v[190:193], v172 offset:32768
	ds_read_b128 v[194:197], v172 offset:33792
	ds_read_b128 v[198:201], v172 offset:34816
	ds_read_b128 v[202:205], v172 offset:35840
	ds_read_b128 v[206:209], v172 offset:36864
	ds_read_b128 v[210:213], v172 offset:37888
	ds_read_b128 v[228:231], v172 offset:38912
	ds_read_b128 v[232:235], v172 offset:39936
	global_load_lds_dwordx4 v150, s[24:25]
	s_mov_b32 m0, s52
	s_nop 0
	global_load_lds_dwordx4 v146, s[24:25]
	s_waitcnt vmcnt(8) lgkmcnt(0)
	s_barrier
	s_setprio 1
	v_mfma_f32_16x16x32_bf16 v[132:135], v[56:59], v[190:193], v[132:135]
	v_mfma_f32_16x16x32_bf16 v[124:127], v[136:139], v[190:193], v[124:127]
	v_mfma_f32_16x16x32_bf16 v[116:119], v[56:59], v[198:201], v[116:119]
	v_mfma_f32_16x16x32_bf16 v[112:115], v[136:139], v[198:201], v[112:115]
	v_mfma_f32_16x16x32_bf16 v[100:103], v[56:59], v[206:209], v[100:103]
	v_mfma_f32_16x16x32_bf16 v[96:99], v[136:139], v[206:209], v[96:99]
	v_mfma_f32_16x16x32_bf16 v[84:87], v[56:59], v[228:231], v[84:87]
	v_mfma_f32_16x16x32_bf16 v[80:83], v[136:139], v[228:231], v[80:83]
	v_mfma_f32_16x16x32_bf16 v[132:135], v[60:63], v[194:197], v[132:135]
	v_mfma_f32_16x16x32_bf16 v[124:127], v[140:143], v[194:197], v[124:127]
	v_mfma_f32_16x16x32_bf16 v[116:119], v[60:63], v[202:205], v[116:119]
	v_mfma_f32_16x16x32_bf16 v[112:115], v[140:143], v[202:205], v[112:115]
	v_mfma_f32_16x16x32_bf16 v[100:103], v[60:63], v[210:213], v[100:103]
	v_mfma_f32_16x16x32_bf16 v[96:99], v[140:143], v[210:213], v[96:99]
	v_mfma_f32_16x16x32_bf16 v[84:87], v[60:63], v[232:235], v[84:87]
	v_mfma_f32_16x16x32_bf16 v[80:83], v[140:143], v[232:235], v[80:83]
	v_mfma_f32_16x16x32_bf16 v[128:131], v[156:159], v[190:193], v[128:131]
	v_mfma_f32_16x16x32_bf16 v[120:123], v[182:185], v[190:193], v[120:123]
	v_mfma_f32_16x16x32_bf16 v[108:111], v[156:159], v[198:201], v[108:111]
	v_mfma_f32_16x16x32_bf16 v[104:107], v[182:185], v[198:201], v[104:107]
	v_mfma_f32_16x16x32_bf16 v[92:95], v[156:159], v[206:209], v[92:95]
	v_mfma_f32_16x16x32_bf16 v[88:91], v[182:185], v[206:209], v[88:91]
	v_mfma_f32_16x16x32_bf16 v[76:79], v[156:159], v[228:231], v[76:79]
	v_mfma_f32_16x16x32_bf16 v[72:75], v[182:185], v[228:231], v[72:75]
	v_mfma_f32_16x16x32_bf16 v[128:131], v[160:163], v[194:197], v[128:131]
	v_mfma_f32_16x16x32_bf16 v[120:123], v[186:189], v[194:197], v[120:123]
	v_mfma_f32_16x16x32_bf16 v[108:111], v[160:163], v[202:205], v[108:111]
	v_mfma_f32_16x16x32_bf16 v[104:107], v[186:189], v[202:205], v[104:107]
	s_setprio 2
	s_barrier
	v_mfma_f32_16x16x32_bf16 v[92:95], v[160:163], v[210:213], v[92:95]
	v_mfma_f32_16x16x32_bf16 v[88:91], v[186:189], v[210:213], v[88:91]
	v_mfma_f32_16x16x32_bf16 v[76:79], v[160:163], v[232:235], v[76:79]
	v_mfma_f32_16x16x32_bf16 v[72:75], v[186:189], v[232:235], v[72:75]
	s_setprio 0
	s_min_i32 s74, s18, 0x80
	s_ashr_i32 s74, s74, 3
	s_mul_hi_i32 s75, s74, 0x5800
	s_mulk_i32 s74, 0x5800
	s_add_u32 s74, s53, s74
	s_addc_u32 s75, s54, s75
	s_lshl_b32 s76, s60, 8
	s_ashr_i32 s77, s76, 31
	s_lshl_b64 s[76:77], s[76:77], 2
	s_add_u32 s74, s74, s76
	s_addc_u32 s75, s75, s77
	s_add_u32 s74, s74, s59
	s_addc_u32 s75, s75, 0
	v_lshl_add_u64 v[178:179], s[74:75], 0, v[176:177]
	global_load_dwordx4 v[238:241], v[178:179], off
	global_load_dwordx4 v[242:245], v[178:179], off offset:16
	global_load_dwordx4 v[246:249], v[178:179], off offset:512
	global_load_dwordx4 v[250:253], v[178:179], off offset:528
	s_add_i32 s24, s64, s41
	s_mov_b32 m0, s24
	ds_read_b128 v[190:193], v172 offset:49152
	ds_read_b128 v[194:197], v172 offset:50176
	ds_read_b128 v[198:201], v172 offset:51200
	ds_read_b128 v[202:205], v172 offset:52224
	ds_read_b128 v[206:209], v172 offset:53248
	ds_read_b128 v[210:213], v172 offset:54272
	ds_read_b128 v[228:231], v172 offset:55296
	ds_read_b128 v[232:235], v172 offset:56320
	global_load_lds_dwordx4 v148, s[94:95]
	s_add_i32 m0, s24, 0x2000
	s_add_u32 s22, s22, 0x40080
	s_addc_u32 s23, s23, 0
	s_add_i32 s24, s65, s41
	global_load_lds_dwordx4 v144, s[94:95]
	s_mov_b32 m0, s24
	s_nop 0
	global_load_lds_dwordx4 v148, s[22:23]
	s_add_i32 m0, s24, 0x2000
	s_nop 0
	global_load_lds_dwordx4 v144, s[22:23]
	s_mov_b32 m0, s55
	s_nop 0
	global_load_lds_dwordx4 v150, s[98:99]
	s_mov_b32 m0, s56
	s_nop 0
	global_load_lds_dwordx4 v146, s[98:99]
	s_waitcnt vmcnt(12) lgkmcnt(0)
	s_barrier
	s_setprio 1
	v_mfma_f32_16x16x32_bf16 v[68:71], v[56:59], v[190:193], v[68:71]
	v_mfma_f32_16x16x32_bf16 v[64:67], v[136:139], v[190:193], v[64:67]
	v_mfma_f32_16x16x32_bf16 v[44:47], v[56:59], v[198:201], v[44:47]
	v_mfma_f32_16x16x32_bf16 v[40:43], v[136:139], v[198:201], v[40:43]
	v_mfma_f32_16x16x32_bf16 v[28:31], v[56:59], v[206:209], v[28:31]
	v_mfma_f32_16x16x32_bf16 v[24:27], v[136:139], v[206:209], v[24:27]
	v_mfma_f32_16x16x32_bf16 v[12:15], v[56:59], v[228:231], v[12:15]
	v_mfma_f32_16x16x32_bf16 v[8:11], v[136:139], v[228:231], v[8:11]
	v_mfma_f32_16x16x32_bf16 v[68:71], v[60:63], v[194:197], v[68:71]
	v_mfma_f32_16x16x32_bf16 v[64:67], v[140:143], v[194:197], v[64:67]
	v_mfma_f32_16x16x32_bf16 v[44:47], v[60:63], v[202:205], v[44:47]
	v_mfma_f32_16x16x32_bf16 v[40:43], v[140:143], v[202:205], v[40:43]
	v_mfma_f32_16x16x32_bf16 v[28:31], v[60:63], v[210:213], v[28:31]
	v_mfma_f32_16x16x32_bf16 v[24:27], v[140:143], v[210:213], v[24:27]
	v_mfma_f32_16x16x32_bf16 v[12:15], v[60:63], v[232:235], v[12:15]
	v_mfma_f32_16x16x32_bf16 v[8:11], v[140:143], v[232:235], v[8:11]
	v_mfma_f32_16x16x32_bf16 v[48:51], v[156:159], v[190:193], v[48:51]
	v_mfma_f32_16x16x32_bf16 v[60:63], v[160:163], v[194:197], v[48:51]
	v_mfma_f32_16x16x32_bf16 v[48:51], v[182:185], v[190:193], v[52:55]
	v_mfma_f32_16x16x32_bf16 v[36:39], v[156:159], v[198:201], v[36:39]
	v_mfma_f32_16x16x32_bf16 v[32:35], v[182:185], v[198:201], v[32:35]
	v_mfma_f32_16x16x32_bf16 v[20:23], v[156:159], v[206:209], v[20:23]
	v_mfma_f32_16x16x32_bf16 v[16:19], v[182:185], v[206:209], v[16:19]
	v_mfma_f32_16x16x32_bf16 v[4:7], v[156:159], v[228:231], v[4:7]
	v_mfma_f32_16x16x32_bf16 v[0:3], v[182:185], v[228:231], v[0:3]
	v_mfma_f32_16x16x32_bf16 v[52:55], v[186:189], v[194:197], v[48:51]
	v_mfma_f32_16x16x32_bf16 v[36:39], v[160:163], v[202:205], v[36:39]
	v_mfma_f32_16x16x32_bf16 v[32:35], v[186:189], v[202:205], v[32:35]
	s_setprio 2
	s_barrier
	v_mfma_f32_16x16x32_bf16 v[20:23], v[160:163], v[210:213], v[20:23]
	v_mfma_f32_16x16x32_bf16 v[16:19], v[186:189], v[210:213], v[16:19]
	v_mfma_f32_16x16x32_bf16 v[4:7], v[160:163], v[232:235], v[4:7]
	v_mfma_f32_16x16x32_bf16 v[0:3], v[186:189], v[232:235], v[0:3]
	s_setprio 0
	s_add_i32 s68, s68, 2
	s_add_u32 s62, s62, 0x100
	s_addc_u32 s63, s63, 0
	s_add_u32 s20, s20, 0x100
	s_addc_u32 s21, s21, 0
	s_cmp_gt_u32 s68, 13
.LBB0_252:
	s_add_u32 s22, s20, 0xfffc0080
	s_addc_u32 s23, s21, -1
	s_add_i32 s64, 0, 0x10000
	s_cmp_eq_u32 s68, 12
	s_cselect_b32 s25, s13, s23
	s_cselect_b32 s24, s19, s22
	s_cselect_b32 s23, s11, s63
	s_cselect_b32 s22, s61, s62
	s_add_i32 s69, 0, 0x14000
	ds_read_b128 v[48:51], v175
	ds_read_b128 v[56:59], v175 offset:1024
	ds_read_b128 v[136:139], v175 offset:2048
	ds_read_b128 v[140:143], v175 offset:3072
	ds_read_b128 v[156:159], v175 offset:16384
	ds_read_b128 v[160:163], v175 offset:17408
	ds_read_b128 v[182:185], v175 offset:18432
	ds_read_b128 v[186:189], v175 offset:19456
	s_add_i32 m0, s49, 0xc000
	ds_read_b128 v[190:193], v172
	ds_read_b128 v[194:197], v172 offset:1024
	ds_read_b128 v[198:201], v172 offset:2048
	ds_read_b128 v[202:205], v172 offset:3072
	ds_read_b128 v[206:209], v172 offset:4096
	ds_read_b128 v[210:213], v172 offset:5120
	ds_read_b128 v[228:231], v172 offset:6144
	ds_read_b128 v[232:235], v172 offset:7168
	global_load_lds_dwordx4 v154, s[20:21]
	s_add_i32 m0, s49, 0xe000
	s_nop 0
	global_load_lds_dwordx4 v152, s[20:21]
	s_waitcnt vmcnt(8) lgkmcnt(0)
	s_barrier
	s_setprio 1
	v_mfma_f32_16x16x32_bf16 v[132:135], v[48:51], v[190:193], v[132:135]
	v_mfma_f32_16x16x32_bf16 v[124:127], v[136:139], v[190:193], v[124:127]
	v_mfma_f32_16x16x32_bf16 v[116:119], v[48:51], v[198:201], v[116:119]
	v_mfma_f32_16x16x32_bf16 v[112:115], v[136:139], v[198:201], v[112:115]
	v_mfma_f32_16x16x32_bf16 v[100:103], v[48:51], v[206:209], v[100:103]
	v_mfma_f32_16x16x32_bf16 v[96:99], v[136:139], v[206:209], v[96:99]
	v_mfma_f32_16x16x32_bf16 v[84:87], v[48:51], v[228:231], v[84:87]
	v_mfma_f32_16x16x32_bf16 v[80:83], v[136:139], v[228:231], v[80:83]
	v_mfma_f32_16x16x32_bf16 v[132:135], v[56:59], v[194:197], v[132:135]
	v_mfma_f32_16x16x32_bf16 v[124:127], v[140:143], v[194:197], v[124:127]
	v_mfma_f32_16x16x32_bf16 v[116:119], v[56:59], v[202:205], v[116:119]
	v_mfma_f32_16x16x32_bf16 v[112:115], v[140:143], v[202:205], v[112:115]
	v_mfma_f32_16x16x32_bf16 v[100:103], v[56:59], v[210:213], v[100:103]
	v_mfma_f32_16x16x32_bf16 v[96:99], v[140:143], v[210:213], v[96:99]
	v_mfma_f32_16x16x32_bf16 v[84:87], v[56:59], v[232:235], v[84:87]
	v_mfma_f32_16x16x32_bf16 v[80:83], v[140:143], v[232:235], v[80:83]
	v_mfma_f32_16x16x32_bf16 v[128:131], v[156:159], v[190:193], v[128:131]
	v_mfma_f32_16x16x32_bf16 v[120:123], v[182:185], v[190:193], v[120:123]
	v_mfma_f32_16x16x32_bf16 v[108:111], v[156:159], v[198:201], v[108:111]
	v_mfma_f32_16x16x32_bf16 v[104:107], v[182:185], v[198:201], v[104:107]
	v_mfma_f32_16x16x32_bf16 v[92:95], v[156:159], v[206:209], v[92:95]
	v_mfma_f32_16x16x32_bf16 v[88:91], v[182:185], v[206:209], v[88:91]
	v_mfma_f32_16x16x32_bf16 v[76:79], v[156:159], v[228:231], v[76:79]
	v_mfma_f32_16x16x32_bf16 v[72:75], v[182:185], v[228:231], v[72:75]
	v_mfma_f32_16x16x32_bf16 v[128:131], v[160:163], v[194:197], v[128:131]
	v_mfma_f32_16x16x32_bf16 v[120:123], v[186:189], v[194:197], v[120:123]
	v_mfma_f32_16x16x32_bf16 v[108:111], v[160:163], v[202:205], v[108:111]
	v_mfma_f32_16x16x32_bf16 v[104:107], v[186:189], v[202:205], v[104:107]
	s_setprio 2
	s_barrier
	v_mfma_f32_16x16x32_bf16 v[92:95], v[160:163], v[210:213], v[92:95]
	v_mfma_f32_16x16x32_bf16 v[88:91], v[186:189], v[210:213], v[88:91]
	v_mfma_f32_16x16x32_bf16 v[76:79], v[160:163], v[232:235], v[76:79]
	v_mfma_f32_16x16x32_bf16 v[72:75], v[186:189], v[232:235], v[72:75]
	s_setprio 0
	s_add_i32 s64, s64, s41
	s_add_u32 s94, s22, s34
	s_addc_u32 s95, s23, s35
	s_mov_b32 m0, s64
	ds_read_b128 v[190:193], v172 offset:16384
	ds_read_b128 v[194:197], v172 offset:17408
	ds_read_b128 v[198:201], v172 offset:18432
	ds_read_b128 v[202:205], v172 offset:19456
	ds_read_b128 v[206:209], v172 offset:20480
	ds_read_b128 v[210:213], v172 offset:21504
	ds_read_b128 v[228:231], v172 offset:22528
	ds_read_b128 v[232:235], v172 offset:23552
	global_load_lds_dwordx4 v148, s[22:23]
	s_add_i32 m0, s64, 0x2000
	s_add_u32 s64, s22, 0x40000
	s_addc_u32 s65, s23, 0
	s_add_i32 s69, s69, s41
	global_load_lds_dwordx4 v144, s[22:23]
	s_mov_b32 m0, s69
	s_nop 0
	global_load_lds_dwordx4 v148, s[64:65]
	s_add_i32 m0, s69, 0x2000
	s_nop 0
	global_load_lds_dwordx4 v144, s[64:65]
	s_add_u32 s98, s24, s34
	s_addc_u32 s99, s25, s35
	s_mov_b32 m0, s49
	s_nop 0
	global_load_lds_dwordx4 v150, s[24:25]
	s_waitcnt vmcnt(7) lgkmcnt(0)
	s_barrier
	s_setprio 1
	v_mfma_f32_16x16x32_bf16 v[68:71], v[48:51], v[190:193], v[68:71]
	v_mfma_f32_16x16x32_bf16 v[64:67], v[136:139], v[190:193], v[64:67]
	v_mfma_f32_16x16x32_bf16 v[44:47], v[48:51], v[198:201], v[44:47]
	v_mfma_f32_16x16x32_bf16 v[40:43], v[136:139], v[198:201], v[40:43]
	v_mfma_f32_16x16x32_bf16 v[28:31], v[48:51], v[206:209], v[28:31]
	v_mfma_f32_16x16x32_bf16 v[24:27], v[136:139], v[206:209], v[24:27]
	v_mfma_f32_16x16x32_bf16 v[12:15], v[48:51], v[228:231], v[12:15]
	v_mfma_f32_16x16x32_bf16 v[8:11], v[136:139], v[228:231], v[8:11]
	v_mfma_f32_16x16x32_bf16 v[68:71], v[56:59], v[194:197], v[68:71]
	v_mfma_f32_16x16x32_bf16 v[64:67], v[140:143], v[194:197], v[64:67]
	v_mfma_f32_16x16x32_bf16 v[44:47], v[56:59], v[202:205], v[44:47]
	v_mfma_f32_16x16x32_bf16 v[40:43], v[140:143], v[202:205], v[40:43]
	v_mfma_f32_16x16x32_bf16 v[28:31], v[56:59], v[210:213], v[28:31]
	v_mfma_f32_16x16x32_bf16 v[24:27], v[140:143], v[210:213], v[24:27]
	v_mfma_f32_16x16x32_bf16 v[12:15], v[56:59], v[232:235], v[12:15]
	v_mfma_f32_16x16x32_bf16 v[8:11], v[140:143], v[232:235], v[8:11]
	v_mfma_f32_16x16x32_bf16 v[52:55], v[182:185], v[190:193], v[52:55]
	v_mfma_f32_16x16x32_bf16 v[36:39], v[156:159], v[198:201], v[36:39]
	v_mfma_f32_16x16x32_bf16 v[32:35], v[182:185], v[198:201], v[32:35]
	v_mfma_f32_16x16x32_bf16 v[20:23], v[156:159], v[206:209], v[20:23]
	v_mfma_f32_16x16x32_bf16 v[16:19], v[182:185], v[206:209], v[16:19]
	v_mfma_f32_16x16x32_bf16 v[4:7], v[156:159], v[228:231], v[4:7]
	v_mfma_f32_16x16x32_bf16 v[0:3], v[182:185], v[228:231], v[0:3]
	v_mfma_f32_16x16x32_bf16 v[48:51], v[156:159], v[190:193], v[60:63]
	v_mfma_f32_16x16x32_bf16 v[52:55], v[186:189], v[194:197], v[52:55]
	v_mfma_f32_16x16x32_bf16 v[36:39], v[160:163], v[202:205], v[36:39]
	v_mfma_f32_16x16x32_bf16 v[32:35], v[186:189], v[202:205], v[32:35]
	v_mfma_f32_16x16x32_bf16 v[20:23], v[160:163], v[210:213], v[20:23]
	s_setprio 2
	s_barrier
	v_mfma_f32_16x16x32_bf16 v[16:19], v[186:189], v[210:213], v[16:19]
	v_mfma_f32_16x16x32_bf16 v[4:7], v[160:163], v[232:235], v[4:7]
	v_mfma_f32_16x16x32_bf16 v[0:3], v[186:189], v[232:235], v[0:3]
	v_mfma_f32_16x16x32_bf16 v[48:51], v[160:163], v[194:197], v[48:51]
	s_setprio 0
	s_mov_b32 m0, s50
	s_nop 0
	global_load_lds_dwordx4 v146, s[24:25]
	s_add_i32 s64, 0, 0x18000
	s_add_i32 s65, 0, 0x1c000
	ds_read_b128 v[56:59], v175 offset:32768
	ds_read_b128 v[60:63], v175 offset:33792
	ds_read_b128 v[136:139], v175 offset:34816
	ds_read_b128 v[140:143], v175 offset:35840
	ds_read_b128 v[156:159], v175 offset:49152
	ds_read_b128 v[160:163], v175 offset:50176
	ds_read_b128 v[182:185], v175 offset:51200
	ds_read_b128 v[186:189], v175 offset:52224
	s_add_u32 s24, s24, 0x40000
	s_addc_u32 s25, s25, 0
	s_mov_b32 m0, s51
	ds_read_b128 v[190:193], v172 offset:32768
	ds_read_b128 v[194:197], v172 offset:33792
	ds_read_b128 v[198:201], v172 offset:34816
	ds_read_b128 v[202:205], v172 offset:35840
	ds_read_b128 v[206:209], v172 offset:36864
	ds_read_b128 v[210:213], v172 offset:37888
	ds_read_b128 v[228:231], v172 offset:38912
	ds_read_b128 v[232:235], v172 offset:39936
	global_load_lds_dwordx4 v150, s[24:25]
	s_mov_b32 m0, s52
	s_nop 0
	global_load_lds_dwordx4 v146, s[24:25]
	s_waitcnt vmcnt(8) lgkmcnt(0)
	s_barrier
	s_setprio 1
	v_mfma_f32_16x16x32_bf16 v[132:135], v[56:59], v[190:193], v[132:135]
	v_mfma_f32_16x16x32_bf16 v[124:127], v[136:139], v[190:193], v[124:127]
	v_mfma_f32_16x16x32_bf16 v[116:119], v[56:59], v[198:201], v[116:119]
	v_mfma_f32_16x16x32_bf16 v[112:115], v[136:139], v[198:201], v[112:115]
	v_mfma_f32_16x16x32_bf16 v[100:103], v[56:59], v[206:209], v[100:103]
	v_mfma_f32_16x16x32_bf16 v[96:99], v[136:139], v[206:209], v[96:99]
	v_mfma_f32_16x16x32_bf16 v[84:87], v[56:59], v[228:231], v[84:87]
	v_mfma_f32_16x16x32_bf16 v[80:83], v[136:139], v[228:231], v[80:83]
	v_mfma_f32_16x16x32_bf16 v[132:135], v[60:63], v[194:197], v[132:135]
	v_mfma_f32_16x16x32_bf16 v[124:127], v[140:143], v[194:197], v[124:127]
	v_mfma_f32_16x16x32_bf16 v[116:119], v[60:63], v[202:205], v[116:119]
	v_mfma_f32_16x16x32_bf16 v[112:115], v[140:143], v[202:205], v[112:115]
	v_mfma_f32_16x16x32_bf16 v[100:103], v[60:63], v[210:213], v[100:103]
	v_mfma_f32_16x16x32_bf16 v[96:99], v[140:143], v[210:213], v[96:99]
	v_mfma_f32_16x16x32_bf16 v[84:87], v[60:63], v[232:235], v[84:87]
	v_mfma_f32_16x16x32_bf16 v[80:83], v[140:143], v[232:235], v[80:83]
	v_mfma_f32_16x16x32_bf16 v[128:131], v[156:159], v[190:193], v[128:131]
	v_mfma_f32_16x16x32_bf16 v[120:123], v[182:185], v[190:193], v[120:123]
	v_mfma_f32_16x16x32_bf16 v[108:111], v[156:159], v[198:201], v[108:111]
	v_mfma_f32_16x16x32_bf16 v[104:107], v[182:185], v[198:201], v[104:107]
	v_mfma_f32_16x16x32_bf16 v[92:95], v[156:159], v[206:209], v[92:95]
	v_mfma_f32_16x16x32_bf16 v[88:91], v[182:185], v[206:209], v[88:91]
	v_mfma_f32_16x16x32_bf16 v[76:79], v[156:159], v[228:231], v[76:79]
	v_mfma_f32_16x16x32_bf16 v[72:75], v[182:185], v[228:231], v[72:75]
	v_mfma_f32_16x16x32_bf16 v[128:131], v[160:163], v[194:197], v[128:131]
	v_mfma_f32_16x16x32_bf16 v[120:123], v[186:189], v[194:197], v[120:123]
	v_mfma_f32_16x16x32_bf16 v[108:111], v[160:163], v[202:205], v[108:111]
	v_mfma_f32_16x16x32_bf16 v[104:107], v[186:189], v[202:205], v[104:107]
	s_setprio 2
	s_barrier
	v_mfma_f32_16x16x32_bf16 v[92:95], v[160:163], v[210:213], v[92:95]
	v_mfma_f32_16x16x32_bf16 v[88:91], v[186:189], v[210:213], v[88:91]
	v_mfma_f32_16x16x32_bf16 v[76:79], v[160:163], v[232:235], v[76:79]
	v_mfma_f32_16x16x32_bf16 v[72:75], v[186:189], v[232:235], v[72:75]
	s_setprio 0
	s_add_i32 s24, s64, s41
	s_mov_b32 m0, s24
	ds_read_b128 v[190:193], v172 offset:49152
	ds_read_b128 v[194:197], v172 offset:50176
	ds_read_b128 v[198:201], v172 offset:51200
	ds_read_b128 v[202:205], v172 offset:52224
	ds_read_b128 v[206:209], v172 offset:53248
	ds_read_b128 v[210:213], v172 offset:54272
	ds_read_b128 v[228:231], v172 offset:55296
	ds_read_b128 v[232:235], v172 offset:56320
	global_load_lds_dwordx4 v148, s[94:95]
	s_add_i32 m0, s24, 0x2000
	s_add_u32 s22, s22, 0x40080
	s_addc_u32 s23, s23, 0
	s_add_i32 s24, s65, s41
	global_load_lds_dwordx4 v144, s[94:95]
	s_mov_b32 m0, s24
	s_nop 0
	global_load_lds_dwordx4 v148, s[22:23]
	s_add_i32 m0, s24, 0x2000
	s_nop 0
	global_load_lds_dwordx4 v144, s[22:23]
	s_mov_b32 m0, s55
	s_nop 0
	global_load_lds_dwordx4 v150, s[98:99]
	s_mov_b32 m0, s56
	s_nop 0
	global_load_lds_dwordx4 v146, s[98:99]
	s_waitcnt vmcnt(8) lgkmcnt(0)
	s_barrier
	s_setprio 1
	v_mfma_f32_16x16x32_bf16 v[68:71], v[56:59], v[190:193], v[68:71]
	v_mfma_f32_16x16x32_bf16 v[64:67], v[136:139], v[190:193], v[64:67]
	v_mfma_f32_16x16x32_bf16 v[44:47], v[56:59], v[198:201], v[44:47]
	v_mfma_f32_16x16x32_bf16 v[40:43], v[136:139], v[198:201], v[40:43]
	v_mfma_f32_16x16x32_bf16 v[28:31], v[56:59], v[206:209], v[28:31]
	v_mfma_f32_16x16x32_bf16 v[24:27], v[136:139], v[206:209], v[24:27]
	v_mfma_f32_16x16x32_bf16 v[12:15], v[56:59], v[228:231], v[12:15]
	v_mfma_f32_16x16x32_bf16 v[8:11], v[136:139], v[228:231], v[8:11]
	v_mfma_f32_16x16x32_bf16 v[68:71], v[60:63], v[194:197], v[68:71]
	v_mfma_f32_16x16x32_bf16 v[64:67], v[140:143], v[194:197], v[64:67]
	v_mfma_f32_16x16x32_bf16 v[44:47], v[60:63], v[202:205], v[44:47]
	v_mfma_f32_16x16x32_bf16 v[40:43], v[140:143], v[202:205], v[40:43]
	v_mfma_f32_16x16x32_bf16 v[28:31], v[60:63], v[210:213], v[28:31]
	v_mfma_f32_16x16x32_bf16 v[24:27], v[140:143], v[210:213], v[24:27]
	v_mfma_f32_16x16x32_bf16 v[12:15], v[60:63], v[232:235], v[12:15]
	v_mfma_f32_16x16x32_bf16 v[8:11], v[140:143], v[232:235], v[8:11]
	v_mfma_f32_16x16x32_bf16 v[48:51], v[156:159], v[190:193], v[48:51]
	v_mfma_f32_16x16x32_bf16 v[60:63], v[160:163], v[194:197], v[48:51]
	v_mfma_f32_16x16x32_bf16 v[48:51], v[182:185], v[190:193], v[52:55]
	v_mfma_f32_16x16x32_bf16 v[36:39], v[156:159], v[198:201], v[36:39]
	v_mfma_f32_16x16x32_bf16 v[32:35], v[182:185], v[198:201], v[32:35]
	v_mfma_f32_16x16x32_bf16 v[20:23], v[156:159], v[206:209], v[20:23]
	v_mfma_f32_16x16x32_bf16 v[16:19], v[182:185], v[206:209], v[16:19]
	v_mfma_f32_16x16x32_bf16 v[4:7], v[156:159], v[228:231], v[4:7]
	v_mfma_f32_16x16x32_bf16 v[0:3], v[182:185], v[228:231], v[0:3]
	v_mfma_f32_16x16x32_bf16 v[52:55], v[186:189], v[194:197], v[48:51]
	v_mfma_f32_16x16x32_bf16 v[36:39], v[160:163], v[202:205], v[36:39]
	v_mfma_f32_16x16x32_bf16 v[32:35], v[186:189], v[202:205], v[32:35]
	s_setprio 2
	s_barrier
	v_mfma_f32_16x16x32_bf16 v[20:23], v[160:163], v[210:213], v[20:23]
	v_mfma_f32_16x16x32_bf16 v[16:19], v[186:189], v[210:213], v[16:19]
	v_mfma_f32_16x16x32_bf16 v[4:7], v[160:163], v[232:235], v[4:7]
	v_mfma_f32_16x16x32_bf16 v[0:3], v[186:189], v[232:235], v[0:3]
	s_setprio 0
	s_add_i32 s68, s68, 2
	s_add_u32 s62, s62, 0x100
	s_addc_u32 s63, s63, 0
	s_add_u32 s20, s20, 0x100
	s_addc_u32 s21, s21, 0
	s_cmp_gt_u32 s68, 13
	s_cbranch_scc0 .LBB0_252
	s_and_b64 vcc, exec, s[8:9]
	s_cbranch_vccz .LBB0_255
	s_barrier

.LBB0_318:
	s_ashr_i32 s15, s14, 31
	s_lshl_b64 s[16:17], s[14:15], 19
	s_add_u32 s16, s37, s16
	s_addc_u32 s17, s42, s17
	s_and_b64 s[18:19], s[6:7], exec
	s_cselect_b32 s9, s17, s25
	s_cselect_b32 s15, s16, s24
	s_ashr_i32 s13, s12, 31
	s_lshl_b64 s[18:19], s[12:13], 19
	s_add_u32 s18, s38, s18
	s_addc_u32 s19, s39, s19
	s_and_b64 s[26:27], s[6:7], exec
	s_cselect_b32 s13, s19, s23
	s_cselect_b32 s21, s18, s22
	s_add_u32 s44, s22, 0x100
	s_addc_u32 s62, s23, 0
	s_add_u32 s22, s24, 0x40080
	s_addc_u32 s23, s25, 0
	s_mov_b32 s63, -2
	v_add_u32_e32 v175, 0x10000, v159
	s_add_u32 s24, s22, 0xfffc0080
	s_addc_u32 s25, s23, -1
	s_add_i32 s64, 0, 0x10000
	s_cmp_eq_u32 s63, 12
	s_cselect_b32 s27, s9, s25
	s_cselect_b32 s26, s15, s24
	s_cselect_b32 s25, s13, s62
	s_cselect_b32 s24, s21, s44
	s_add_i32 s68, 0, 0x14000
	ds_read_b128 v[96:99], v175
	ds_read_b128 v[100:103], v175 offset:1024
	ds_read_b128 v[108:111], v175 offset:2048
	ds_read_b128 v[112:115], v175 offset:3072
	ds_read_b128 v[154:157], v175 offset:16384
	ds_read_b128 v[166:169], v175 offset:17408
	ds_read_b128 v[170:173], v175 offset:18432
	ds_read_b128 v[182:185], v175 offset:19456
	s_add_i32 m0, s50, 0xc000
	ds_read_b128 v[186:189], v164
	ds_read_b128 v[190:193], v164 offset:1024
	ds_read_b128 v[194:197], v164 offset:2048
	ds_read_b128 v[198:201], v164 offset:3072
	ds_read_b128 v[202:205], v164 offset:4096
	ds_read_b128 v[206:209], v164 offset:5120
	ds_read_b128 v[210:213], v164 offset:6144
	ds_read_b128 v[228:231], v164 offset:7168
	global_load_lds_dwordx4 v152, s[22:23]
	s_add_i32 m0, s50, 0xe000
	s_nop 0
	global_load_lds_dwordx4 v150, s[22:23]
	s_waitcnt vmcnt(8) lgkmcnt(0)
	s_barrier
	s_setprio 1
	v_mfma_f32_16x16x32_bf16 v[140:143], v[96:99], v[186:189], 0
	v_mfma_f32_16x16x32_bf16 v[136:139], v[108:111], v[186:189], 0
	v_mfma_f32_16x16x32_bf16 v[124:127], v[96:99], v[194:197], 0
	v_mfma_f32_16x16x32_bf16 v[120:123], v[108:111], v[194:197], 0
	v_mfma_f32_16x16x32_bf16 v[92:95], v[96:99], v[202:205], 0
	v_mfma_f32_16x16x32_bf16 v[88:91], v[108:111], v[202:205], 0
	v_mfma_f32_16x16x32_bf16 v[76:79], v[96:99], v[210:213], 0
	v_mfma_f32_16x16x32_bf16 v[72:75], v[108:111], v[210:213], 0
	v_mfma_f32_16x16x32_bf16 v[140:143], v[100:103], v[190:193], v[140:143]
	v_mfma_f32_16x16x32_bf16 v[136:139], v[112:115], v[190:193], v[136:139]
	v_mfma_f32_16x16x32_bf16 v[124:127], v[100:103], v[198:201], v[124:127]
	v_mfma_f32_16x16x32_bf16 v[120:123], v[112:115], v[198:201], v[120:123]
	v_mfma_f32_16x16x32_bf16 v[92:95], v[100:103], v[206:209], v[92:95]
	v_mfma_f32_16x16x32_bf16 v[88:91], v[112:115], v[206:209], v[88:91]
	v_mfma_f32_16x16x32_bf16 v[76:79], v[100:103], v[228:231], v[76:79]
	v_mfma_f32_16x16x32_bf16 v[72:75], v[112:115], v[228:231], v[72:75]
	v_mfma_f32_16x16x32_bf16 v[132:135], v[154:157], v[186:189], 0
	v_mfma_f32_16x16x32_bf16 v[128:131], v[170:173], v[186:189], 0
	v_mfma_f32_16x16x32_bf16 v[116:119], v[154:157], v[194:197], 0
	v_mfma_f32_16x16x32_bf16 v[104:107], v[170:173], v[194:197], 0
	v_mfma_f32_16x16x32_bf16 v[84:87], v[154:157], v[202:205], 0
	v_mfma_f32_16x16x32_bf16 v[80:83], v[170:173], v[202:205], 0
	v_mfma_f32_16x16x32_bf16 v[68:71], v[154:157], v[210:213], 0
	v_mfma_f32_16x16x32_bf16 v[64:67], v[170:173], v[210:213], 0
	v_mfma_f32_16x16x32_bf16 v[132:135], v[166:169], v[190:193], v[132:135]
	v_mfma_f32_16x16x32_bf16 v[128:131], v[182:185], v[190:193], v[128:131]
	v_mfma_f32_16x16x32_bf16 v[116:119], v[166:169], v[198:201], v[116:119]
	v_mfma_f32_16x16x32_bf16 v[104:107], v[182:185], v[198:201], v[104:107]
	s_setprio 2
	s_barrier
	v_mfma_f32_16x16x32_bf16 v[84:87], v[166:169], v[206:209], v[84:87]
	v_mfma_f32_16x16x32_bf16 v[80:83], v[182:185], v[206:209], v[80:83]
	v_mfma_f32_16x16x32_bf16 v[68:71], v[166:169], v[228:231], v[68:71]
	v_mfma_f32_16x16x32_bf16 v[64:67], v[182:185], v[228:231], v[64:67]
	s_setprio 0
	s_add_i32 s64, s64, s43
	s_add_u32 s94, s24, s34
	s_addc_u32 s95, s25, s35
	s_mov_b32 m0, s64
	ds_read_b128 v[186:189], v164 offset:16384
	ds_read_b128 v[190:193], v164 offset:17408
	ds_read_b128 v[194:197], v164 offset:18432
	ds_read_b128 v[198:201], v164 offset:19456
	ds_read_b128 v[202:205], v164 offset:20480
	ds_read_b128 v[206:209], v164 offset:21504
	ds_read_b128 v[210:213], v164 offset:22528
	ds_read_b128 v[228:231], v164 offset:23552
	global_load_lds_dwordx4 v176, s[24:25]
	s_add_i32 m0, s64, 0x2000
	s_add_u32 s64, s24, 0x40000
	s_addc_u32 s65, s25, 0
	s_add_i32 s68, s68, s43
	global_load_lds_dwordx4 v148, s[24:25]
	s_mov_b32 m0, s68
	s_nop 0
	global_load_lds_dwordx4 v176, s[64:65]
	s_add_i32 m0, s68, 0x2000
	s_nop 0
	global_load_lds_dwordx4 v148, s[64:65]
	s_add_u32 s98, s26, s34
	s_addc_u32 s99, s27, s35
	s_mov_b32 m0, s50
	s_nop 0
	global_load_lds_dwordx4 v144, s[26:27]
	s_waitcnt vmcnt(7) lgkmcnt(0)
	s_barrier
	s_setprio 1
	v_mfma_f32_16x16x32_bf16 v[60:63], v[96:99], v[186:189], 0
	v_mfma_f32_16x16x32_bf16 v[56:59], v[108:111], v[186:189], 0
	v_mfma_f32_16x16x32_bf16 v[44:47], v[96:99], v[194:197], 0
	v_mfma_f32_16x16x32_bf16 v[40:43], v[108:111], v[194:197], 0
	v_mfma_f32_16x16x32_bf16 v[28:31], v[96:99], v[202:205], 0
	v_mfma_f32_16x16x32_bf16 v[24:27], v[108:111], v[202:205], 0
	v_mfma_f32_16x16x32_bf16 v[12:15], v[96:99], v[210:213], 0
	v_mfma_f32_16x16x32_bf16 v[8:11], v[108:111], v[210:213], 0
	v_mfma_f32_16x16x32_bf16 v[60:63], v[100:103], v[190:193], v[60:63]
	v_mfma_f32_16x16x32_bf16 v[56:59], v[112:115], v[190:193], v[56:59]
	v_mfma_f32_16x16x32_bf16 v[44:47], v[100:103], v[198:201], v[44:47]
	v_mfma_f32_16x16x32_bf16 v[40:43], v[112:115], v[198:201], v[40:43]
	v_mfma_f32_16x16x32_bf16 v[28:31], v[100:103], v[206:209], v[28:31]
	v_mfma_f32_16x16x32_bf16 v[24:27], v[112:115], v[206:209], v[24:27]
	v_mfma_f32_16x16x32_bf16 v[12:15], v[100:103], v[228:231], v[12:15]
	v_mfma_f32_16x16x32_bf16 v[8:11], v[112:115], v[228:231], v[8:11]
	v_mfma_f32_16x16x32_bf16 v[52:55], v[154:157], v[186:189], 0
	v_mfma_f32_16x16x32_bf16 v[48:51], v[170:173], v[186:189], 0
	v_mfma_f32_16x16x32_bf16 v[36:39], v[154:157], v[194:197], 0
	v_mfma_f32_16x16x32_bf16 v[32:35], v[170:173], v[194:197], 0
	v_mfma_f32_16x16x32_bf16 v[20:23], v[154:157], v[202:205], 0
	v_mfma_f32_16x16x32_bf16 v[16:19], v[170:173], v[202:205], 0
	v_mfma_f32_16x16x32_bf16 v[4:7], v[154:157], v[210:213], 0
	v_mfma_f32_16x16x32_bf16 v[0:3], v[170:173], v[210:213], 0
	v_mfma_f32_16x16x32_bf16 v[52:55], v[166:169], v[190:193], v[52:55]
	v_mfma_f32_16x16x32_bf16 v[48:51], v[182:185], v[190:193], v[48:51]
	v_mfma_f32_16x16x32_bf16 v[36:39], v[166:169], v[198:201], v[36:39]
	v_mfma_f32_16x16x32_bf16 v[32:35], v[182:185], v[198:201], v[32:35]
	s_setprio 2
	s_barrier
	v_mfma_f32_16x16x32_bf16 v[20:23], v[166:169], v[206:209], v[20:23]
	v_mfma_f32_16x16x32_bf16 v[16:19], v[182:185], v[206:209], v[16:19]
	v_mfma_f32_16x16x32_bf16 v[4:7], v[166:169], v[228:231], v[4:7]
	v_mfma_f32_16x16x32_bf16 v[0:3], v[182:185], v[228:231], v[0:3]
	s_setprio 0
	s_mov_b32 m0, s51
	s_nop 0
	global_load_lds_dwordx4 v146, s[26:27]
	s_add_i32 s64, 0, 0x18000
	s_add_i32 s65, 0, 0x1c000
	ds_read_b128 v[96:99], v175 offset:32768
	ds_read_b128 v[100:103], v175 offset:33792
	ds_read_b128 v[108:111], v175 offset:34816
	ds_read_b128 v[112:115], v175 offset:35840
	ds_read_b128 v[154:157], v175 offset:49152
	ds_read_b128 v[166:169], v175 offset:50176
	ds_read_b128 v[170:173], v175 offset:51200
	ds_read_b128 v[182:185], v175 offset:52224
	s_add_u32 s26, s26, 0x40000
	s_addc_u32 s27, s27, 0
	s_mov_b32 m0, s52
	ds_read_b128 v[186:189], v164 offset:32768
	ds_read_b128 v[190:193], v164 offset:33792
	ds_read_b128 v[194:197], v164 offset:34816
	ds_read_b128 v[198:201], v164 offset:35840
	ds_read_b128 v[202:205], v164 offset:36864
	ds_read_b128 v[206:209], v164 offset:37888
	ds_read_b128 v[210:213], v164 offset:38912
	ds_read_b128 v[228:231], v164 offset:39936
	global_load_lds_dwordx4 v144, s[26:27]
	s_mov_b32 m0, s53
	s_nop 0
	global_load_lds_dwordx4 v146, s[26:27]
	s_waitcnt vmcnt(8) lgkmcnt(0)
	s_barrier
	s_setprio 1
	v_mfma_f32_16x16x32_bf16 v[140:143], v[96:99], v[186:189], v[140:143]
	v_mfma_f32_16x16x32_bf16 v[136:139], v[108:111], v[186:189], v[136:139]
	v_mfma_f32_16x16x32_bf16 v[124:127], v[96:99], v[194:197], v[124:127]
	v_mfma_f32_16x16x32_bf16 v[120:123], v[108:111], v[194:197], v[120:123]
	v_mfma_f32_16x16x32_bf16 v[92:95], v[96:99], v[202:205], v[92:95]
	v_mfma_f32_16x16x32_bf16 v[88:91], v[108:111], v[202:205], v[88:91]
	v_mfma_f32_16x16x32_bf16 v[76:79], v[96:99], v[210:213], v[76:79]
	v_mfma_f32_16x16x32_bf16 v[72:75], v[108:111], v[210:213], v[72:75]
	v_mfma_f32_16x16x32_bf16 v[140:143], v[100:103], v[190:193], v[140:143]
	v_mfma_f32_16x16x32_bf16 v[136:139], v[112:115], v[190:193], v[136:139]
	v_mfma_f32_16x16x32_bf16 v[124:127], v[100:103], v[198:201], v[124:127]
	v_mfma_f32_16x16x32_bf16 v[120:123], v[112:115], v[198:201], v[120:123]
	v_mfma_f32_16x16x32_bf16 v[92:95], v[100:103], v[206:209], v[92:95]
	v_mfma_f32_16x16x32_bf16 v[88:91], v[112:115], v[206:209], v[88:91]
	v_mfma_f32_16x16x32_bf16 v[76:79], v[100:103], v[228:231], v[76:79]
	v_mfma_f32_16x16x32_bf16 v[72:75], v[112:115], v[228:231], v[72:75]
	v_mfma_f32_16x16x32_bf16 v[132:135], v[154:157], v[186:189], v[132:135]
	v_mfma_f32_16x16x32_bf16 v[128:131], v[170:173], v[186:189], v[128:131]
	v_mfma_f32_16x16x32_bf16 v[116:119], v[154:157], v[194:197], v[116:119]
	v_mfma_f32_16x16x32_bf16 v[104:107], v[170:173], v[194:197], v[104:107]
	v_mfma_f32_16x16x32_bf16 v[84:87], v[154:157], v[202:205], v[84:87]
	v_mfma_f32_16x16x32_bf16 v[80:83], v[170:173], v[202:205], v[80:83]
	v_mfma_f32_16x16x32_bf16 v[68:71], v[154:157], v[210:213], v[68:71]
	v_mfma_f32_16x16x32_bf16 v[64:67], v[170:173], v[210:213], v[64:67]
	v_mfma_f32_16x16x32_bf16 v[132:135], v[166:169], v[190:193], v[132:135]
	v_mfma_f32_16x16x32_bf16 v[128:131], v[182:185], v[190:193], v[128:131]
	v_mfma_f32_16x16x32_bf16 v[116:119], v[166:169], v[198:201], v[116:119]
	v_mfma_f32_16x16x32_bf16 v[104:107], v[182:185], v[198:201], v[104:107]
	s_setprio 2
	s_barrier
	v_mfma_f32_16x16x32_bf16 v[84:87], v[166:169], v[206:209], v[84:87]
	v_mfma_f32_16x16x32_bf16 v[80:83], v[182:185], v[206:209], v[80:83]
	v_mfma_f32_16x16x32_bf16 v[68:71], v[166:169], v[228:231], v[68:71]
	v_mfma_f32_16x16x32_bf16 v[64:67], v[182:185], v[228:231], v[64:67]
	s_setprio 0
	s_add_i32 s26, s64, s43
	s_mov_b32 m0, s26
	ds_read_b128 v[186:189], v164 offset:49152
	ds_read_b128 v[190:193], v164 offset:50176
	ds_read_b128 v[194:197], v164 offset:51200
	ds_read_b128 v[198:201], v164 offset:52224
	ds_read_b128 v[202:205], v164 offset:53248
	ds_read_b128 v[206:209], v164 offset:54272
	ds_read_b128 v[210:213], v164 offset:55296
	ds_read_b128 v[228:231], v164 offset:56320
	global_load_lds_dwordx4 v176, s[94:95]
	s_add_i32 m0, s26, 0x2000
	s_add_u32 s24, s24, 0x40080
	s_addc_u32 s25, s25, 0
	s_add_i32 s26, s65, s43
	global_load_lds_dwordx4 v148, s[94:95]
	s_mov_b32 m0, s26
	s_nop 0
	global_load_lds_dwordx4 v176, s[24:25]
	s_add_i32 m0, s26, 0x2000
	s_nop 0
	global_load_lds_dwordx4 v148, s[24:25]
	s_mov_b32 m0, s57
	s_nop 0
	global_load_lds_dwordx4 v144, s[98:99]
	s_mov_b32 m0, s58
	s_nop 0
	global_load_lds_dwordx4 v146, s[98:99]
	s_waitcnt vmcnt(8) lgkmcnt(0)
	s_barrier
	s_setprio 1
	v_mfma_f32_16x16x32_bf16 v[60:63], v[96:99], v[186:189], v[60:63]
	v_mfma_f32_16x16x32_bf16 v[56:59], v[108:111], v[186:189], v[56:59]
	v_mfma_f32_16x16x32_bf16 v[44:47], v[96:99], v[194:197], v[44:47]
	v_mfma_f32_16x16x32_bf16 v[40:43], v[108:111], v[194:197], v[40:43]
	v_mfma_f32_16x16x32_bf16 v[28:31], v[96:99], v[202:205], v[28:31]
	v_mfma_f32_16x16x32_bf16 v[24:27], v[108:111], v[202:205], v[24:27]
	v_mfma_f32_16x16x32_bf16 v[12:15], v[96:99], v[210:213], v[12:15]
	v_mfma_f32_16x16x32_bf16 v[8:11], v[108:111], v[210:213], v[8:11]
	v_mfma_f32_16x16x32_bf16 v[60:63], v[100:103], v[190:193], v[60:63]
	v_mfma_f32_16x16x32_bf16 v[56:59], v[112:115], v[190:193], v[56:59]
	v_mfma_f32_16x16x32_bf16 v[44:47], v[100:103], v[198:201], v[44:47]
	v_mfma_f32_16x16x32_bf16 v[40:43], v[112:115], v[198:201], v[40:43]
	v_mfma_f32_16x16x32_bf16 v[28:31], v[100:103], v[206:209], v[28:31]
	v_mfma_f32_16x16x32_bf16 v[24:27], v[112:115], v[206:209], v[24:27]
	v_mfma_f32_16x16x32_bf16 v[12:15], v[100:103], v[228:231], v[12:15]
	v_mfma_f32_16x16x32_bf16 v[8:11], v[112:115], v[228:231], v[8:11]
	v_mfma_f32_16x16x32_bf16 v[52:55], v[154:157], v[186:189], v[52:55]
	v_mfma_f32_16x16x32_bf16 v[48:51], v[170:173], v[186:189], v[48:51]
	v_mfma_f32_16x16x32_bf16 v[36:39], v[154:157], v[194:197], v[36:39]
	v_mfma_f32_16x16x32_bf16 v[32:35], v[170:173], v[194:197], v[32:35]
	v_mfma_f32_16x16x32_bf16 v[20:23], v[154:157], v[202:205], v[20:23]
	v_mfma_f32_16x16x32_bf16 v[16:19], v[170:173], v[202:205], v[16:19]
	v_mfma_f32_16x16x32_bf16 v[4:7], v[154:157], v[210:213], v[4:7]
	v_mfma_f32_16x16x32_bf16 v[0:3], v[170:173], v[210:213], v[0:3]
	v_mfma_f32_16x16x32_bf16 v[52:55], v[166:169], v[190:193], v[52:55]
	v_mfma_f32_16x16x32_bf16 v[48:51], v[182:185], v[190:193], v[48:51]
	v_mfma_f32_16x16x32_bf16 v[36:39], v[166:169], v[198:201], v[36:39]
	v_mfma_f32_16x16x32_bf16 v[32:35], v[182:185], v[198:201], v[32:35]
	s_setprio 2
	s_barrier
	v_mfma_f32_16x16x32_bf16 v[20:23], v[166:169], v[206:209], v[20:23]
	v_mfma_f32_16x16x32_bf16 v[16:19], v[182:185], v[206:209], v[16:19]
	v_mfma_f32_16x16x32_bf16 v[4:7], v[166:169], v[228:231], v[4:7]
	v_mfma_f32_16x16x32_bf16 v[0:3], v[182:185], v[228:231], v[0:3]
	s_setprio 0
	s_add_i32 s63, s63, 2
	s_add_u32 s44, s44, 0x100
	s_addc_u32 s62, s62, 0
	s_add_u32 s22, s22, 0x100
	s_addc_u32 s23, s23, 0
	s_cmp_gt_u32 s63, 13
	s_cbranch_scc1 .Lpeel_exit_0
.LBB0_319:
	s_add_u32 s24, s22, 0xfffc0080
	s_addc_u32 s25, s23, -1
	s_add_i32 s64, 0, 0x10000
	s_cmp_eq_u32 s63, 12
	s_cselect_b32 s27, s9, s25
	s_cselect_b32 s26, s15, s24
	s_cselect_b32 s25, s13, s62
	s_cselect_b32 s24, s21, s44
	s_add_i32 s68, 0, 0x14000
	ds_read_b128 v[96:99], v175
	ds_read_b128 v[100:103], v175 offset:1024
	ds_read_b128 v[108:111], v175 offset:2048
	ds_read_b128 v[112:115], v175 offset:3072
	ds_read_b128 v[154:157], v175 offset:16384
	ds_read_b128 v[166:169], v175 offset:17408
	ds_read_b128 v[170:173], v175 offset:18432
	ds_read_b128 v[182:185], v175 offset:19456
	s_add_i32 m0, s50, 0xc000
	ds_read_b128 v[186:189], v164
	ds_read_b128 v[190:193], v164 offset:1024
	ds_read_b128 v[194:197], v164 offset:2048
	ds_read_b128 v[198:201], v164 offset:3072
	ds_read_b128 v[202:205], v164 offset:4096
	ds_read_b128 v[206:209], v164 offset:5120
	ds_read_b128 v[210:213], v164 offset:6144
	ds_read_b128 v[228:231], v164 offset:7168
	global_load_lds_dwordx4 v152, s[22:23]
	s_add_i32 m0, s50, 0xe000
	s_nop 0
	global_load_lds_dwordx4 v150, s[22:23]
	s_waitcnt vmcnt(8) lgkmcnt(0)
	s_barrier
	s_setprio 1
	v_mfma_f32_16x16x32_bf16 v[140:143], v[96:99], v[186:189], v[140:143]
	v_mfma_f32_16x16x32_bf16 v[136:139], v[108:111], v[186:189], v[136:139]
	v_mfma_f32_16x16x32_bf16 v[124:127], v[96:99], v[194:197], v[124:127]
	v_mfma_f32_16x16x32_bf16 v[120:123], v[108:111], v[194:197], v[120:123]
	v_mfma_f32_16x16x32_bf16 v[92:95], v[96:99], v[202:205], v[92:95]
	v_mfma_f32_16x16x32_bf16 v[88:91], v[108:111], v[202:205], v[88:91]
	v_mfma_f32_16x16x32_bf16 v[76:79], v[96:99], v[210:213], v[76:79]
	v_mfma_f32_16x16x32_bf16 v[72:75], v[108:111], v[210:213], v[72:75]
	v_mfma_f32_16x16x32_bf16 v[140:143], v[100:103], v[190:193], v[140:143]
	v_mfma_f32_16x16x32_bf16 v[136:139], v[112:115], v[190:193], v[136:139]
	v_mfma_f32_16x16x32_bf16 v[124:127], v[100:103], v[198:201], v[124:127]
	v_mfma_f32_16x16x32_bf16 v[120:123], v[112:115], v[198:201], v[120:123]
	v_mfma_f32_16x16x32_bf16 v[92:95], v[100:103], v[206:209], v[92:95]
	v_mfma_f32_16x16x32_bf16 v[88:91], v[112:115], v[206:209], v[88:91]
	v_mfma_f32_16x16x32_bf16 v[76:79], v[100:103], v[228:231], v[76:79]
	v_mfma_f32_16x16x32_bf16 v[72:75], v[112:115], v[228:231], v[72:75]
	v_mfma_f32_16x16x32_bf16 v[132:135], v[154:157], v[186:189], v[132:135]
	v_mfma_f32_16x16x32_bf16 v[128:131], v[170:173], v[186:189], v[128:131]
	v_mfma_f32_16x16x32_bf16 v[116:119], v[154:157], v[194:197], v[116:119]
	v_mfma_f32_16x16x32_bf16 v[104:107], v[170:173], v[194:197], v[104:107]
	v_mfma_f32_16x16x32_bf16 v[84:87], v[154:157], v[202:205], v[84:87]
	v_mfma_f32_16x16x32_bf16 v[80:83], v[170:173], v[202:205], v[80:83]
	v_mfma_f32_16x16x32_bf16 v[68:71], v[154:157], v[210:213], v[68:71]
	v_mfma_f32_16x16x32_bf16 v[64:67], v[170:173], v[210:213], v[64:67]
	v_mfma_f32_16x16x32_bf16 v[132:135], v[166:169], v[190:193], v[132:135]
	v_mfma_f32_16x16x32_bf16 v[128:131], v[182:185], v[190:193], v[128:131]
	v_mfma_f32_16x16x32_bf16 v[116:119], v[166:169], v[198:201], v[116:119]
	v_mfma_f32_16x16x32_bf16 v[104:107], v[182:185], v[198:201], v[104:107]
	s_setprio 2
	s_barrier
	v_mfma_f32_16x16x32_bf16 v[84:87], v[166:169], v[206:209], v[84:87]
	v_mfma_f32_16x16x32_bf16 v[80:83], v[182:185], v[206:209], v[80:83]
	v_mfma_f32_16x16x32_bf16 v[68:71], v[166:169], v[228:231], v[68:71]
	v_mfma_f32_16x16x32_bf16 v[64:67], v[182:185], v[228:231], v[64:67]
	s_setprio 0
	s_add_i32 s64, s64, s43
	s_add_u32 s94, s24, s34
	s_addc_u32 s95, s25, s35
	s_mov_b32 m0, s64
	ds_read_b128 v[186:189], v164 offset:16384
	ds_read_b128 v[190:193], v164 offset:17408
	ds_read_b128 v[194:197], v164 offset:18432
	ds_read_b128 v[198:201], v164 offset:19456
	ds_read_b128 v[202:205], v164 offset:20480
	ds_read_b128 v[206:209], v164 offset:21504
	ds_read_b128 v[210:213], v164 offset:22528
	ds_read_b128 v[228:231], v164 offset:23552
	global_load_lds_dwordx4 v176, s[24:25]
	s_add_i32 m0, s64, 0x2000
	s_add_u32 s64, s24, 0x40000
	s_addc_u32 s65, s25, 0
	s_add_i32 s68, s68, s43
	global_load_lds_dwordx4 v148, s[24:25]
	s_mov_b32 m0, s68
	s_nop 0
	global_load_lds_dwordx4 v176, s[64:65]
	s_add_i32 m0, s68, 0x2000
	s_nop 0
	global_load_lds_dwordx4 v148, s[64:65]
	s_add_u32 s98, s26, s34
	s_addc_u32 s99, s27, s35
	s_mov_b32 m0, s50
	s_nop 0
	global_load_lds_dwordx4 v144, s[26:27]
	s_waitcnt vmcnt(7) lgkmcnt(0)
	s_barrier
	s_setprio 1
	v_mfma_f32_16x16x32_bf16 v[60:63], v[96:99], v[186:189], v[60:63]
	v_mfma_f32_16x16x32_bf16 v[56:59], v[108:111], v[186:189], v[56:59]
	v_mfma_f32_16x16x32_bf16 v[44:47], v[96:99], v[194:197], v[44:47]
	v_mfma_f32_16x16x32_bf16 v[40:43], v[108:111], v[194:197], v[40:43]
	v_mfma_f32_16x16x32_bf16 v[28:31], v[96:99], v[202:205], v[28:31]
	v_mfma_f32_16x16x32_bf16 v[24:27], v[108:111], v[202:205], v[24:27]
	v_mfma_f32_16x16x32_bf16 v[12:15], v[96:99], v[210:213], v[12:15]
	v_mfma_f32_16x16x32_bf16 v[8:11], v[108:111], v[210:213], v[8:11]
	v_mfma_f32_16x16x32_bf16 v[60:63], v[100:103], v[190:193], v[60:63]
	v_mfma_f32_16x16x32_bf16 v[56:59], v[112:115], v[190:193], v[56:59]
	v_mfma_f32_16x16x32_bf16 v[44:47], v[100:103], v[198:201], v[44:47]
	v_mfma_f32_16x16x32_bf16 v[40:43], v[112:115], v[198:201], v[40:43]
	v_mfma_f32_16x16x32_bf16 v[28:31], v[100:103], v[206:209], v[28:31]
	v_mfma_f32_16x16x32_bf16 v[24:27], v[112:115], v[206:209], v[24:27]
	v_mfma_f32_16x16x32_bf16 v[12:15], v[100:103], v[228:231], v[12:15]
	v_mfma_f32_16x16x32_bf16 v[8:11], v[112:115], v[228:231], v[8:11]
	v_mfma_f32_16x16x32_bf16 v[52:55], v[154:157], v[186:189], v[52:55]
	v_mfma_f32_16x16x32_bf16 v[48:51], v[170:173], v[186:189], v[48:51]
	v_mfma_f32_16x16x32_bf16 v[36:39], v[154:157], v[194:197], v[36:39]
	v_mfma_f32_16x16x32_bf16 v[32:35], v[170:173], v[194:197], v[32:35]
	v_mfma_f32_16x16x32_bf16 v[20:23], v[154:157], v[202:205], v[20:23]
	v_mfma_f32_16x16x32_bf16 v[16:19], v[170:173], v[202:205], v[16:19]
	v_mfma_f32_16x16x32_bf16 v[4:7], v[154:157], v[210:213], v[4:7]
	v_mfma_f32_16x16x32_bf16 v[0:3], v[170:173], v[210:213], v[0:3]
	v_mfma_f32_16x16x32_bf16 v[52:55], v[166:169], v[190:193], v[52:55]
	v_mfma_f32_16x16x32_bf16 v[48:51], v[182:185], v[190:193], v[48:51]
	v_mfma_f32_16x16x32_bf16 v[36:39], v[166:169], v[198:201], v[36:39]
	v_mfma_f32_16x16x32_bf16 v[32:35], v[182:185], v[198:201], v[32:35]
	s_setprio 2
	s_barrier
	v_mfma_f32_16x16x32_bf16 v[20:23], v[166:169], v[206:209], v[20:23]
	v_mfma_f32_16x16x32_bf16 v[16:19], v[182:185], v[206:209], v[16:19]
	v_mfma_f32_16x16x32_bf16 v[4:7], v[166:169], v[228:231], v[4:7]
	v_mfma_f32_16x16x32_bf16 v[0:3], v[182:185], v[228:231], v[0:3]
	s_setprio 0
	s_mov_b32 m0, s51
	s_nop 0
	global_load_lds_dwordx4 v146, s[26:27]
	s_add_i32 s64, 0, 0x18000
	s_add_i32 s65, 0, 0x1c000
	ds_read_b128 v[96:99], v175 offset:32768
	ds_read_b128 v[100:103], v175 offset:33792
	ds_read_b128 v[108:111], v175 offset:34816
	ds_read_b128 v[112:115], v175 offset:35840
	ds_read_b128 v[154:157], v175 offset:49152
	ds_read_b128 v[166:169], v175 offset:50176
	ds_read_b128 v[170:173], v175 offset:51200
	ds_read_b128 v[182:185], v175 offset:52224
	s_add_u32 s26, s26, 0x40000
	s_addc_u32 s27, s27, 0
	s_mov_b32 m0, s52
	ds_read_b128 v[186:189], v164 offset:32768
	ds_read_b128 v[190:193], v164 offset:33792
	ds_read_b128 v[194:197], v164 offset:34816
	ds_read_b128 v[198:201], v164 offset:35840
	ds_read_b128 v[202:205], v164 offset:36864
	ds_read_b128 v[206:209], v164 offset:37888
	ds_read_b128 v[210:213], v164 offset:38912
	ds_read_b128 v[228:231], v164 offset:39936
	global_load_lds_dwordx4 v144, s[26:27]
	s_mov_b32 m0, s53
	s_nop 0
	global_load_lds_dwordx4 v146, s[26:27]
	s_waitcnt vmcnt(8) lgkmcnt(0)
	s_barrier
	s_setprio 1
	v_mfma_f32_16x16x32_bf16 v[140:143], v[96:99], v[186:189], v[140:143]
	v_mfma_f32_16x16x32_bf16 v[136:139], v[108:111], v[186:189], v[136:139]
	v_mfma_f32_16x16x32_bf16 v[124:127], v[96:99], v[194:197], v[124:127]
	v_mfma_f32_16x16x32_bf16 v[120:123], v[108:111], v[194:197], v[120:123]
	v_mfma_f32_16x16x32_bf16 v[92:95], v[96:99], v[202:205], v[92:95]
	v_mfma_f32_16x16x32_bf16 v[88:91], v[108:111], v[202:205], v[88:91]
	v_mfma_f32_16x16x32_bf16 v[76:79], v[96:99], v[210:213], v[76:79]
	v_mfma_f32_16x16x32_bf16 v[72:75], v[108:111], v[210:213], v[72:75]
	v_mfma_f32_16x16x32_bf16 v[140:143], v[100:103], v[190:193], v[140:143]
	v_mfma_f32_16x16x32_bf16 v[136:139], v[112:115], v[190:193], v[136:139]
	v_mfma_f32_16x16x32_bf16 v[124:127], v[100:103], v[198:201], v[124:127]
	v_mfma_f32_16x16x32_bf16 v[120:123], v[112:115], v[198:201], v[120:123]
	v_mfma_f32_16x16x32_bf16 v[92:95], v[100:103], v[206:209], v[92:95]
	v_mfma_f32_16x16x32_bf16 v[88:91], v[112:115], v[206:209], v[88:91]
	v_mfma_f32_16x16x32_bf16 v[76:79], v[100:103], v[228:231], v[76:79]
	v_mfma_f32_16x16x32_bf16 v[72:75], v[112:115], v[228:231], v[72:75]
	v_mfma_f32_16x16x32_bf16 v[132:135], v[154:157], v[186:189], v[132:135]
	v_mfma_f32_16x16x32_bf16 v[128:131], v[170:173], v[186:189], v[128:131]
	v_mfma_f32_16x16x32_bf16 v[116:119], v[154:157], v[194:197], v[116:119]
	v_mfma_f32_16x16x32_bf16 v[104:107], v[170:173], v[194:197], v[104:107]
	v_mfma_f32_16x16x32_bf16 v[84:87], v[154:157], v[202:205], v[84:87]
	v_mfma_f32_16x16x32_bf16 v[80:83], v[170:173], v[202:205], v[80:83]
	v_mfma_f32_16x16x32_bf16 v[68:71], v[154:157], v[210:213], v[68:71]
	v_mfma_f32_16x16x32_bf16 v[64:67], v[170:173], v[210:213], v[64:67]
	v_mfma_f32_16x16x32_bf16 v[132:135], v[166:169], v[190:193], v[132:135]
	v_mfma_f32_16x16x32_bf16 v[128:131], v[182:185], v[190:193], v[128:131]
	v_mfma_f32_16x16x32_bf16 v[116:119], v[166:169], v[198:201], v[116:119]
	v_mfma_f32_16x16x32_bf16 v[104:107], v[182:185], v[198:201], v[104:107]
	s_setprio 2
	s_barrier
	v_mfma_f32_16x16x32_bf16 v[84:87], v[166:169], v[206:209], v[84:87]
	v_mfma_f32_16x16x32_bf16 v[80:83], v[182:185], v[206:209], v[80:83]
	v_mfma_f32_16x16x32_bf16 v[68:71], v[166:169], v[228:231], v[68:71]
	v_mfma_f32_16x16x32_bf16 v[64:67], v[182:185], v[228:231], v[64:67]
	s_setprio 0
	s_add_i32 s26, s64, s43
	s_mov_b32 m0, s26
	ds_read_b128 v[186:189], v164 offset:49152
	ds_read_b128 v[190:193], v164 offset:50176
	ds_read_b128 v[194:197], v164 offset:51200
	ds_read_b128 v[198:201], v164 offset:52224
	ds_read_b128 v[202:205], v164 offset:53248
	ds_read_b128 v[206:209], v164 offset:54272
	ds_read_b128 v[210:213], v164 offset:55296
	ds_read_b128 v[228:231], v164 offset:56320
	global_load_lds_dwordx4 v176, s[94:95]
	s_add_i32 m0, s26, 0x2000
	s_add_u32 s24, s24, 0x40080
	s_addc_u32 s25, s25, 0
	s_add_i32 s26, s65, s43
	global_load_lds_dwordx4 v148, s[94:95]
	s_mov_b32 m0, s26
	s_nop 0
	global_load_lds_dwordx4 v176, s[24:25]
	s_add_i32 m0, s26, 0x2000
	s_nop 0
	global_load_lds_dwordx4 v148, s[24:25]
	s_mov_b32 m0, s57
	s_nop 0
	global_load_lds_dwordx4 v144, s[98:99]
	s_mov_b32 m0, s58
	s_nop 0
	global_load_lds_dwordx4 v146, s[98:99]
	s_waitcnt vmcnt(8) lgkmcnt(0)
	s_barrier
	s_setprio 1
	v_mfma_f32_16x16x32_bf16 v[60:63], v[96:99], v[186:189], v[60:63]
	v_mfma_f32_16x16x32_bf16 v[56:59], v[108:111], v[186:189], v[56:59]
	v_mfma_f32_16x16x32_bf16 v[44:47], v[96:99], v[194:197], v[44:47]
	v_mfma_f32_16x16x32_bf16 v[40:43], v[108:111], v[194:197], v[40:43]
	v_mfma_f32_16x16x32_bf16 v[28:31], v[96:99], v[202:205], v[28:31]
	v_mfma_f32_16x16x32_bf16 v[24:27], v[108:111], v[202:205], v[24:27]
	v_mfma_f32_16x16x32_bf16 v[12:15], v[96:99], v[210:213], v[12:15]
	v_mfma_f32_16x16x32_bf16 v[8:11], v[108:111], v[210:213], v[8:11]
	v_mfma_f32_16x16x32_bf16 v[60:63], v[100:103], v[190:193], v[60:63]
	v_mfma_f32_16x16x32_bf16 v[56:59], v[112:115], v[190:193], v[56:59]
	v_mfma_f32_16x16x32_bf16 v[44:47], v[100:103], v[198:201], v[44:47]
	v_mfma_f32_16x16x32_bf16 v[40:43], v[112:115], v[198:201], v[40:43]
	v_mfma_f32_16x16x32_bf16 v[28:31], v[100:103], v[206:209], v[28:31]
	v_mfma_f32_16x16x32_bf16 v[24:27], v[112:115], v[206:209], v[24:27]
	v_mfma_f32_16x16x32_bf16 v[12:15], v[100:103], v[228:231], v[12:15]
	v_mfma_f32_16x16x32_bf16 v[8:11], v[112:115], v[228:231], v[8:11]
	v_mfma_f32_16x16x32_bf16 v[52:55], v[154:157], v[186:189], v[52:55]
	v_mfma_f32_16x16x32_bf16 v[48:51], v[170:173], v[186:189], v[48:51]
	v_mfma_f32_16x16x32_bf16 v[36:39], v[154:157], v[194:197], v[36:39]
	v_mfma_f32_16x16x32_bf16 v[32:35], v[170:173], v[194:197], v[32:35]
	v_mfma_f32_16x16x32_bf16 v[20:23], v[154:157], v[202:205], v[20:23]
	v_mfma_f32_16x16x32_bf16 v[16:19], v[170:173], v[202:205], v[16:19]
	v_mfma_f32_16x16x32_bf16 v[4:7], v[154:157], v[210:213], v[4:7]
	v_mfma_f32_16x16x32_bf16 v[0:3], v[170:173], v[210:213], v[0:3]
	v_mfma_f32_16x16x32_bf16 v[52:55], v[166:169], v[190:193], v[52:55]
	v_mfma_f32_16x16x32_bf16 v[48:51], v[182:185], v[190:193], v[48:51]
	v_mfma_f32_16x16x32_bf16 v[36:39], v[166:169], v[198:201], v[36:39]
	v_mfma_f32_16x16x32_bf16 v[32:35], v[182:185], v[198:201], v[32:35]
	s_setprio 2
	s_barrier
	v_mfma_f32_16x16x32_bf16 v[20:23], v[166:169], v[206:209], v[20:23]
	v_mfma_f32_16x16x32_bf16 v[16:19], v[182:185], v[206:209], v[16:19]
	v_mfma_f32_16x16x32_bf16 v[4:7], v[166:169], v[228:231], v[4:7]
	v_mfma_f32_16x16x32_bf16 v[0:3], v[182:185], v[228:231], v[0:3]
	s_setprio 0
	s_add_i32 s63, s63, 2
	s_add_u32 s44, s44, 0x100
	s_addc_u32 s62, s62, 0
	s_add_u32 s22, s22, 0x100
	s_addc_u32 s23, s23, 0
	s_cmp_gt_u32 s63, 13
	s_cbranch_scc0 .LBB0_319

.LBB0_633:
	s_ashr_i32 s13, s12, 31
	s_lshl_b64 s[14:15], s[12:13], 19
	s_add_u32 s14, s37, s14
	s_addc_u32 s15, s42, s15
	s_and_b64 s[16:17], s[4:5], exec
	s_cselect_b32 s13, s15, s23
	s_cselect_b32 s19, s14, s22
	s_ashr_i32 s11, s10, 31
	s_lshl_b64 s[16:17], s[10:11], 19
	s_add_u32 s16, s29, s16
	s_addc_u32 s17, s43, s17
	s_and_b64 s[24:25], s[4:5], exec
	s_cselect_b32 s11, s17, s21
	s_cselect_b32 s60, s16, s20
	s_add_u32 s61, s20, 0x100
	s_addc_u32 s62, s21, 0
	s_add_u32 s20, s22, 0x40080
	s_addc_u32 s21, s23, 0
	s_mov_b32 s63, -2
	v_add_u32_e32 v236, 0x10000, v175
	s_add_u32 s22, s20, 0xfffc0080
	s_addc_u32 s23, s21, -1
	s_add_i32 s64, 0, 0x10000
	s_cmp_eq_u32 s63, 12
	s_cselect_b32 s25, s13, s23
	s_cselect_b32 s24, s19, s22
	s_cselect_b32 s23, s11, s62
	s_cselect_b32 s22, s60, s61
	s_add_i32 s68, 0, 0x14000
	s_waitcnt lgkmcnt(0)
	s_lshl_b32 s74, s18, 8
	v_add_u32_e32 v178, s74, v182
	v_ashrrev_i32_e32 v179, 31, v178
	v_lshlrev_b64 v[178:179], 6, v[178:179]
	v_lshl_add_u64 v[178:179], s[70:71], 0, v[178:179]
	s_and_saveexec_b64 s[78:79], s[2:3]
	global_load_dwordx4 v[238:241], v[178:179], off
	global_load_dwordx4 v[242:245], v[178:179], off offset:16
	global_load_dwordx4 v[246:249], v[178:179], off offset:32
	global_load_dwordx4 v[250:253], v[178:179], off offset:48
	s_mov_b64 exec, s[78:79]
	ds_read_b128 v[128:131], v236
	ds_read_b128 v[132:135], v236 offset:1024
	ds_read_b128 v[136:139], v236 offset:2048
	ds_read_b128 v[140:143], v236 offset:3072
	ds_read_b128 v[144:147], v236 offset:16384
	ds_read_b128 v[162:165], v236 offset:17408
	ds_read_b128 v[166:169], v236 offset:18432
	ds_read_b128 v[170:173], v236 offset:19456
	s_add_i32 m0, s50, 0xc000
	ds_read_b128 v[186:189], v185
	ds_read_b128 v[190:193], v185 offset:1024
	ds_read_b128 v[194:197], v185 offset:2048
	ds_read_b128 v[198:201], v185 offset:3072
	ds_read_b128 v[202:205], v185 offset:4096
	ds_read_b128 v[206:209], v185 offset:5120
	ds_read_b128 v[210:213], v185 offset:6144
	ds_read_b128 v[228:231], v185 offset:7168
	global_load_lds_dwordx4 v160, s[20:21]
	s_add_i32 m0, s50, 0xe000
	s_nop 0
	global_load_lds_dwordx4 v158, s[20:21]
	s_waitcnt vmcnt(16) lgkmcnt(0)
	s_barrier
	s_setprio 1
	v_mfma_f32_16x16x32_bf16 v[124:127], v[128:131], v[186:189], 0
	v_mfma_f32_16x16x32_bf16 v[120:123], v[136:139], v[186:189], 0
	v_mfma_f32_16x16x32_bf16 v[108:111], v[128:131], v[194:197], 0
	v_mfma_f32_16x16x32_bf16 v[104:107], v[136:139], v[194:197], 0
	v_mfma_f32_16x16x32_bf16 v[92:95], v[128:131], v[202:205], 0
	v_mfma_f32_16x16x32_bf16 v[88:91], v[136:139], v[202:205], 0
	v_mfma_f32_16x16x32_bf16 v[76:79], v[128:131], v[210:213], 0
	v_mfma_f32_16x16x32_bf16 v[72:75], v[136:139], v[210:213], 0
	v_mfma_f32_16x16x32_bf16 v[124:127], v[132:135], v[190:193], v[124:127]
	v_mfma_f32_16x16x32_bf16 v[120:123], v[140:143], v[190:193], v[120:123]
	v_mfma_f32_16x16x32_bf16 v[108:111], v[132:135], v[198:201], v[108:111]
	v_mfma_f32_16x16x32_bf16 v[104:107], v[140:143], v[198:201], v[104:107]
	v_mfma_f32_16x16x32_bf16 v[92:95], v[132:135], v[206:209], v[92:95]
	v_mfma_f32_16x16x32_bf16 v[88:91], v[140:143], v[206:209], v[88:91]
	v_mfma_f32_16x16x32_bf16 v[76:79], v[132:135], v[228:231], v[76:79]
	v_mfma_f32_16x16x32_bf16 v[72:75], v[140:143], v[228:231], v[72:75]
	v_mfma_f32_16x16x32_bf16 v[116:119], v[144:147], v[186:189], 0
	v_mfma_f32_16x16x32_bf16 v[112:115], v[166:169], v[186:189], 0
	v_mfma_f32_16x16x32_bf16 v[100:103], v[144:147], v[194:197], 0
	v_mfma_f32_16x16x32_bf16 v[96:99], v[166:169], v[194:197], 0
	v_mfma_f32_16x16x32_bf16 v[84:87], v[144:147], v[202:205], 0
	v_mfma_f32_16x16x32_bf16 v[80:83], v[166:169], v[202:205], 0
	v_mfma_f32_16x16x32_bf16 v[68:71], v[144:147], v[210:213], 0
	v_mfma_f32_16x16x32_bf16 v[64:67], v[166:169], v[210:213], 0
	v_mfma_f32_16x16x32_bf16 v[116:119], v[162:165], v[190:193], v[116:119]
	v_mfma_f32_16x16x32_bf16 v[112:115], v[170:173], v[190:193], v[112:115]
	v_mfma_f32_16x16x32_bf16 v[100:103], v[162:165], v[198:201], v[100:103]
	v_mfma_f32_16x16x32_bf16 v[96:99], v[170:173], v[198:201], v[96:99]
	s_setprio 2
	s_barrier
	v_mfma_f32_16x16x32_bf16 v[84:87], v[162:165], v[206:209], v[84:87]
	v_mfma_f32_16x16x32_bf16 v[80:83], v[170:173], v[206:209], v[80:83]
	v_mfma_f32_16x16x32_bf16 v[68:71], v[162:165], v[228:231], v[68:71]
	v_mfma_f32_16x16x32_bf16 v[64:67], v[170:173], v[228:231], v[64:67]
	s_setprio 0
	s_add_i32 s64, s64, s46
	s_add_u32 s94, s22, s34
	s_addc_u32 s95, s23, s35
	s_mov_b32 m0, s64
	ds_read_b128 v[186:189], v185 offset:16384
	ds_read_b128 v[190:193], v185 offset:17408
	ds_read_b128 v[194:197], v185 offset:18432
	ds_read_b128 v[198:201], v185 offset:19456
	ds_read_b128 v[202:205], v185 offset:20480
	ds_read_b128 v[206:209], v185 offset:21504
	ds_read_b128 v[210:213], v185 offset:22528
	ds_read_b128 v[228:231], v185 offset:23552
	global_load_lds_dwordx4 v152, s[22:23]
	s_add_i32 m0, s64, 0x2000
	s_add_u32 s64, s22, 0x40000
	s_addc_u32 s65, s23, 0
	s_add_i32 s68, s68, s46
	global_load_lds_dwordx4 v148, s[22:23]
	s_mov_b32 m0, s68
	s_nop 0
	global_load_lds_dwordx4 v152, s[64:65]
	s_add_i32 m0, s68, 0x2000
	s_nop 0
	global_load_lds_dwordx4 v148, s[64:65]
	s_add_u32 s98, s24, s34
	s_addc_u32 s99, s25, s35
	s_mov_b32 m0, s50
	s_nop 0
	global_load_lds_dwordx4 v154, s[24:25]
	s_waitcnt vmcnt(7) lgkmcnt(0)
	s_barrier
	s_setprio 1
	v_mfma_f32_16x16x32_bf16 v[60:63], v[128:131], v[186:189], 0
	v_mfma_f32_16x16x32_bf16 v[56:59], v[136:139], v[186:189], 0
	v_mfma_f32_16x16x32_bf16 v[48:51], v[128:131], v[194:197], 0
	v_mfma_f32_16x16x32_bf16 v[40:43], v[136:139], v[194:197], 0
	v_mfma_f32_16x16x32_bf16 v[32:35], v[128:131], v[202:205], 0
	v_mfma_f32_16x16x32_bf16 v[24:27], v[136:139], v[202:205], 0
	v_mfma_f32_16x16x32_bf16 v[16:19], v[128:131], v[210:213], 0
	v_mfma_f32_16x16x32_bf16 v[8:11], v[136:139], v[210:213], 0
	v_mfma_f32_16x16x32_bf16 v[60:63], v[132:135], v[190:193], v[60:63]
	v_mfma_f32_16x16x32_bf16 v[56:59], v[140:143], v[190:193], v[56:59]
	v_mfma_f32_16x16x32_bf16 v[48:51], v[132:135], v[198:201], v[48:51]
	v_mfma_f32_16x16x32_bf16 v[40:43], v[140:143], v[198:201], v[40:43]
	v_mfma_f32_16x16x32_bf16 v[32:35], v[132:135], v[206:209], v[32:35]
	v_mfma_f32_16x16x32_bf16 v[24:27], v[140:143], v[206:209], v[24:27]
	v_mfma_f32_16x16x32_bf16 v[16:19], v[132:135], v[228:231], v[16:19]
	v_mfma_f32_16x16x32_bf16 v[8:11], v[140:143], v[228:231], v[8:11]
	v_mfma_f32_16x16x32_bf16 v[52:55], v[144:147], v[186:189], 0
	v_mfma_f32_16x16x32_bf16 v[44:47], v[166:169], v[186:189], 0
	v_mfma_f32_16x16x32_bf16 v[36:39], v[144:147], v[194:197], 0
	v_mfma_f32_16x16x32_bf16 v[28:31], v[166:169], v[194:197], 0
	v_mfma_f32_16x16x32_bf16 v[20:23], v[144:147], v[202:205], 0
	v_mfma_f32_16x16x32_bf16 v[12:15], v[166:169], v[202:205], 0
	v_mfma_f32_16x16x32_bf16 v[4:7], v[144:147], v[210:213], 0
	v_mfma_f32_16x16x32_bf16 v[0:3], v[166:169], v[210:213], 0
	v_mfma_f32_16x16x32_bf16 v[52:55], v[162:165], v[190:193], v[52:55]
	v_mfma_f32_16x16x32_bf16 v[44:47], v[170:173], v[190:193], v[44:47]
	v_mfma_f32_16x16x32_bf16 v[36:39], v[162:165], v[198:201], v[36:39]
	v_mfma_f32_16x16x32_bf16 v[28:31], v[170:173], v[198:201], v[28:31]
	s_setprio 2
	s_barrier
	v_mfma_f32_16x16x32_bf16 v[20:23], v[162:165], v[206:209], v[20:23]
	v_mfma_f32_16x16x32_bf16 v[12:15], v[170:173], v[206:209], v[12:15]
	v_mfma_f32_16x16x32_bf16 v[4:7], v[162:165], v[228:231], v[4:7]
	v_mfma_f32_16x16x32_bf16 v[0:3], v[170:173], v[228:231], v[0:3]
	s_setprio 0
	s_mov_b32 m0, s51
	s_nop 0
	global_load_lds_dwordx4 v150, s[24:25]
	s_and_saveexec_b64 s[78:79], s[2:3]
	v_add_f32_e32 v238, v238, v239
	v_add_f32_e32 v240, v240, v241
	v_add_f32_e32 v242, v242, v243
	v_add_f32_e32 v244, v244, v245
	v_add_f32_e32 v246, v246, v247
	v_add_f32_e32 v248, v248, v249
	v_add_f32_e32 v250, v250, v251
	v_add_f32_e32 v252, v252, v253
	v_add_f32_e32 v238, v238, v240
	v_add_f32_e32 v242, v242, v244
	v_add_f32_e32 v246, v246, v248
	v_add_f32_e32 v250, v250, v252
	v_add_f32_e32 v238, v238, v242
	v_add_f32_e32 v246, v246, v250
	v_add_f32_e32 v238, v238, v246
	v_fmamk_f32 v238, v238, 0x3a800000, v216
	v_rsq_f32_e32 v238, v238
	s_nop 0
	ds_write_b32 v183, v238
	s_mov_b64 exec, s[78:79]
	s_add_i32 s64, 0, 0x18000
	s_add_i32 s65, 0, 0x1c000
	ds_read_b128 v[128:131], v236 offset:32768
	ds_read_b128 v[132:135], v236 offset:33792
	ds_read_b128 v[136:139], v236 offset:34816
	ds_read_b128 v[140:143], v236 offset:35840
	ds_read_b128 v[144:147], v236 offset:49152
	ds_read_b128 v[162:165], v236 offset:50176
	ds_read_b128 v[166:169], v236 offset:51200
	ds_read_b128 v[170:173], v236 offset:52224
	s_add_u32 s24, s24, 0x40000
	s_addc_u32 s25, s25, 0
	s_mov_b32 m0, s52
	ds_read_b128 v[186:189], v185 offset:32768
	ds_read_b128 v[190:193], v185 offset:33792
	ds_read_b128 v[194:197], v185 offset:34816
	ds_read_b128 v[198:201], v185 offset:35840
	ds_read_b128 v[202:205], v185 offset:36864
	ds_read_b128 v[206:209], v185 offset:37888
	ds_read_b128 v[210:213], v185 offset:38912
	ds_read_b128 v[228:231], v185 offset:39936
	global_load_lds_dwordx4 v154, s[24:25]
	s_mov_b32 m0, s53
	s_nop 0
	global_load_lds_dwordx4 v150, s[24:25]
	s_waitcnt vmcnt(8) lgkmcnt(0)
	s_barrier
	s_setprio 1
	v_mfma_f32_16x16x32_bf16 v[124:127], v[128:131], v[186:189], v[124:127]
	v_mfma_f32_16x16x32_bf16 v[120:123], v[136:139], v[186:189], v[120:123]
	v_mfma_f32_16x16x32_bf16 v[108:111], v[128:131], v[194:197], v[108:111]
	v_mfma_f32_16x16x32_bf16 v[104:107], v[136:139], v[194:197], v[104:107]
	v_mfma_f32_16x16x32_bf16 v[92:95], v[128:131], v[202:205], v[92:95]
	v_mfma_f32_16x16x32_bf16 v[88:91], v[136:139], v[202:205], v[88:91]
	v_mfma_f32_16x16x32_bf16 v[76:79], v[128:131], v[210:213], v[76:79]
	v_mfma_f32_16x16x32_bf16 v[72:75], v[136:139], v[210:213], v[72:75]
	v_mfma_f32_16x16x32_bf16 v[124:127], v[132:135], v[190:193], v[124:127]
	v_mfma_f32_16x16x32_bf16 v[120:123], v[140:143], v[190:193], v[120:123]
	v_mfma_f32_16x16x32_bf16 v[108:111], v[132:135], v[198:201], v[108:111]
	v_mfma_f32_16x16x32_bf16 v[104:107], v[140:143], v[198:201], v[104:107]
	v_mfma_f32_16x16x32_bf16 v[92:95], v[132:135], v[206:209], v[92:95]
	v_mfma_f32_16x16x32_bf16 v[88:91], v[140:143], v[206:209], v[88:91]
	v_mfma_f32_16x16x32_bf16 v[76:79], v[132:135], v[228:231], v[76:79]
	v_mfma_f32_16x16x32_bf16 v[72:75], v[140:143], v[228:231], v[72:75]
	v_mfma_f32_16x16x32_bf16 v[116:119], v[144:147], v[186:189], v[116:119]
	v_mfma_f32_16x16x32_bf16 v[112:115], v[166:169], v[186:189], v[112:115]
	v_mfma_f32_16x16x32_bf16 v[100:103], v[144:147], v[194:197], v[100:103]
	v_mfma_f32_16x16x32_bf16 v[96:99], v[166:169], v[194:197], v[96:99]
	v_mfma_f32_16x16x32_bf16 v[84:87], v[144:147], v[202:205], v[84:87]
	v_mfma_f32_16x16x32_bf16 v[80:83], v[166:169], v[202:205], v[80:83]
	v_mfma_f32_16x16x32_bf16 v[68:71], v[144:147], v[210:213], v[68:71]
	v_mfma_f32_16x16x32_bf16 v[64:67], v[166:169], v[210:213], v[64:67]
	v_mfma_f32_16x16x32_bf16 v[116:119], v[162:165], v[190:193], v[116:119]
	v_mfma_f32_16x16x32_bf16 v[112:115], v[170:173], v[190:193], v[112:115]
	v_mfma_f32_16x16x32_bf16 v[100:103], v[162:165], v[198:201], v[100:103]
	v_mfma_f32_16x16x32_bf16 v[96:99], v[170:173], v[198:201], v[96:99]
	s_setprio 2
	s_barrier
	v_mfma_f32_16x16x32_bf16 v[84:87], v[162:165], v[206:209], v[84:87]
	v_mfma_f32_16x16x32_bf16 v[80:83], v[170:173], v[206:209], v[80:83]
	v_mfma_f32_16x16x32_bf16 v[68:71], v[162:165], v[228:231], v[68:71]
	v_mfma_f32_16x16x32_bf16 v[64:67], v[170:173], v[228:231], v[64:67]
	s_setprio 0
	s_min_i32 s74, s18, 0x80
	s_ashr_i32 s74, s74, 3
	s_mul_hi_i32 s75, s74, 0x3000
	s_mulk_i32 s74, 0x3000
	s_add_u32 s74, s54, s74
	s_addc_u32 s75, s55, s75
	s_lshl_b32 s76, s44, 8
	s_ashr_i32 s77, s76, 31
	s_lshl_b64 s[76:77], s[76:77], 2
	s_add_u32 s74, s74, s76
	s_addc_u32 s75, s75, s77
	v_lshl_add_u64 v[178:179], s[74:75], 0, v[176:177]
	global_load_dwordx4 v[238:241], v[178:179], off
	global_load_dwordx4 v[242:245], v[178:179], off offset:16
	global_load_dwordx4 v[246:249], v[178:179], off offset:512
	global_load_dwordx4 v[250:253], v[178:179], off offset:528
	s_add_i32 s24, s64, s46
	s_mov_b32 m0, s24
	ds_read_b128 v[186:189], v185 offset:49152
	ds_read_b128 v[190:193], v185 offset:50176
	ds_read_b128 v[194:197], v185 offset:51200
	ds_read_b128 v[198:201], v185 offset:52224
	ds_read_b128 v[202:205], v185 offset:53248
	ds_read_b128 v[206:209], v185 offset:54272
	ds_read_b128 v[210:213], v185 offset:55296
	ds_read_b128 v[228:231], v185 offset:56320
	global_load_lds_dwordx4 v152, s[94:95]
	s_add_i32 m0, s24, 0x2000
	s_add_u32 s22, s22, 0x40080
	s_addc_u32 s23, s23, 0
	s_add_i32 s24, s65, s46
	global_load_lds_dwordx4 v148, s[94:95]
	s_mov_b32 m0, s24
	s_nop 0
	global_load_lds_dwordx4 v152, s[22:23]
	s_add_i32 m0, s24, 0x2000
	s_nop 0
	global_load_lds_dwordx4 v148, s[22:23]
	s_mov_b32 m0, s56
	s_nop 0
	global_load_lds_dwordx4 v154, s[98:99]
	s_mov_b32 m0, s57
	s_nop 0
	global_load_lds_dwordx4 v150, s[98:99]
	s_waitcnt vmcnt(12) lgkmcnt(0)
	s_barrier
	s_setprio 1
	v_mfma_f32_16x16x32_bf16 v[60:63], v[128:131], v[186:189], v[60:63]
	v_mfma_f32_16x16x32_bf16 v[56:59], v[136:139], v[186:189], v[56:59]
	v_mfma_f32_16x16x32_bf16 v[48:51], v[128:131], v[194:197], v[48:51]
	v_mfma_f32_16x16x32_bf16 v[40:43], v[136:139], v[194:197], v[40:43]
	v_mfma_f32_16x16x32_bf16 v[32:35], v[128:131], v[202:205], v[32:35]
	v_mfma_f32_16x16x32_bf16 v[24:27], v[136:139], v[202:205], v[24:27]
	v_mfma_f32_16x16x32_bf16 v[16:19], v[128:131], v[210:213], v[16:19]
	v_mfma_f32_16x16x32_bf16 v[8:11], v[136:139], v[210:213], v[8:11]
	v_mfma_f32_16x16x32_bf16 v[60:63], v[132:135], v[190:193], v[60:63]
	v_mfma_f32_16x16x32_bf16 v[56:59], v[140:143], v[190:193], v[56:59]
	v_mfma_f32_16x16x32_bf16 v[48:51], v[132:135], v[198:201], v[48:51]
	v_mfma_f32_16x16x32_bf16 v[40:43], v[140:143], v[198:201], v[40:43]
	v_mfma_f32_16x16x32_bf16 v[32:35], v[132:135], v[206:209], v[32:35]
	v_mfma_f32_16x16x32_bf16 v[24:27], v[140:143], v[206:209], v[24:27]
	v_mfma_f32_16x16x32_bf16 v[16:19], v[132:135], v[228:231], v[16:19]
	v_mfma_f32_16x16x32_bf16 v[8:11], v[140:143], v[228:231], v[8:11]
	v_mfma_f32_16x16x32_bf16 v[52:55], v[144:147], v[186:189], v[52:55]
	v_mfma_f32_16x16x32_bf16 v[44:47], v[166:169], v[186:189], v[44:47]
	v_mfma_f32_16x16x32_bf16 v[36:39], v[144:147], v[194:197], v[36:39]
	v_mfma_f32_16x16x32_bf16 v[28:31], v[166:169], v[194:197], v[28:31]
	v_mfma_f32_16x16x32_bf16 v[20:23], v[144:147], v[202:205], v[20:23]
	v_mfma_f32_16x16x32_bf16 v[12:15], v[166:169], v[202:205], v[12:15]
	v_mfma_f32_16x16x32_bf16 v[4:7], v[144:147], v[210:213], v[4:7]
	v_mfma_f32_16x16x32_bf16 v[0:3], v[166:169], v[210:213], v[0:3]
	v_mfma_f32_16x16x32_bf16 v[52:55], v[162:165], v[190:193], v[52:55]
	v_mfma_f32_16x16x32_bf16 v[44:47], v[170:173], v[190:193], v[44:47]
	v_mfma_f32_16x16x32_bf16 v[36:39], v[162:165], v[198:201], v[36:39]
	v_mfma_f32_16x16x32_bf16 v[28:31], v[170:173], v[198:201], v[28:31]
	s_setprio 2
	s_barrier
	v_mfma_f32_16x16x32_bf16 v[20:23], v[162:165], v[206:209], v[20:23]
	v_mfma_f32_16x16x32_bf16 v[12:15], v[170:173], v[206:209], v[12:15]
	v_mfma_f32_16x16x32_bf16 v[4:7], v[162:165], v[228:231], v[4:7]
	v_mfma_f32_16x16x32_bf16 v[0:3], v[170:173], v[228:231], v[0:3]
	s_setprio 0
	s_add_i32 s63, s63, 2
	s_add_u32 s61, s61, 0x100
	s_addc_u32 s62, s62, 0
	s_add_u32 s20, s20, 0x100
	s_addc_u32 s21, s21, 0
	s_cmp_gt_u32 s63, 13
	s_cbranch_scc1 .Lpeel_exit_1
.LBB0_634:
	s_add_u32 s22, s20, 0xfffc0080
	s_addc_u32 s23, s21, -1
	s_add_i32 s64, 0, 0x10000
	s_cmp_eq_u32 s63, 12
	s_cselect_b32 s25, s13, s23
	s_cselect_b32 s24, s19, s22
	s_cselect_b32 s23, s11, s62
	s_cselect_b32 s22, s60, s61
	s_add_i32 s68, 0, 0x14000
	s_waitcnt lgkmcnt(0)
	ds_read_b128 v[128:131], v236
	ds_read_b128 v[132:135], v236 offset:1024
	ds_read_b128 v[136:139], v236 offset:2048
	ds_read_b128 v[140:143], v236 offset:3072
	ds_read_b128 v[144:147], v236 offset:16384
	ds_read_b128 v[162:165], v236 offset:17408
	ds_read_b128 v[166:169], v236 offset:18432
	ds_read_b128 v[170:173], v236 offset:19456
	s_add_i32 m0, s50, 0xc000
	ds_read_b128 v[186:189], v185
	ds_read_b128 v[190:193], v185 offset:1024
	ds_read_b128 v[194:197], v185 offset:2048
	ds_read_b128 v[198:201], v185 offset:3072
	ds_read_b128 v[202:205], v185 offset:4096
	ds_read_b128 v[206:209], v185 offset:5120
	ds_read_b128 v[210:213], v185 offset:6144
	ds_read_b128 v[228:231], v185 offset:7168
	global_load_lds_dwordx4 v160, s[20:21]
	s_add_i32 m0, s50, 0xe000
	s_nop 0
	global_load_lds_dwordx4 v158, s[20:21]
	s_waitcnt vmcnt(8) lgkmcnt(0)
	s_barrier
	s_setprio 1
	v_mfma_f32_16x16x32_bf16 v[124:127], v[128:131], v[186:189], v[124:127]
	v_mfma_f32_16x16x32_bf16 v[120:123], v[136:139], v[186:189], v[120:123]
	v_mfma_f32_16x16x32_bf16 v[108:111], v[128:131], v[194:197], v[108:111]
	v_mfma_f32_16x16x32_bf16 v[104:107], v[136:139], v[194:197], v[104:107]
	v_mfma_f32_16x16x32_bf16 v[92:95], v[128:131], v[202:205], v[92:95]
	v_mfma_f32_16x16x32_bf16 v[88:91], v[136:139], v[202:205], v[88:91]
	v_mfma_f32_16x16x32_bf16 v[76:79], v[128:131], v[210:213], v[76:79]
	v_mfma_f32_16x16x32_bf16 v[72:75], v[136:139], v[210:213], v[72:75]
	v_mfma_f32_16x16x32_bf16 v[124:127], v[132:135], v[190:193], v[124:127]
	v_mfma_f32_16x16x32_bf16 v[120:123], v[140:143], v[190:193], v[120:123]
	v_mfma_f32_16x16x32_bf16 v[108:111], v[132:135], v[198:201], v[108:111]
	v_mfma_f32_16x16x32_bf16 v[104:107], v[140:143], v[198:201], v[104:107]
	v_mfma_f32_16x16x32_bf16 v[92:95], v[132:135], v[206:209], v[92:95]
	v_mfma_f32_16x16x32_bf16 v[88:91], v[140:143], v[206:209], v[88:91]
	v_mfma_f32_16x16x32_bf16 v[76:79], v[132:135], v[228:231], v[76:79]
	v_mfma_f32_16x16x32_bf16 v[72:75], v[140:143], v[228:231], v[72:75]
	v_mfma_f32_16x16x32_bf16 v[116:119], v[144:147], v[186:189], v[116:119]
	v_mfma_f32_16x16x32_bf16 v[112:115], v[166:169], v[186:189], v[112:115]
	v_mfma_f32_16x16x32_bf16 v[100:103], v[144:147], v[194:197], v[100:103]
	v_mfma_f32_16x16x32_bf16 v[96:99], v[166:169], v[194:197], v[96:99]
	v_mfma_f32_16x16x32_bf16 v[84:87], v[144:147], v[202:205], v[84:87]
	v_mfma_f32_16x16x32_bf16 v[80:83], v[166:169], v[202:205], v[80:83]
	v_mfma_f32_16x16x32_bf16 v[68:71], v[144:147], v[210:213], v[68:71]
	v_mfma_f32_16x16x32_bf16 v[64:67], v[166:169], v[210:213], v[64:67]
	v_mfma_f32_16x16x32_bf16 v[116:119], v[162:165], v[190:193], v[116:119]
	v_mfma_f32_16x16x32_bf16 v[112:115], v[170:173], v[190:193], v[112:115]
	v_mfma_f32_16x16x32_bf16 v[100:103], v[162:165], v[198:201], v[100:103]
	v_mfma_f32_16x16x32_bf16 v[96:99], v[170:173], v[198:201], v[96:99]
	s_setprio 2
	s_barrier
	v_mfma_f32_16x16x32_bf16 v[84:87], v[162:165], v[206:209], v[84:87]
	v_mfma_f32_16x16x32_bf16 v[80:83], v[170:173], v[206:209], v[80:83]
	v_mfma_f32_16x16x32_bf16 v[68:71], v[162:165], v[228:231], v[68:71]
	v_mfma_f32_16x16x32_bf16 v[64:67], v[170:173], v[228:231], v[64:67]
	s_setprio 0
	s_add_i32 s64, s64, s46
	s_add_u32 s94, s22, s34
	s_addc_u32 s95, s23, s35
	s_mov_b32 m0, s64
	ds_read_b128 v[186:189], v185 offset:16384
	ds_read_b128 v[190:193], v185 offset:17408
	ds_read_b128 v[194:197], v185 offset:18432
	ds_read_b128 v[198:201], v185 offset:19456
	ds_read_b128 v[202:205], v185 offset:20480
	ds_read_b128 v[206:209], v185 offset:21504
	ds_read_b128 v[210:213], v185 offset:22528
	ds_read_b128 v[228:231], v185 offset:23552
	global_load_lds_dwordx4 v152, s[22:23]
	s_add_i32 m0, s64, 0x2000
	s_add_u32 s64, s22, 0x40000
	s_addc_u32 s65, s23, 0
	s_add_i32 s68, s68, s46
	global_load_lds_dwordx4 v148, s[22:23]
	s_mov_b32 m0, s68
	s_nop 0
	global_load_lds_dwordx4 v152, s[64:65]
	s_add_i32 m0, s68, 0x2000
	s_nop 0
	global_load_lds_dwordx4 v148, s[64:65]
	s_add_u32 s98, s24, s34
	s_addc_u32 s99, s25, s35
	s_mov_b32 m0, s50
	s_nop 0
	global_load_lds_dwordx4 v154, s[24:25]
	s_waitcnt vmcnt(7) lgkmcnt(0)
	s_barrier
	s_setprio 1
	v_mfma_f32_16x16x32_bf16 v[60:63], v[128:131], v[186:189], v[60:63]
	v_mfma_f32_16x16x32_bf16 v[56:59], v[136:139], v[186:189], v[56:59]
	v_mfma_f32_16x16x32_bf16 v[48:51], v[128:131], v[194:197], v[48:51]
	v_mfma_f32_16x16x32_bf16 v[40:43], v[136:139], v[194:197], v[40:43]
	v_mfma_f32_16x16x32_bf16 v[32:35], v[128:131], v[202:205], v[32:35]
	v_mfma_f32_16x16x32_bf16 v[24:27], v[136:139], v[202:205], v[24:27]
	v_mfma_f32_16x16x32_bf16 v[16:19], v[128:131], v[210:213], v[16:19]
	v_mfma_f32_16x16x32_bf16 v[8:11], v[136:139], v[210:213], v[8:11]
	v_mfma_f32_16x16x32_bf16 v[60:63], v[132:135], v[190:193], v[60:63]
	v_mfma_f32_16x16x32_bf16 v[56:59], v[140:143], v[190:193], v[56:59]
	v_mfma_f32_16x16x32_bf16 v[48:51], v[132:135], v[198:201], v[48:51]
	v_mfma_f32_16x16x32_bf16 v[40:43], v[140:143], v[198:201], v[40:43]
	v_mfma_f32_16x16x32_bf16 v[32:35], v[132:135], v[206:209], v[32:35]
	v_mfma_f32_16x16x32_bf16 v[24:27], v[140:143], v[206:209], v[24:27]
	v_mfma_f32_16x16x32_bf16 v[16:19], v[132:135], v[228:231], v[16:19]
	v_mfma_f32_16x16x32_bf16 v[8:11], v[140:143], v[228:231], v[8:11]
	v_mfma_f32_16x16x32_bf16 v[52:55], v[144:147], v[186:189], v[52:55]
	v_mfma_f32_16x16x32_bf16 v[44:47], v[166:169], v[186:189], v[44:47]
	v_mfma_f32_16x16x32_bf16 v[36:39], v[144:147], v[194:197], v[36:39]
	v_mfma_f32_16x16x32_bf16 v[28:31], v[166:169], v[194:197], v[28:31]
	v_mfma_f32_16x16x32_bf16 v[20:23], v[144:147], v[202:205], v[20:23]
	v_mfma_f32_16x16x32_bf16 v[12:15], v[166:169], v[202:205], v[12:15]
	v_mfma_f32_16x16x32_bf16 v[4:7], v[144:147], v[210:213], v[4:7]
	v_mfma_f32_16x16x32_bf16 v[0:3], v[166:169], v[210:213], v[0:3]
	v_mfma_f32_16x16x32_bf16 v[52:55], v[162:165], v[190:193], v[52:55]
	v_mfma_f32_16x16x32_bf16 v[44:47], v[170:173], v[190:193], v[44:47]
	v_mfma_f32_16x16x32_bf16 v[36:39], v[162:165], v[198:201], v[36:39]
	v_mfma_f32_16x16x32_bf16 v[28:31], v[170:173], v[198:201], v[28:31]
	s_setprio 2
	s_barrier
	v_mfma_f32_16x16x32_bf16 v[20:23], v[162:165], v[206:209], v[20:23]
	v_mfma_f32_16x16x32_bf16 v[12:15], v[170:173], v[206:209], v[12:15]
	v_mfma_f32_16x16x32_bf16 v[4:7], v[162:165], v[228:231], v[4:7]
	v_mfma_f32_16x16x32_bf16 v[0:3], v[170:173], v[228:231], v[0:3]
	s_setprio 0
	s_mov_b32 m0, s51
	s_nop 0
	global_load_lds_dwordx4 v150, s[24:25]
	s_add_i32 s64, 0, 0x18000
	s_add_i32 s65, 0, 0x1c000
	ds_read_b128 v[128:131], v236 offset:32768
	ds_read_b128 v[132:135], v236 offset:33792
	ds_read_b128 v[136:139], v236 offset:34816
	ds_read_b128 v[140:143], v236 offset:35840
	ds_read_b128 v[144:147], v236 offset:49152
	ds_read_b128 v[162:165], v236 offset:50176
	ds_read_b128 v[166:169], v236 offset:51200
	ds_read_b128 v[170:173], v236 offset:52224
	s_add_u32 s24, s24, 0x40000
	s_addc_u32 s25, s25, 0
	s_mov_b32 m0, s52
	ds_read_b128 v[186:189], v185 offset:32768
	ds_read_b128 v[190:193], v185 offset:33792
	ds_read_b128 v[194:197], v185 offset:34816
	ds_read_b128 v[198:201], v185 offset:35840
	ds_read_b128 v[202:205], v185 offset:36864
	ds_read_b128 v[206:209], v185 offset:37888
	ds_read_b128 v[210:213], v185 offset:38912
	ds_read_b128 v[228:231], v185 offset:39936
	global_load_lds_dwordx4 v154, s[24:25]
	s_mov_b32 m0, s53
	s_nop 0
	global_load_lds_dwordx4 v150, s[24:25]
	s_waitcnt vmcnt(8) lgkmcnt(0)
	s_barrier
	s_setprio 1
	v_mfma_f32_16x16x32_bf16 v[124:127], v[128:131], v[186:189], v[124:127]
	v_mfma_f32_16x16x32_bf16 v[120:123], v[136:139], v[186:189], v[120:123]
	v_mfma_f32_16x16x32_bf16 v[108:111], v[128:131], v[194:197], v[108:111]
	v_mfma_f32_16x16x32_bf16 v[104:107], v[136:139], v[194:197], v[104:107]
	v_mfma_f32_16x16x32_bf16 v[92:95], v[128:131], v[202:205], v[92:95]
	v_mfma_f32_16x16x32_bf16 v[88:91], v[136:139], v[202:205], v[88:91]
	v_mfma_f32_16x16x32_bf16 v[76:79], v[128:131], v[210:213], v[76:79]
	v_mfma_f32_16x16x32_bf16 v[72:75], v[136:139], v[210:213], v[72:75]
	v_mfma_f32_16x16x32_bf16 v[124:127], v[132:135], v[190:193], v[124:127]
	v_mfma_f32_16x16x32_bf16 v[120:123], v[140:143], v[190:193], v[120:123]
	v_mfma_f32_16x16x32_bf16 v[108:111], v[132:135], v[198:201], v[108:111]
	v_mfma_f32_16x16x32_bf16 v[104:107], v[140:143], v[198:201], v[104:107]
	v_mfma_f32_16x16x32_bf16 v[92:95], v[132:135], v[206:209], v[92:95]
	v_mfma_f32_16x16x32_bf16 v[88:91], v[140:143], v[206:209], v[88:91]
	v_mfma_f32_16x16x32_bf16 v[76:79], v[132:135], v[228:231], v[76:79]
	v_mfma_f32_16x16x32_bf16 v[72:75], v[140:143], v[228:231], v[72:75]
	v_mfma_f32_16x16x32_bf16 v[116:119], v[144:147], v[186:189], v[116:119]
	v_mfma_f32_16x16x32_bf16 v[112:115], v[166:169], v[186:189], v[112:115]
	v_mfma_f32_16x16x32_bf16 v[100:103], v[144:147], v[194:197], v[100:103]
	v_mfma_f32_16x16x32_bf16 v[96:99], v[166:169], v[194:197], v[96:99]
	v_mfma_f32_16x16x32_bf16 v[84:87], v[144:147], v[202:205], v[84:87]
	v_mfma_f32_16x16x32_bf16 v[80:83], v[166:169], v[202:205], v[80:83]
	v_mfma_f32_16x16x32_bf16 v[68:71], v[144:147], v[210:213], v[68:71]
	v_mfma_f32_16x16x32_bf16 v[64:67], v[166:169], v[210:213], v[64:67]
	v_mfma_f32_16x16x32_bf16 v[116:119], v[162:165], v[190:193], v[116:119]
	v_mfma_f32_16x16x32_bf16 v[112:115], v[170:173], v[190:193], v[112:115]
	v_mfma_f32_16x16x32_bf16 v[100:103], v[162:165], v[198:201], v[100:103]
	v_mfma_f32_16x16x32_bf16 v[96:99], v[170:173], v[198:201], v[96:99]
	s_setprio 2
	s_barrier
	v_mfma_f32_16x16x32_bf16 v[84:87], v[162:165], v[206:209], v[84:87]
	v_mfma_f32_16x16x32_bf16 v[80:83], v[170:173], v[206:209], v[80:83]
	v_mfma_f32_16x16x32_bf16 v[68:71], v[162:165], v[228:231], v[68:71]
	v_mfma_f32_16x16x32_bf16 v[64:67], v[170:173], v[228:231], v[64:67]
	s_setprio 0
	s_add_i32 s24, s64, s46
	s_mov_b32 m0, s24
	ds_read_b128 v[186:189], v185 offset:49152
	ds_read_b128 v[190:193], v185 offset:50176
	ds_read_b128 v[194:197], v185 offset:51200
	ds_read_b128 v[198:201], v185 offset:52224
	ds_read_b128 v[202:205], v185 offset:53248
	ds_read_b128 v[206:209], v185 offset:54272
	ds_read_b128 v[210:213], v185 offset:55296
	ds_read_b128 v[228:231], v185 offset:56320
	global_load_lds_dwordx4 v152, s[94:95]
	s_add_i32 m0, s24, 0x2000
	s_add_u32 s22, s22, 0x40080
	s_addc_u32 s23, s23, 0
	s_add_i32 s24, s65, s46
	global_load_lds_dwordx4 v148, s[94:95]
	s_mov_b32 m0, s24
	s_nop 0
	global_load_lds_dwordx4 v152, s[22:23]
	s_add_i32 m0, s24, 0x2000
	s_nop 0
	global_load_lds_dwordx4 v148, s[22:23]
	s_mov_b32 m0, s56
	s_nop 0
	global_load_lds_dwordx4 v154, s[98:99]
	s_mov_b32 m0, s57
	s_nop 0
	global_load_lds_dwordx4 v150, s[98:99]
	s_waitcnt vmcnt(8) lgkmcnt(0)
	s_barrier
	s_setprio 1
	v_mfma_f32_16x16x32_bf16 v[60:63], v[128:131], v[186:189], v[60:63]
	v_mfma_f32_16x16x32_bf16 v[56:59], v[136:139], v[186:189], v[56:59]
	v_mfma_f32_16x16x32_bf16 v[48:51], v[128:131], v[194:197], v[48:51]
	v_mfma_f32_16x16x32_bf16 v[40:43], v[136:139], v[194:197], v[40:43]
	v_mfma_f32_16x16x32_bf16 v[32:35], v[128:131], v[202:205], v[32:35]
	v_mfma_f32_16x16x32_bf16 v[24:27], v[136:139], v[202:205], v[24:27]
	v_mfma_f32_16x16x32_bf16 v[16:19], v[128:131], v[210:213], v[16:19]
	v_mfma_f32_16x16x32_bf16 v[8:11], v[136:139], v[210:213], v[8:11]
	v_mfma_f32_16x16x32_bf16 v[60:63], v[132:135], v[190:193], v[60:63]
	v_mfma_f32_16x16x32_bf16 v[56:59], v[140:143], v[190:193], v[56:59]
	v_mfma_f32_16x16x32_bf16 v[48:51], v[132:135], v[198:201], v[48:51]
	v_mfma_f32_16x16x32_bf16 v[40:43], v[140:143], v[198:201], v[40:43]
	v_mfma_f32_16x16x32_bf16 v[32:35], v[132:135], v[206:209], v[32:35]
	v_mfma_f32_16x16x32_bf16 v[24:27], v[140:143], v[206:209], v[24:27]
	v_mfma_f32_16x16x32_bf16 v[16:19], v[132:135], v[228:231], v[16:19]
	v_mfma_f32_16x16x32_bf16 v[8:11], v[140:143], v[228:231], v[8:11]
	v_mfma_f32_16x16x32_bf16 v[52:55], v[144:147], v[186:189], v[52:55]
	v_mfma_f32_16x16x32_bf16 v[44:47], v[166:169], v[186:189], v[44:47]
	v_mfma_f32_16x16x32_bf16 v[36:39], v[144:147], v[194:197], v[36:39]
	v_mfma_f32_16x16x32_bf16 v[28:31], v[166:169], v[194:197], v[28:31]
	v_mfma_f32_16x16x32_bf16 v[20:23], v[144:147], v[202:205], v[20:23]
	v_mfma_f32_16x16x32_bf16 v[12:15], v[166:169], v[202:205], v[12:15]
	v_mfma_f32_16x16x32_bf16 v[4:7], v[144:147], v[210:213], v[4:7]
	v_mfma_f32_16x16x32_bf16 v[0:3], v[166:169], v[210:213], v[0:3]
	v_mfma_f32_16x16x32_bf16 v[52:55], v[162:165], v[190:193], v[52:55]
	v_mfma_f32_16x16x32_bf16 v[44:47], v[170:173], v[190:193], v[44:47]
	v_mfma_f32_16x16x32_bf16 v[36:39], v[162:165], v[198:201], v[36:39]
	v_mfma_f32_16x16x32_bf16 v[28:31], v[170:173], v[198:201], v[28:31]
	s_setprio 2
	s_barrier
	v_mfma_f32_16x16x32_bf16 v[20:23], v[162:165], v[206:209], v[20:23]
	v_mfma_f32_16x16x32_bf16 v[12:15], v[170:173], v[206:209], v[12:15]
	v_mfma_f32_16x16x32_bf16 v[4:7], v[162:165], v[228:231], v[4:7]
	v_mfma_f32_16x16x32_bf16 v[0:3], v[170:173], v[228:231], v[0:3]
	s_setprio 0
	s_add_i32 s63, s63, 2
	s_add_u32 s61, s61, 0x100
	s_addc_u32 s62, s62, 0
	s_add_u32 s20, s20, 0x100
	s_addc_u32 s21, s21, 0
	s_cmp_gt_u32 s63, 13
	s_cbranch_scc0 .LBB0_634

.LBB0_768:
	s_add_u32 s44, s40, 0x100
	s_addc_u32 s55, s41, 0
	s_mov_b32 s92, -2
	v_add_u32_e32 v226, 0x10000, v228
	s_add_u32 s40, s8, 0x100
	s_addc_u32 s41, s9, 0
	s_add_i32 s64, 0, 0x10000
	s_cmp_eq_u32 s92, 40
	s_cselect_b32 s53, s1, s41
	s_cselect_b32 s52, s0, s40
	s_cselect_b32 s51, s39, s55
	s_cselect_b32 s50, s38, s44
	s_add_i32 s65, 0, 0x14000
	ds_read_b128 v[128:131], v226
	ds_read_b128 v[132:135], v226 offset:1024
	ds_read_b128 v[136:139], v226 offset:2048
	ds_read_b128 v[140:143], v226 offset:3072
	ds_read_b128 v[144:147], v226 offset:16384
	ds_read_b128 v[148:151], v226 offset:17408
	ds_read_b128 v[152:155], v226 offset:18432
	ds_read_b128 v[156:159], v226 offset:19456
	s_add_i32 m0, s62, 0xc000
	ds_read_b128 v[160:163], v231
	ds_read_b128 v[164:167], v231 offset:1024
	ds_read_b128 v[186:189], v231 offset:2048
	ds_read_b128 v[190:193], v231 offset:3072
	ds_read_b128 v[194:197], v231 offset:4096
	ds_read_b128 v[198:201], v231 offset:5120
	ds_read_b128 v[202:205], v231 offset:6144
	ds_read_b128 v[206:209], v231 offset:7168
	global_load_lds_dwordx4 v184, s[8:9]
	s_add_i32 m0, s62, 0xe000
	s_nop 0
	global_load_lds_dwordx4 v182, s[8:9]
	s_waitcnt vmcnt(24) lgkmcnt(0)
	s_barrier
	s_setprio 1
	v_mfma_f32_16x16x32_bf16 v[124:127], v[128:131], v[160:163], 0
	v_mfma_f32_16x16x32_bf16 v[120:123], v[136:139], v[160:163], 0
	v_mfma_f32_16x16x32_bf16 v[108:111], v[128:131], v[186:189], 0
	v_mfma_f32_16x16x32_bf16 v[104:107], v[136:139], v[186:189], 0
	v_mfma_f32_16x16x32_bf16 v[92:95], v[128:131], v[194:197], 0
	v_mfma_f32_16x16x32_bf16 v[88:91], v[136:139], v[194:197], 0
	v_mfma_f32_16x16x32_bf16 v[76:79], v[128:131], v[202:205], 0
	v_mfma_f32_16x16x32_bf16 v[72:75], v[136:139], v[202:205], 0
	v_mfma_f32_16x16x32_bf16 v[124:127], v[132:135], v[164:167], v[124:127]
	v_mfma_f32_16x16x32_bf16 v[120:123], v[140:143], v[164:167], v[120:123]
	v_mfma_f32_16x16x32_bf16 v[108:111], v[132:135], v[190:193], v[108:111]
	v_mfma_f32_16x16x32_bf16 v[104:107], v[140:143], v[190:193], v[104:107]
	v_mfma_f32_16x16x32_bf16 v[92:95], v[132:135], v[198:201], v[92:95]
	v_mfma_f32_16x16x32_bf16 v[88:91], v[140:143], v[198:201], v[88:91]
	v_mfma_f32_16x16x32_bf16 v[76:79], v[132:135], v[206:209], v[76:79]
	v_mfma_f32_16x16x32_bf16 v[72:75], v[140:143], v[206:209], v[72:75]
	v_mfma_f32_16x16x32_bf16 v[116:119], v[144:147], v[160:163], 0
	v_mfma_f32_16x16x32_bf16 v[112:115], v[152:155], v[160:163], 0
	v_mfma_f32_16x16x32_bf16 v[100:103], v[144:147], v[186:189], 0
	v_mfma_f32_16x16x32_bf16 v[96:99], v[152:155], v[186:189], 0
	v_mfma_f32_16x16x32_bf16 v[84:87], v[144:147], v[194:197], 0
	v_mfma_f32_16x16x32_bf16 v[80:83], v[152:155], v[194:197], 0
	v_mfma_f32_16x16x32_bf16 v[68:71], v[144:147], v[202:205], 0
	v_mfma_f32_16x16x32_bf16 v[64:67], v[152:155], v[202:205], 0
	v_mfma_f32_16x16x32_bf16 v[116:119], v[148:151], v[164:167], v[116:119]
	v_mfma_f32_16x16x32_bf16 v[112:115], v[156:159], v[164:167], v[112:115]
	v_mfma_f32_16x16x32_bf16 v[100:103], v[148:151], v[190:193], v[100:103]
	v_mfma_f32_16x16x32_bf16 v[96:99], v[156:159], v[190:193], v[96:99]
	s_setprio 2
	s_barrier
	v_mfma_f32_16x16x32_bf16 v[84:87], v[148:151], v[198:201], v[84:87]
	v_mfma_f32_16x16x32_bf16 v[80:83], v[156:159], v[198:201], v[80:83]
	v_mfma_f32_16x16x32_bf16 v[68:71], v[148:151], v[206:209], v[68:71]
	v_mfma_f32_16x16x32_bf16 v[64:67], v[156:159], v[206:209], v[64:67]
	s_setprio 0
	s_add_i32 s8, s64, s37
	s_add_u32 s98, s50, s34
	s_addc_u32 s99, s51, s35
	s_mov_b32 m0, s8
	ds_read_b128 v[160:163], v231 offset:16384
	ds_read_b128 v[164:167], v231 offset:17408
	ds_read_b128 v[186:189], v231 offset:18432
	ds_read_b128 v[190:193], v231 offset:19456
	ds_read_b128 v[194:197], v231 offset:20480
	ds_read_b128 v[198:201], v231 offset:21504
	ds_read_b128 v[202:205], v231 offset:22528
	ds_read_b128 v[206:209], v231 offset:23552
	global_load_lds_dwordx4 v170, s[50:51]
	s_add_i32 m0, s8, 0x2000
	s_add_u32 s8, s50, 0xb0000
	s_addc_u32 s9, s51, 0
	s_add_i32 s64, s65, s37
	global_load_lds_dwordx4 v174, s[50:51]
	s_mov_b32 m0, s64
	s_nop 0
	global_load_lds_dwordx4 v170, s[8:9]
	s_add_i32 m0, s64, 0x2000
	s_nop 0
	global_load_lds_dwordx4 v174, s[8:9]
	s_add_u32 s100, s52, s34
	s_addc_u32 s101, s53, s35
	s_mov_b32 m0, s62
	s_nop 0
	global_load_lds_dwordx4 v168, s[52:53]
	s_waitcnt vmcnt(7) lgkmcnt(0)
	s_barrier
	s_setprio 1
	v_mfma_f32_16x16x32_bf16 v[60:63], v[128:131], v[160:163], 0
	v_mfma_f32_16x16x32_bf16 v[56:59], v[136:139], v[160:163], 0
	v_mfma_f32_16x16x32_bf16 v[44:47], v[128:131], v[186:189], 0
	v_mfma_f32_16x16x32_bf16 v[40:43], v[136:139], v[186:189], 0
	v_mfma_f32_16x16x32_bf16 v[28:31], v[128:131], v[194:197], 0
	v_mfma_f32_16x16x32_bf16 v[24:27], v[136:139], v[194:197], 0
	v_mfma_f32_16x16x32_bf16 v[12:15], v[128:131], v[202:205], 0
	v_mfma_f32_16x16x32_bf16 v[8:11], v[136:139], v[202:205], 0
	v_mfma_f32_16x16x32_bf16 v[60:63], v[132:135], v[164:167], v[60:63]
	v_mfma_f32_16x16x32_bf16 v[56:59], v[140:143], v[164:167], v[56:59]
	v_mfma_f32_16x16x32_bf16 v[44:47], v[132:135], v[190:193], v[44:47]
	v_mfma_f32_16x16x32_bf16 v[40:43], v[140:143], v[190:193], v[40:43]
	v_mfma_f32_16x16x32_bf16 v[28:31], v[132:135], v[198:201], v[28:31]
	v_mfma_f32_16x16x32_bf16 v[24:27], v[140:143], v[198:201], v[24:27]
	v_mfma_f32_16x16x32_bf16 v[12:15], v[132:135], v[206:209], v[12:15]
	v_mfma_f32_16x16x32_bf16 v[8:11], v[140:143], v[206:209], v[8:11]
	v_mfma_f32_16x16x32_bf16 v[52:55], v[144:147], v[160:163], 0
	v_mfma_f32_16x16x32_bf16 v[48:51], v[152:155], v[160:163], 0
	v_mfma_f32_16x16x32_bf16 v[36:39], v[144:147], v[186:189], 0
	v_mfma_f32_16x16x32_bf16 v[32:35], v[152:155], v[186:189], 0
	v_mfma_f32_16x16x32_bf16 v[20:23], v[144:147], v[194:197], 0
	v_mfma_f32_16x16x32_bf16 v[16:19], v[152:155], v[194:197], 0
	v_mfma_f32_16x16x32_bf16 v[4:7], v[144:147], v[202:205], 0
	v_mfma_f32_16x16x32_bf16 v[0:3], v[152:155], v[202:205], 0
	v_mfma_f32_16x16x32_bf16 v[52:55], v[148:151], v[164:167], v[52:55]
	v_mfma_f32_16x16x32_bf16 v[48:51], v[156:159], v[164:167], v[48:51]
	v_mfma_f32_16x16x32_bf16 v[36:39], v[148:151], v[190:193], v[36:39]
	v_mfma_f32_16x16x32_bf16 v[32:35], v[156:159], v[190:193], v[32:35]
	s_setprio 2
	s_barrier
	v_mfma_f32_16x16x32_bf16 v[20:23], v[148:151], v[198:201], v[20:23]
	v_mfma_f32_16x16x32_bf16 v[16:19], v[156:159], v[198:201], v[16:19]
	v_mfma_f32_16x16x32_bf16 v[4:7], v[148:151], v[206:209], v[4:7]
	v_mfma_f32_16x16x32_bf16 v[0:3], v[156:159], v[206:209], v[0:3]
	s_setprio 0
	s_mov_b32 m0, s63
	s_nop 0
	global_load_lds_dwordx4 v172, s[52:53]
	s_add_i32 s64, 0, 0x18000
	s_add_i32 s65, 0, 0x1c000
	ds_read_b128 v[128:131], v226 offset:32768
	ds_read_b128 v[132:135], v226 offset:33792
	ds_read_b128 v[136:139], v226 offset:34816
	ds_read_b128 v[140:143], v226 offset:35840
	ds_read_b128 v[144:147], v226 offset:49152
	ds_read_b128 v[148:151], v226 offset:50176
	ds_read_b128 v[152:155], v226 offset:51200
	ds_read_b128 v[156:159], v226 offset:52224
	s_add_u32 s8, s52, 0xb0000
	s_addc_u32 s9, s53, 0
	s_mov_b32 m0, s68
	ds_read_b128 v[160:163], v231 offset:32768
	ds_read_b128 v[164:167], v231 offset:33792
	ds_read_b128 v[186:189], v231 offset:34816
	ds_read_b128 v[190:193], v231 offset:35840
	ds_read_b128 v[194:197], v231 offset:36864
	ds_read_b128 v[198:201], v231 offset:37888
	ds_read_b128 v[202:205], v231 offset:38912
	ds_read_b128 v[206:209], v231 offset:39936
	global_load_lds_dwordx4 v168, s[8:9]
	s_mov_b32 m0, s69
	s_nop 0
	global_load_lds_dwordx4 v172, s[8:9]
	s_waitcnt vmcnt(8) lgkmcnt(0)
	s_barrier
	s_setprio 1
	v_mfma_f32_16x16x32_bf16 v[124:127], v[128:131], v[160:163], v[124:127]
	v_mfma_f32_16x16x32_bf16 v[120:123], v[136:139], v[160:163], v[120:123]
	v_mfma_f32_16x16x32_bf16 v[108:111], v[128:131], v[186:189], v[108:111]
	v_mfma_f32_16x16x32_bf16 v[104:107], v[136:139], v[186:189], v[104:107]
	v_mfma_f32_16x16x32_bf16 v[92:95], v[128:131], v[194:197], v[92:95]
	v_mfma_f32_16x16x32_bf16 v[88:91], v[136:139], v[194:197], v[88:91]
	v_mfma_f32_16x16x32_bf16 v[76:79], v[128:131], v[202:205], v[76:79]
	v_mfma_f32_16x16x32_bf16 v[72:75], v[136:139], v[202:205], v[72:75]
	v_mfma_f32_16x16x32_bf16 v[124:127], v[132:135], v[164:167], v[124:127]
	v_mfma_f32_16x16x32_bf16 v[120:123], v[140:143], v[164:167], v[120:123]
	v_mfma_f32_16x16x32_bf16 v[108:111], v[132:135], v[190:193], v[108:111]
	v_mfma_f32_16x16x32_bf16 v[104:107], v[140:143], v[190:193], v[104:107]
	v_mfma_f32_16x16x32_bf16 v[92:95], v[132:135], v[198:201], v[92:95]
	v_mfma_f32_16x16x32_bf16 v[88:91], v[140:143], v[198:201], v[88:91]
	v_mfma_f32_16x16x32_bf16 v[76:79], v[132:135], v[206:209], v[76:79]
	v_mfma_f32_16x16x32_bf16 v[72:75], v[140:143], v[206:209], v[72:75]
	v_mfma_f32_16x16x32_bf16 v[116:119], v[144:147], v[160:163], v[116:119]
	v_mfma_f32_16x16x32_bf16 v[112:115], v[152:155], v[160:163], v[112:115]
	v_mfma_f32_16x16x32_bf16 v[100:103], v[144:147], v[186:189], v[100:103]
	v_mfma_f32_16x16x32_bf16 v[96:99], v[152:155], v[186:189], v[96:99]
	v_mfma_f32_16x16x32_bf16 v[84:87], v[144:147], v[194:197], v[84:87]
	v_mfma_f32_16x16x32_bf16 v[80:83], v[152:155], v[194:197], v[80:83]
	v_mfma_f32_16x16x32_bf16 v[68:71], v[144:147], v[202:205], v[68:71]
	v_mfma_f32_16x16x32_bf16 v[64:67], v[152:155], v[202:205], v[64:67]
	v_mfma_f32_16x16x32_bf16 v[116:119], v[148:151], v[164:167], v[116:119]
	v_mfma_f32_16x16x32_bf16 v[112:115], v[156:159], v[164:167], v[112:115]
	v_mfma_f32_16x16x32_bf16 v[100:103], v[148:151], v[190:193], v[100:103]
	v_mfma_f32_16x16x32_bf16 v[96:99], v[156:159], v[190:193], v[96:99]
	s_setprio 2
	s_barrier
	v_mfma_f32_16x16x32_bf16 v[84:87], v[148:151], v[198:201], v[84:87]
	v_mfma_f32_16x16x32_bf16 v[80:83], v[156:159], v[198:201], v[80:83]
	v_mfma_f32_16x16x32_bf16 v[68:71], v[148:151], v[206:209], v[68:71]
	v_mfma_f32_16x16x32_bf16 v[64:67], v[156:159], v[206:209], v[64:67]
	s_setprio 0
	s_add_i32 s8, s64, s37
	s_mov_b32 m0, s8
	ds_read_b128 v[160:163], v231 offset:49152
	ds_read_b128 v[164:167], v231 offset:50176
	ds_read_b128 v[186:189], v231 offset:51200
	ds_read_b128 v[190:193], v231 offset:52224
	ds_read_b128 v[194:197], v231 offset:53248
	ds_read_b128 v[198:201], v231 offset:54272
	ds_read_b128 v[202:205], v231 offset:55296
	ds_read_b128 v[206:209], v231 offset:56320
	global_load_lds_dwordx4 v170, s[98:99]
	s_add_i32 m0, s8, 0x2000
	s_add_u32 s8, s50, 0xb0080
	s_addc_u32 s9, s51, 0
	s_add_i32 s50, s65, s37
	global_load_lds_dwordx4 v174, s[98:99]
	s_mov_b32 m0, s50
	s_nop 0
	global_load_lds_dwordx4 v170, s[8:9]
	s_add_i32 m0, s50, 0x2000
	s_nop 0
	global_load_lds_dwordx4 v174, s[8:9]
	s_mov_b32 m0, s73
	s_nop 0
	global_load_lds_dwordx4 v168, s[100:101]
	s_mov_b32 m0, s74
	s_nop 0
	global_load_lds_dwordx4 v172, s[100:101]
	s_waitcnt vmcnt(8) lgkmcnt(0)
	s_barrier
	s_setprio 1
	v_mfma_f32_16x16x32_bf16 v[60:63], v[128:131], v[160:163], v[60:63]
	v_mfma_f32_16x16x32_bf16 v[56:59], v[136:139], v[160:163], v[56:59]
	v_mfma_f32_16x16x32_bf16 v[44:47], v[128:131], v[186:189], v[44:47]
	v_mfma_f32_16x16x32_bf16 v[40:43], v[136:139], v[186:189], v[40:43]
	v_mfma_f32_16x16x32_bf16 v[28:31], v[128:131], v[194:197], v[28:31]
	v_mfma_f32_16x16x32_bf16 v[24:27], v[136:139], v[194:197], v[24:27]
	v_mfma_f32_16x16x32_bf16 v[12:15], v[128:131], v[202:205], v[12:15]
	v_mfma_f32_16x16x32_bf16 v[8:11], v[136:139], v[202:205], v[8:11]
	v_mfma_f32_16x16x32_bf16 v[60:63], v[132:135], v[164:167], v[60:63]
	v_mfma_f32_16x16x32_bf16 v[56:59], v[140:143], v[164:167], v[56:59]
	v_mfma_f32_16x16x32_bf16 v[44:47], v[132:135], v[190:193], v[44:47]
	v_mfma_f32_16x16x32_bf16 v[40:43], v[140:143], v[190:193], v[40:43]
	v_mfma_f32_16x16x32_bf16 v[28:31], v[132:135], v[198:201], v[28:31]
	v_mfma_f32_16x16x32_bf16 v[24:27], v[140:143], v[198:201], v[24:27]
	v_mfma_f32_16x16x32_bf16 v[12:15], v[132:135], v[206:209], v[12:15]
	v_mfma_f32_16x16x32_bf16 v[8:11], v[140:143], v[206:209], v[8:11]
	v_mfma_f32_16x16x32_bf16 v[52:55], v[144:147], v[160:163], v[52:55]
	v_mfma_f32_16x16x32_bf16 v[48:51], v[152:155], v[160:163], v[48:51]
	v_mfma_f32_16x16x32_bf16 v[36:39], v[144:147], v[186:189], v[36:39]
	v_mfma_f32_16x16x32_bf16 v[32:35], v[152:155], v[186:189], v[32:35]
	v_mfma_f32_16x16x32_bf16 v[20:23], v[144:147], v[194:197], v[20:23]
	v_mfma_f32_16x16x32_bf16 v[16:19], v[152:155], v[194:197], v[16:19]
	v_mfma_f32_16x16x32_bf16 v[4:7], v[144:147], v[202:205], v[4:7]
	v_mfma_f32_16x16x32_bf16 v[0:3], v[152:155], v[202:205], v[0:3]
	v_mfma_f32_16x16x32_bf16 v[52:55], v[148:151], v[164:167], v[52:55]
	v_mfma_f32_16x16x32_bf16 v[48:51], v[156:159], v[164:167], v[48:51]
	v_mfma_f32_16x16x32_bf16 v[36:39], v[148:151], v[190:193], v[36:39]
	v_mfma_f32_16x16x32_bf16 v[32:35], v[156:159], v[190:193], v[32:35]
	s_setprio 2
	s_barrier
	v_mfma_f32_16x16x32_bf16 v[20:23], v[148:151], v[198:201], v[20:23]
	v_mfma_f32_16x16x32_bf16 v[16:19], v[156:159], v[198:201], v[16:19]
	v_mfma_f32_16x16x32_bf16 v[4:7], v[148:151], v[206:209], v[4:7]
	v_mfma_f32_16x16x32_bf16 v[0:3], v[156:159], v[206:209], v[0:3]
	s_setprio 0
	s_add_i32 s92, s92, 2
	s_add_u32 s44, s44, 0x100
	s_addc_u32 s55, s55, 0
	s_cmp_gt_u32 s92, 41
	s_mov_b64 s[8:9], s[40:41]
	s_cbranch_scc1 .Lpeel_exit_2
.LBB0_769:
	s_add_u32 s40, s8, 0x100
	s_addc_u32 s41, s9, 0
	s_add_i32 s64, 0, 0x10000
	s_cmp_eq_u32 s92, 40
	s_cselect_b32 s53, s1, s41
	s_cselect_b32 s52, s0, s40
	s_cselect_b32 s51, s39, s55
	s_cselect_b32 s50, s38, s44
	s_add_i32 s65, 0, 0x14000
	ds_read_b128 v[128:131], v226
	ds_read_b128 v[132:135], v226 offset:1024
	ds_read_b128 v[136:139], v226 offset:2048
	ds_read_b128 v[140:143], v226 offset:3072
	ds_read_b128 v[144:147], v226 offset:16384
	ds_read_b128 v[148:151], v226 offset:17408
	ds_read_b128 v[152:155], v226 offset:18432
	ds_read_b128 v[156:159], v226 offset:19456
	s_add_i32 m0, s62, 0xc000
	ds_read_b128 v[160:163], v231
	ds_read_b128 v[164:167], v231 offset:1024
	ds_read_b128 v[186:189], v231 offset:2048
	ds_read_b128 v[190:193], v231 offset:3072
	ds_read_b128 v[194:197], v231 offset:4096
	ds_read_b128 v[198:201], v231 offset:5120
	ds_read_b128 v[202:205], v231 offset:6144
	ds_read_b128 v[206:209], v231 offset:7168
	global_load_lds_dwordx4 v184, s[8:9]
	s_add_i32 m0, s62, 0xe000
	s_nop 0
	global_load_lds_dwordx4 v182, s[8:9]
	s_waitcnt vmcnt(8) lgkmcnt(0)
	s_barrier
	s_setprio 1
	v_mfma_f32_16x16x32_bf16 v[124:127], v[128:131], v[160:163], v[124:127]
	v_mfma_f32_16x16x32_bf16 v[120:123], v[136:139], v[160:163], v[120:123]
	v_mfma_f32_16x16x32_bf16 v[108:111], v[128:131], v[186:189], v[108:111]
	v_mfma_f32_16x16x32_bf16 v[104:107], v[136:139], v[186:189], v[104:107]
	v_mfma_f32_16x16x32_bf16 v[92:95], v[128:131], v[194:197], v[92:95]
	v_mfma_f32_16x16x32_bf16 v[88:91], v[136:139], v[194:197], v[88:91]
	v_mfma_f32_16x16x32_bf16 v[76:79], v[128:131], v[202:205], v[76:79]
	v_mfma_f32_16x16x32_bf16 v[72:75], v[136:139], v[202:205], v[72:75]
	v_mfma_f32_16x16x32_bf16 v[124:127], v[132:135], v[164:167], v[124:127]
	v_mfma_f32_16x16x32_bf16 v[120:123], v[140:143], v[164:167], v[120:123]
	v_mfma_f32_16x16x32_bf16 v[108:111], v[132:135], v[190:193], v[108:111]
	v_mfma_f32_16x16x32_bf16 v[104:107], v[140:143], v[190:193], v[104:107]
	v_mfma_f32_16x16x32_bf16 v[92:95], v[132:135], v[198:201], v[92:95]
	v_mfma_f32_16x16x32_bf16 v[88:91], v[140:143], v[198:201], v[88:91]
	v_mfma_f32_16x16x32_bf16 v[76:79], v[132:135], v[206:209], v[76:79]
	v_mfma_f32_16x16x32_bf16 v[72:75], v[140:143], v[206:209], v[72:75]
	v_mfma_f32_16x16x32_bf16 v[116:119], v[144:147], v[160:163], v[116:119]
	v_mfma_f32_16x16x32_bf16 v[112:115], v[152:155], v[160:163], v[112:115]
	v_mfma_f32_16x16x32_bf16 v[100:103], v[144:147], v[186:189], v[100:103]
	v_mfma_f32_16x16x32_bf16 v[96:99], v[152:155], v[186:189], v[96:99]
	v_mfma_f32_16x16x32_bf16 v[84:87], v[144:147], v[194:197], v[84:87]
	v_mfma_f32_16x16x32_bf16 v[80:83], v[152:155], v[194:197], v[80:83]
	v_mfma_f32_16x16x32_bf16 v[68:71], v[144:147], v[202:205], v[68:71]
	v_mfma_f32_16x16x32_bf16 v[64:67], v[152:155], v[202:205], v[64:67]
	v_mfma_f32_16x16x32_bf16 v[116:119], v[148:151], v[164:167], v[116:119]
	v_mfma_f32_16x16x32_bf16 v[112:115], v[156:159], v[164:167], v[112:115]
	v_mfma_f32_16x16x32_bf16 v[100:103], v[148:151], v[190:193], v[100:103]
	v_mfma_f32_16x16x32_bf16 v[96:99], v[156:159], v[190:193], v[96:99]
	s_setprio 2
	s_barrier
	v_mfma_f32_16x16x32_bf16 v[84:87], v[148:151], v[198:201], v[84:87]
	v_mfma_f32_16x16x32_bf16 v[80:83], v[156:159], v[198:201], v[80:83]
	v_mfma_f32_16x16x32_bf16 v[68:71], v[148:151], v[206:209], v[68:71]
	v_mfma_f32_16x16x32_bf16 v[64:67], v[156:159], v[206:209], v[64:67]
	s_setprio 0
	s_add_i32 s8, s64, s37
	s_add_u32 s98, s50, s34
	s_addc_u32 s99, s51, s35
	s_mov_b32 m0, s8
	ds_read_b128 v[160:163], v231 offset:16384
	ds_read_b128 v[164:167], v231 offset:17408
	ds_read_b128 v[186:189], v231 offset:18432
	ds_read_b128 v[190:193], v231 offset:19456
	ds_read_b128 v[194:197], v231 offset:20480
	ds_read_b128 v[198:201], v231 offset:21504
	ds_read_b128 v[202:205], v231 offset:22528
	ds_read_b128 v[206:209], v231 offset:23552
	global_load_lds_dwordx4 v170, s[50:51]
	s_add_i32 m0, s8, 0x2000
	s_add_u32 s8, s50, 0xb0000
	s_addc_u32 s9, s51, 0
	s_add_i32 s64, s65, s37
	global_load_lds_dwordx4 v174, s[50:51]
	s_mov_b32 m0, s64
	s_nop 0
	global_load_lds_dwordx4 v170, s[8:9]
	s_add_i32 m0, s64, 0x2000
	s_nop 0
	global_load_lds_dwordx4 v174, s[8:9]
	s_add_u32 s100, s52, s34
	s_addc_u32 s101, s53, s35
	s_mov_b32 m0, s62
	s_nop 0
	global_load_lds_dwordx4 v168, s[52:53]
	s_waitcnt vmcnt(7) lgkmcnt(0)
	s_barrier
	s_setprio 1
	v_mfma_f32_16x16x32_bf16 v[60:63], v[128:131], v[160:163], v[60:63]
	v_mfma_f32_16x16x32_bf16 v[56:59], v[136:139], v[160:163], v[56:59]
	v_mfma_f32_16x16x32_bf16 v[44:47], v[128:131], v[186:189], v[44:47]
	v_mfma_f32_16x16x32_bf16 v[40:43], v[136:139], v[186:189], v[40:43]
	v_mfma_f32_16x16x32_bf16 v[28:31], v[128:131], v[194:197], v[28:31]
	v_mfma_f32_16x16x32_bf16 v[24:27], v[136:139], v[194:197], v[24:27]
	v_mfma_f32_16x16x32_bf16 v[12:15], v[128:131], v[202:205], v[12:15]
	v_mfma_f32_16x16x32_bf16 v[8:11], v[136:139], v[202:205], v[8:11]
	v_mfma_f32_16x16x32_bf16 v[60:63], v[132:135], v[164:167], v[60:63]
	v_mfma_f32_16x16x32_bf16 v[56:59], v[140:143], v[164:167], v[56:59]
	v_mfma_f32_16x16x32_bf16 v[44:47], v[132:135], v[190:193], v[44:47]
	v_mfma_f32_16x16x32_bf16 v[40:43], v[140:143], v[190:193], v[40:43]
	v_mfma_f32_16x16x32_bf16 v[28:31], v[132:135], v[198:201], v[28:31]
	v_mfma_f32_16x16x32_bf16 v[24:27], v[140:143], v[198:201], v[24:27]
	v_mfma_f32_16x16x32_bf16 v[12:15], v[132:135], v[206:209], v[12:15]
	v_mfma_f32_16x16x32_bf16 v[8:11], v[140:143], v[206:209], v[8:11]
	v_mfma_f32_16x16x32_bf16 v[52:55], v[144:147], v[160:163], v[52:55]
	v_mfma_f32_16x16x32_bf16 v[48:51], v[152:155], v[160:163], v[48:51]
	v_mfma_f32_16x16x32_bf16 v[36:39], v[144:147], v[186:189], v[36:39]
	v_mfma_f32_16x16x32_bf16 v[32:35], v[152:155], v[186:189], v[32:35]
	v_mfma_f32_16x16x32_bf16 v[20:23], v[144:147], v[194:197], v[20:23]
	v_mfma_f32_16x16x32_bf16 v[16:19], v[152:155], v[194:197], v[16:19]
	v_mfma_f32_16x16x32_bf16 v[4:7], v[144:147], v[202:205], v[4:7]
	v_mfma_f32_16x16x32_bf16 v[0:3], v[152:155], v[202:205], v[0:3]
	v_mfma_f32_16x16x32_bf16 v[52:55], v[148:151], v[164:167], v[52:55]
	v_mfma_f32_16x16x32_bf16 v[48:51], v[156:159], v[164:167], v[48:51]
	v_mfma_f32_16x16x32_bf16 v[36:39], v[148:151], v[190:193], v[36:39]
	v_mfma_f32_16x16x32_bf16 v[32:35], v[156:159], v[190:193], v[32:35]
	s_setprio 2
	s_barrier
	v_mfma_f32_16x16x32_bf16 v[20:23], v[148:151], v[198:201], v[20:23]
	v_mfma_f32_16x16x32_bf16 v[16:19], v[156:159], v[198:201], v[16:19]
	v_mfma_f32_16x16x32_bf16 v[4:7], v[148:151], v[206:209], v[4:7]
	v_mfma_f32_16x16x32_bf16 v[0:3], v[156:159], v[206:209], v[0:3]
	s_setprio 0
	s_mov_b32 m0, s63
	s_nop 0
	global_load_lds_dwordx4 v172, s[52:53]
	s_add_i32 s64, 0, 0x18000
	s_add_i32 s65, 0, 0x1c000
	ds_read_b128 v[128:131], v226 offset:32768
	ds_read_b128 v[132:135], v226 offset:33792
	ds_read_b128 v[136:139], v226 offset:34816
	ds_read_b128 v[140:143], v226 offset:35840
	ds_read_b128 v[144:147], v226 offset:49152
	ds_read_b128 v[148:151], v226 offset:50176
	ds_read_b128 v[152:155], v226 offset:51200
	ds_read_b128 v[156:159], v226 offset:52224
	s_add_u32 s8, s52, 0xb0000
	s_addc_u32 s9, s53, 0
	s_mov_b32 m0, s68
	ds_read_b128 v[160:163], v231 offset:32768
	ds_read_b128 v[164:167], v231 offset:33792
	ds_read_b128 v[186:189], v231 offset:34816
	ds_read_b128 v[190:193], v231 offset:35840
	ds_read_b128 v[194:197], v231 offset:36864
	ds_read_b128 v[198:201], v231 offset:37888
	ds_read_b128 v[202:205], v231 offset:38912
	ds_read_b128 v[206:209], v231 offset:39936
	global_load_lds_dwordx4 v168, s[8:9]
	s_mov_b32 m0, s69
	s_nop 0
	global_load_lds_dwordx4 v172, s[8:9]
	s_waitcnt vmcnt(8) lgkmcnt(0)
	s_barrier
	s_setprio 1
	v_mfma_f32_16x16x32_bf16 v[124:127], v[128:131], v[160:163], v[124:127]
	v_mfma_f32_16x16x32_bf16 v[120:123], v[136:139], v[160:163], v[120:123]
	v_mfma_f32_16x16x32_bf16 v[108:111], v[128:131], v[186:189], v[108:111]
	v_mfma_f32_16x16x32_bf16 v[104:107], v[136:139], v[186:189], v[104:107]
	v_mfma_f32_16x16x32_bf16 v[92:95], v[128:131], v[194:197], v[92:95]
	v_mfma_f32_16x16x32_bf16 v[88:91], v[136:139], v[194:197], v[88:91]
	v_mfma_f32_16x16x32_bf16 v[76:79], v[128:131], v[202:205], v[76:79]
	v_mfma_f32_16x16x32_bf16 v[72:75], v[136:139], v[202:205], v[72:75]
	v_mfma_f32_16x16x32_bf16 v[124:127], v[132:135], v[164:167], v[124:127]
	v_mfma_f32_16x16x32_bf16 v[120:123], v[140:143], v[164:167], v[120:123]
	v_mfma_f32_16x16x32_bf16 v[108:111], v[132:135], v[190:193], v[108:111]
	v_mfma_f32_16x16x32_bf16 v[104:107], v[140:143], v[190:193], v[104:107]
	v_mfma_f32_16x16x32_bf16 v[92:95], v[132:135], v[198:201], v[92:95]
	v_mfma_f32_16x16x32_bf16 v[88:91], v[140:143], v[198:201], v[88:91]
	v_mfma_f32_16x16x32_bf16 v[76:79], v[132:135], v[206:209], v[76:79]
	v_mfma_f32_16x16x32_bf16 v[72:75], v[140:143], v[206:209], v[72:75]
	v_mfma_f32_16x16x32_bf16 v[116:119], v[144:147], v[160:163], v[116:119]
	v_mfma_f32_16x16x32_bf16 v[112:115], v[152:155], v[160:163], v[112:115]
	v_mfma_f32_16x16x32_bf16 v[100:103], v[144:147], v[186:189], v[100:103]
	v_mfma_f32_16x16x32_bf16 v[96:99], v[152:155], v[186:189], v[96:99]
	v_mfma_f32_16x16x32_bf16 v[84:87], v[144:147], v[194:197], v[84:87]
	v_mfma_f32_16x16x32_bf16 v[80:83], v[152:155], v[194:197], v[80:83]
	v_mfma_f32_16x16x32_bf16 v[68:71], v[144:147], v[202:205], v[68:71]
	v_mfma_f32_16x16x32_bf16 v[64:67], v[152:155], v[202:205], v[64:67]
	v_mfma_f32_16x16x32_bf16 v[116:119], v[148:151], v[164:167], v[116:119]
	v_mfma_f32_16x16x32_bf16 v[112:115], v[156:159], v[164:167], v[112:115]
	v_mfma_f32_16x16x32_bf16 v[100:103], v[148:151], v[190:193], v[100:103]
	v_mfma_f32_16x16x32_bf16 v[96:99], v[156:159], v[190:193], v[96:99]
	s_setprio 2
	s_barrier
	v_mfma_f32_16x16x32_bf16 v[84:87], v[148:151], v[198:201], v[84:87]
	v_mfma_f32_16x16x32_bf16 v[80:83], v[156:159], v[198:201], v[80:83]
	v_mfma_f32_16x16x32_bf16 v[68:71], v[148:151], v[206:209], v[68:71]
	v_mfma_f32_16x16x32_bf16 v[64:67], v[156:159], v[206:209], v[64:67]
	s_setprio 0
	s_add_i32 s8, s64, s37
	s_mov_b32 m0, s8
	ds_read_b128 v[160:163], v231 offset:49152
	ds_read_b128 v[164:167], v231 offset:50176
	ds_read_b128 v[186:189], v231 offset:51200
	ds_read_b128 v[190:193], v231 offset:52224
	ds_read_b128 v[194:197], v231 offset:53248
	ds_read_b128 v[198:201], v231 offset:54272
	ds_read_b128 v[202:205], v231 offset:55296
	ds_read_b128 v[206:209], v231 offset:56320
	global_load_lds_dwordx4 v170, s[98:99]
	s_add_i32 m0, s8, 0x2000
	s_add_u32 s8, s50, 0xb0080
	s_addc_u32 s9, s51, 0
	s_add_i32 s50, s65, s37
	global_load_lds_dwordx4 v174, s[98:99]
	s_mov_b32 m0, s50
	s_nop 0
	global_load_lds_dwordx4 v170, s[8:9]
	s_add_i32 m0, s50, 0x2000
	s_nop 0
	global_load_lds_dwordx4 v174, s[8:9]
	s_mov_b32 m0, s73
	s_nop 0
	global_load_lds_dwordx4 v168, s[100:101]
	s_mov_b32 m0, s74
	s_nop 0
	global_load_lds_dwordx4 v172, s[100:101]
	s_waitcnt vmcnt(8) lgkmcnt(0)
	s_barrier
	s_setprio 1
	v_mfma_f32_16x16x32_bf16 v[60:63], v[128:131], v[160:163], v[60:63]
	v_mfma_f32_16x16x32_bf16 v[56:59], v[136:139], v[160:163], v[56:59]
	v_mfma_f32_16x16x32_bf16 v[44:47], v[128:131], v[186:189], v[44:47]
	v_mfma_f32_16x16x32_bf16 v[40:43], v[136:139], v[186:189], v[40:43]
	v_mfma_f32_16x16x32_bf16 v[28:31], v[128:131], v[194:197], v[28:31]
	v_mfma_f32_16x16x32_bf16 v[24:27], v[136:139], v[194:197], v[24:27]
	v_mfma_f32_16x16x32_bf16 v[12:15], v[128:131], v[202:205], v[12:15]
	v_mfma_f32_16x16x32_bf16 v[8:11], v[136:139], v[202:205], v[8:11]
	v_mfma_f32_16x16x32_bf16 v[60:63], v[132:135], v[164:167], v[60:63]
	v_mfma_f32_16x16x32_bf16 v[56:59], v[140:143], v[164:167], v[56:59]
	v_mfma_f32_16x16x32_bf16 v[44:47], v[132:135], v[190:193], v[44:47]
	v_mfma_f32_16x16x32_bf16 v[40:43], v[140:143], v[190:193], v[40:43]
	v_mfma_f32_16x16x32_bf16 v[28:31], v[132:135], v[198:201], v[28:31]
	v_mfma_f32_16x16x32_bf16 v[24:27], v[140:143], v[198:201], v[24:27]
	v_mfma_f32_16x16x32_bf16 v[12:15], v[132:135], v[206:209], v[12:15]
	v_mfma_f32_16x16x32_bf16 v[8:11], v[140:143], v[206:209], v[8:11]
	v_mfma_f32_16x16x32_bf16 v[52:55], v[144:147], v[160:163], v[52:55]
	v_mfma_f32_16x16x32_bf16 v[48:51], v[152:155], v[160:163], v[48:51]
	v_mfma_f32_16x16x32_bf16 v[36:39], v[144:147], v[186:189], v[36:39]
	v_mfma_f32_16x16x32_bf16 v[32:35], v[152:155], v[186:189], v[32:35]
	v_mfma_f32_16x16x32_bf16 v[20:23], v[144:147], v[194:197], v[20:23]
	v_mfma_f32_16x16x32_bf16 v[16:19], v[152:155], v[194:197], v[16:19]
	v_mfma_f32_16x16x32_bf16 v[4:7], v[144:147], v[202:205], v[4:7]
	v_mfma_f32_16x16x32_bf16 v[0:3], v[152:155], v[202:205], v[0:3]
	v_mfma_f32_16x16x32_bf16 v[52:55], v[148:151], v[164:167], v[52:55]
	v_mfma_f32_16x16x32_bf16 v[48:51], v[156:159], v[164:167], v[48:51]
	v_mfma_f32_16x16x32_bf16 v[36:39], v[148:151], v[190:193], v[36:39]
	v_mfma_f32_16x16x32_bf16 v[32:35], v[156:159], v[190:193], v[32:35]
	s_setprio 2
	s_barrier
	v_mfma_f32_16x16x32_bf16 v[20:23], v[148:151], v[198:201], v[20:23]
	v_mfma_f32_16x16x32_bf16 v[16:19], v[156:159], v[198:201], v[16:19]
	v_mfma_f32_16x16x32_bf16 v[4:7], v[148:151], v[206:209], v[4:7]
	v_mfma_f32_16x16x32_bf16 v[0:3], v[156:159], v[206:209], v[0:3]
	s_setprio 0
	s_add_i32 s92, s92, 2
	s_add_u32 s44, s44, 0x100
	s_addc_u32 s55, s55, 0
	s_cmp_gt_u32 s92, 41
	s_mov_b64 s[8:9], s[40:41]
	s_cbranch_scc0 .LBB0_769

.LBB0_862:
	s_add_i32 s27, s63, -2
	s_add_u32 vcc_lo, s40, 0x100
	s_addc_u32 vcc_hi, s41, 0
	s_mov_b32 s50, 0
	v_add_u32_e32 v226, 0x10000, v228
	s_add_i32 s64, s50, 2
	s_add_u32 s40, s8, 0x100
	s_addc_u32 s41, s9, 0
	s_add_i32 s65, 0, 0x10000
	s_cmp_eq_u32 s27, s50
	s_cselect_b32 s53, s29, s41
	s_cselect_b32 s52, s28, s40
	s_cselect_b32 s51, s39, vcc_hi
	s_cselect_b32 s50, s38, vcc_lo
	s_add_i32 s66, 0, 0x14000
	ds_read_b128 v[128:131], v226
	ds_read_b128 v[132:135], v226 offset:1024
	ds_read_b128 v[136:139], v226 offset:2048
	ds_read_b128 v[140:143], v226 offset:3072
	ds_read_b128 v[144:147], v226 offset:16384
	ds_read_b128 v[148:151], v226 offset:17408
	ds_read_b128 v[152:155], v226 offset:18432
	ds_read_b128 v[156:159], v226 offset:19456
	s_add_i32 m0, s74, 0xc000
	ds_read_b128 v[160:163], v232
	ds_read_b128 v[164:167], v232 offset:1024
	ds_read_b128 v[186:189], v232 offset:2048
	ds_read_b128 v[190:193], v232 offset:3072
	ds_read_b128 v[194:197], v232 offset:4096
	ds_read_b128 v[198:201], v232 offset:5120
	ds_read_b128 v[202:205], v232 offset:6144
	ds_read_b128 v[206:209], v232 offset:7168
	global_load_lds_dwordx4 v184, s[8:9]
	s_add_i32 m0, s74, 0xe000
	s_nop 0
	global_load_lds_dwordx4 v182, s[8:9]
	s_waitcnt vmcnt(24) lgkmcnt(0)
	s_barrier
	s_setprio 1
	v_mfma_f32_16x16x32_bf16 v[124:127], v[128:131], v[160:163], 0
	v_mfma_f32_16x16x32_bf16 v[120:123], v[136:139], v[160:163], 0
	v_mfma_f32_16x16x32_bf16 v[108:111], v[128:131], v[186:189], 0
	v_mfma_f32_16x16x32_bf16 v[104:107], v[136:139], v[186:189], 0
	v_mfma_f32_16x16x32_bf16 v[92:95], v[128:131], v[194:197], 0
	v_mfma_f32_16x16x32_bf16 v[88:91], v[136:139], v[194:197], 0
	v_mfma_f32_16x16x32_bf16 v[76:79], v[128:131], v[202:205], 0
	v_mfma_f32_16x16x32_bf16 v[72:75], v[136:139], v[202:205], 0
	v_mfma_f32_16x16x32_bf16 v[124:127], v[132:135], v[164:167], v[124:127]
	v_mfma_f32_16x16x32_bf16 v[120:123], v[140:143], v[164:167], v[120:123]
	v_mfma_f32_16x16x32_bf16 v[108:111], v[132:135], v[190:193], v[108:111]
	v_mfma_f32_16x16x32_bf16 v[104:107], v[140:143], v[190:193], v[104:107]
	v_mfma_f32_16x16x32_bf16 v[92:95], v[132:135], v[198:201], v[92:95]
	v_mfma_f32_16x16x32_bf16 v[88:91], v[140:143], v[198:201], v[88:91]
	v_mfma_f32_16x16x32_bf16 v[76:79], v[132:135], v[206:209], v[76:79]
	v_mfma_f32_16x16x32_bf16 v[72:75], v[140:143], v[206:209], v[72:75]
	v_mfma_f32_16x16x32_bf16 v[116:119], v[144:147], v[160:163], 0
	v_mfma_f32_16x16x32_bf16 v[112:115], v[152:155], v[160:163], 0
	v_mfma_f32_16x16x32_bf16 v[100:103], v[144:147], v[186:189], 0
	v_mfma_f32_16x16x32_bf16 v[96:99], v[152:155], v[186:189], 0
	v_mfma_f32_16x16x32_bf16 v[84:87], v[144:147], v[194:197], 0
	v_mfma_f32_16x16x32_bf16 v[80:83], v[152:155], v[194:197], 0
	v_mfma_f32_16x16x32_bf16 v[68:71], v[144:147], v[202:205], 0
	v_mfma_f32_16x16x32_bf16 v[64:67], v[152:155], v[202:205], 0
	v_mfma_f32_16x16x32_bf16 v[116:119], v[148:151], v[164:167], v[116:119]
	v_mfma_f32_16x16x32_bf16 v[112:115], v[156:159], v[164:167], v[112:115]
	v_mfma_f32_16x16x32_bf16 v[100:103], v[148:151], v[190:193], v[100:103]
	v_mfma_f32_16x16x32_bf16 v[96:99], v[156:159], v[190:193], v[96:99]
	s_setprio 2
	s_barrier
	v_mfma_f32_16x16x32_bf16 v[84:87], v[148:151], v[198:201], v[84:87]
	v_mfma_f32_16x16x32_bf16 v[80:83], v[156:159], v[198:201], v[80:83]
	v_mfma_f32_16x16x32_bf16 v[68:71], v[148:151], v[206:209], v[68:71]
	v_mfma_f32_16x16x32_bf16 v[64:67], v[156:159], v[206:209], v[64:67]
	s_setprio 0
	s_add_i32 s8, s65, s72
	s_add_u32 s98, s50, s34
	s_addc_u32 s99, s51, s35
	s_mov_b32 m0, s8
	ds_read_b128 v[160:163], v232 offset:16384
	ds_read_b128 v[164:167], v232 offset:17408
	ds_read_b128 v[186:189], v232 offset:18432
	ds_read_b128 v[190:193], v232 offset:19456
	ds_read_b128 v[194:197], v232 offset:20480
	ds_read_b128 v[198:201], v232 offset:21504
	ds_read_b128 v[202:205], v232 offset:22528
	ds_read_b128 v[206:209], v232 offset:23552
	global_load_lds_dwordx4 v170, s[50:51]
	s_add_i32 m0, s8, 0x2000
	s_add_u32 s8, s50, 0xb0000
	s_addc_u32 s9, s51, 0
	s_add_i32 s65, s66, s72
	global_load_lds_dwordx4 v174, s[50:51]
	s_mov_b32 m0, s65
	s_nop 0
	global_load_lds_dwordx4 v170, s[8:9]
	s_add_i32 m0, s65, 0x2000
	s_nop 0
	global_load_lds_dwordx4 v174, s[8:9]
	s_add_u32 s100, s52, s34
	s_addc_u32 s101, s53, s35
	s_mov_b32 m0, s74
	s_nop 0
	global_load_lds_dwordx4 v168, s[52:53]
	s_waitcnt vmcnt(7) lgkmcnt(0)
	s_barrier
	s_setprio 1
	v_mfma_f32_16x16x32_bf16 v[60:63], v[128:131], v[160:163], 0
	v_mfma_f32_16x16x32_bf16 v[56:59], v[136:139], v[160:163], 0
	v_mfma_f32_16x16x32_bf16 v[44:47], v[128:131], v[186:189], 0
	v_mfma_f32_16x16x32_bf16 v[40:43], v[136:139], v[186:189], 0
	v_mfma_f32_16x16x32_bf16 v[28:31], v[128:131], v[194:197], 0
	v_mfma_f32_16x16x32_bf16 v[24:27], v[136:139], v[194:197], 0
	v_mfma_f32_16x16x32_bf16 v[12:15], v[128:131], v[202:205], 0
	v_mfma_f32_16x16x32_bf16 v[8:11], v[136:139], v[202:205], 0
	v_mfma_f32_16x16x32_bf16 v[60:63], v[132:135], v[164:167], v[60:63]
	v_mfma_f32_16x16x32_bf16 v[56:59], v[140:143], v[164:167], v[56:59]
	v_mfma_f32_16x16x32_bf16 v[44:47], v[132:135], v[190:193], v[44:47]
	v_mfma_f32_16x16x32_bf16 v[40:43], v[140:143], v[190:193], v[40:43]
	v_mfma_f32_16x16x32_bf16 v[28:31], v[132:135], v[198:201], v[28:31]
	v_mfma_f32_16x16x32_bf16 v[24:27], v[140:143], v[198:201], v[24:27]
	v_mfma_f32_16x16x32_bf16 v[12:15], v[132:135], v[206:209], v[12:15]
	v_mfma_f32_16x16x32_bf16 v[8:11], v[140:143], v[206:209], v[8:11]
	v_mfma_f32_16x16x32_bf16 v[52:55], v[144:147], v[160:163], 0
	v_mfma_f32_16x16x32_bf16 v[48:51], v[152:155], v[160:163], 0
	v_mfma_f32_16x16x32_bf16 v[36:39], v[144:147], v[186:189], 0
	v_mfma_f32_16x16x32_bf16 v[32:35], v[152:155], v[186:189], 0
	v_mfma_f32_16x16x32_bf16 v[20:23], v[144:147], v[194:197], 0
	v_mfma_f32_16x16x32_bf16 v[16:19], v[152:155], v[194:197], 0
	v_mfma_f32_16x16x32_bf16 v[4:7], v[144:147], v[202:205], 0
	v_mfma_f32_16x16x32_bf16 v[0:3], v[152:155], v[202:205], 0
	v_mfma_f32_16x16x32_bf16 v[52:55], v[148:151], v[164:167], v[52:55]
	v_mfma_f32_16x16x32_bf16 v[48:51], v[156:159], v[164:167], v[48:51]
	v_mfma_f32_16x16x32_bf16 v[36:39], v[148:151], v[190:193], v[36:39]
	v_mfma_f32_16x16x32_bf16 v[32:35], v[156:159], v[190:193], v[32:35]
	s_setprio 2
	s_barrier
	v_mfma_f32_16x16x32_bf16 v[20:23], v[148:151], v[198:201], v[20:23]
	v_mfma_f32_16x16x32_bf16 v[16:19], v[156:159], v[198:201], v[16:19]
	v_mfma_f32_16x16x32_bf16 v[4:7], v[148:151], v[206:209], v[4:7]
	v_mfma_f32_16x16x32_bf16 v[0:3], v[156:159], v[206:209], v[0:3]
	s_setprio 0
	s_mov_b32 m0, s75
	s_nop 0
	global_load_lds_dwordx4 v172, s[52:53]
	s_add_i32 s65, 0, 0x18000
	s_add_i32 s66, 0, 0x1c000
	ds_read_b128 v[128:131], v226 offset:32768
	ds_read_b128 v[132:135], v226 offset:33792
	ds_read_b128 v[136:139], v226 offset:34816
	ds_read_b128 v[140:143], v226 offset:35840
	ds_read_b128 v[144:147], v226 offset:49152
	ds_read_b128 v[148:151], v226 offset:50176
	ds_read_b128 v[152:155], v226 offset:51200
	ds_read_b128 v[156:159], v226 offset:52224
	s_add_u32 s8, s52, 0xb0000
	s_addc_u32 s9, s53, 0
	s_mov_b32 m0, s80
	ds_read_b128 v[160:163], v232 offset:32768
	ds_read_b128 v[164:167], v232 offset:33792
	ds_read_b128 v[186:189], v232 offset:34816
	ds_read_b128 v[190:193], v232 offset:35840
	ds_read_b128 v[194:197], v232 offset:36864
	ds_read_b128 v[198:201], v232 offset:37888
	ds_read_b128 v[202:205], v232 offset:38912
	ds_read_b128 v[206:209], v232 offset:39936
	global_load_lds_dwordx4 v168, s[8:9]
	s_mov_b32 m0, s81
	s_nop 0
	global_load_lds_dwordx4 v172, s[8:9]
	s_waitcnt vmcnt(8) lgkmcnt(0)
	s_barrier
	s_setprio 1
	v_mfma_f32_16x16x32_bf16 v[124:127], v[128:131], v[160:163], v[124:127]
	v_mfma_f32_16x16x32_bf16 v[120:123], v[136:139], v[160:163], v[120:123]
	v_mfma_f32_16x16x32_bf16 v[108:111], v[128:131], v[186:189], v[108:111]
	v_mfma_f32_16x16x32_bf16 v[104:107], v[136:139], v[186:189], v[104:107]
	v_mfma_f32_16x16x32_bf16 v[92:95], v[128:131], v[194:197], v[92:95]
	v_mfma_f32_16x16x32_bf16 v[88:91], v[136:139], v[194:197], v[88:91]
	v_mfma_f32_16x16x32_bf16 v[76:79], v[128:131], v[202:205], v[76:79]
	v_mfma_f32_16x16x32_bf16 v[72:75], v[136:139], v[202:205], v[72:75]
	v_mfma_f32_16x16x32_bf16 v[124:127], v[132:135], v[164:167], v[124:127]
	v_mfma_f32_16x16x32_bf16 v[120:123], v[140:143], v[164:167], v[120:123]
	v_mfma_f32_16x16x32_bf16 v[108:111], v[132:135], v[190:193], v[108:111]
	v_mfma_f32_16x16x32_bf16 v[104:107], v[140:143], v[190:193], v[104:107]
	v_mfma_f32_16x16x32_bf16 v[92:95], v[132:135], v[198:201], v[92:95]
	v_mfma_f32_16x16x32_bf16 v[88:91], v[140:143], v[198:201], v[88:91]
	v_mfma_f32_16x16x32_bf16 v[76:79], v[132:135], v[206:209], v[76:79]
	v_mfma_f32_16x16x32_bf16 v[72:75], v[140:143], v[206:209], v[72:75]
	v_mfma_f32_16x16x32_bf16 v[116:119], v[144:147], v[160:163], v[116:119]
	v_mfma_f32_16x16x32_bf16 v[112:115], v[152:155], v[160:163], v[112:115]
	v_mfma_f32_16x16x32_bf16 v[100:103], v[144:147], v[186:189], v[100:103]
	v_mfma_f32_16x16x32_bf16 v[96:99], v[152:155], v[186:189], v[96:99]
	v_mfma_f32_16x16x32_bf16 v[84:87], v[144:147], v[194:197], v[84:87]
	v_mfma_f32_16x16x32_bf16 v[80:83], v[152:155], v[194:197], v[80:83]
	v_mfma_f32_16x16x32_bf16 v[68:71], v[144:147], v[202:205], v[68:71]
	v_mfma_f32_16x16x32_bf16 v[64:67], v[152:155], v[202:205], v[64:67]
	v_mfma_f32_16x16x32_bf16 v[116:119], v[148:151], v[164:167], v[116:119]
	v_mfma_f32_16x16x32_bf16 v[112:115], v[156:159], v[164:167], v[112:115]
	v_mfma_f32_16x16x32_bf16 v[100:103], v[148:151], v[190:193], v[100:103]
	v_mfma_f32_16x16x32_bf16 v[96:99], v[156:159], v[190:193], v[96:99]
	s_setprio 2
	s_barrier
	v_mfma_f32_16x16x32_bf16 v[84:87], v[148:151], v[198:201], v[84:87]
	v_mfma_f32_16x16x32_bf16 v[80:83], v[156:159], v[198:201], v[80:83]
	v_mfma_f32_16x16x32_bf16 v[68:71], v[148:151], v[206:209], v[68:71]
	v_mfma_f32_16x16x32_bf16 v[64:67], v[156:159], v[206:209], v[64:67]
	s_setprio 0
	s_add_i32 s8, s65, s72
	s_mov_b32 m0, s8
	ds_read_b128 v[160:163], v232 offset:49152
	ds_read_b128 v[164:167], v232 offset:50176
	ds_read_b128 v[186:189], v232 offset:51200
	ds_read_b128 v[190:193], v232 offset:52224
	ds_read_b128 v[194:197], v232 offset:53248
	ds_read_b128 v[198:201], v232 offset:54272
	ds_read_b128 v[202:205], v232 offset:55296
	ds_read_b128 v[206:209], v232 offset:56320
	global_load_lds_dwordx4 v170, s[98:99]
	s_add_i32 m0, s8, 0x2000
	s_add_u32 s8, s50, 0xb0080
	s_addc_u32 s9, s51, 0
	s_add_i32 s50, s66, s72
	global_load_lds_dwordx4 v174, s[98:99]
	s_mov_b32 m0, s50
	s_nop 0
	global_load_lds_dwordx4 v170, s[8:9]
	s_add_i32 m0, s50, 0x2000
	s_nop 0
	global_load_lds_dwordx4 v174, s[8:9]
	s_mov_b32 m0, s83
	s_nop 0
	global_load_lds_dwordx4 v168, s[100:101]
	s_mov_b32 m0, s91
	s_nop 0
	global_load_lds_dwordx4 v172, s[100:101]
	s_waitcnt vmcnt(8) lgkmcnt(0)
	s_barrier
	s_setprio 1
	v_mfma_f32_16x16x32_bf16 v[60:63], v[128:131], v[160:163], v[60:63]
	v_mfma_f32_16x16x32_bf16 v[56:59], v[136:139], v[160:163], v[56:59]
	v_mfma_f32_16x16x32_bf16 v[44:47], v[128:131], v[186:189], v[44:47]
	v_mfma_f32_16x16x32_bf16 v[40:43], v[136:139], v[186:189], v[40:43]
	v_mfma_f32_16x16x32_bf16 v[28:31], v[128:131], v[194:197], v[28:31]
	v_mfma_f32_16x16x32_bf16 v[24:27], v[136:139], v[194:197], v[24:27]
	v_mfma_f32_16x16x32_bf16 v[12:15], v[128:131], v[202:205], v[12:15]
	v_mfma_f32_16x16x32_bf16 v[8:11], v[136:139], v[202:205], v[8:11]
	v_mfma_f32_16x16x32_bf16 v[60:63], v[132:135], v[164:167], v[60:63]
	v_mfma_f32_16x16x32_bf16 v[56:59], v[140:143], v[164:167], v[56:59]
	v_mfma_f32_16x16x32_bf16 v[44:47], v[132:135], v[190:193], v[44:47]
	v_mfma_f32_16x16x32_bf16 v[40:43], v[140:143], v[190:193], v[40:43]
	v_mfma_f32_16x16x32_bf16 v[28:31], v[132:135], v[198:201], v[28:31]
	v_mfma_f32_16x16x32_bf16 v[24:27], v[140:143], v[198:201], v[24:27]
	v_mfma_f32_16x16x32_bf16 v[12:15], v[132:135], v[206:209], v[12:15]
	v_mfma_f32_16x16x32_bf16 v[8:11], v[140:143], v[206:209], v[8:11]
	v_mfma_f32_16x16x32_bf16 v[52:55], v[144:147], v[160:163], v[52:55]
	v_mfma_f32_16x16x32_bf16 v[48:51], v[152:155], v[160:163], v[48:51]
	v_mfma_f32_16x16x32_bf16 v[36:39], v[144:147], v[186:189], v[36:39]
	v_mfma_f32_16x16x32_bf16 v[32:35], v[152:155], v[186:189], v[32:35]
	v_mfma_f32_16x16x32_bf16 v[20:23], v[144:147], v[194:197], v[20:23]
	v_mfma_f32_16x16x32_bf16 v[16:19], v[152:155], v[194:197], v[16:19]
	v_mfma_f32_16x16x32_bf16 v[4:7], v[144:147], v[202:205], v[4:7]
	v_mfma_f32_16x16x32_bf16 v[0:3], v[152:155], v[202:205], v[0:3]
	v_mfma_f32_16x16x32_bf16 v[52:55], v[148:151], v[164:167], v[52:55]
	v_mfma_f32_16x16x32_bf16 v[48:51], v[156:159], v[164:167], v[48:51]
	v_mfma_f32_16x16x32_bf16 v[36:39], v[148:151], v[190:193], v[36:39]
	v_mfma_f32_16x16x32_bf16 v[32:35], v[156:159], v[190:193], v[32:35]
	s_setprio 2
	s_barrier
	v_mfma_f32_16x16x32_bf16 v[20:23], v[148:151], v[198:201], v[20:23]
	v_mfma_f32_16x16x32_bf16 v[16:19], v[156:159], v[198:201], v[16:19]
	v_mfma_f32_16x16x32_bf16 v[4:7], v[148:151], v[206:209], v[4:7]
	v_mfma_f32_16x16x32_bf16 v[0:3], v[156:159], v[206:209], v[0:3]
	s_setprio 0
	s_add_u32 vcc_lo, vcc_lo, 0x100
	s_addc_u32 vcc_hi, vcc_hi, 0
	s_cmp_ge_i32 s64, s63
	s_mov_b64 s[8:9], s[40:41]
	s_mov_b32 s50, s64
	s_cbranch_scc1 .Lpeel_exit_3
.LBB0_863:
	s_add_i32 s64, s50, 2
	s_add_u32 s40, s8, 0x100
	s_addc_u32 s41, s9, 0
	s_add_i32 s65, 0, 0x10000
	s_cmp_eq_u32 s27, s50
	s_cselect_b32 s53, s29, s41
	s_cselect_b32 s52, s28, s40
	s_cselect_b32 s51, s39, vcc_hi
	s_cselect_b32 s50, s38, vcc_lo
	s_add_i32 s66, 0, 0x14000
	ds_read_b128 v[128:131], v226
	ds_read_b128 v[132:135], v226 offset:1024
	ds_read_b128 v[136:139], v226 offset:2048
	ds_read_b128 v[140:143], v226 offset:3072
	ds_read_b128 v[144:147], v226 offset:16384
	ds_read_b128 v[148:151], v226 offset:17408
	ds_read_b128 v[152:155], v226 offset:18432
	ds_read_b128 v[156:159], v226 offset:19456
	s_add_i32 m0, s74, 0xc000
	ds_read_b128 v[160:163], v232
	ds_read_b128 v[164:167], v232 offset:1024
	ds_read_b128 v[186:189], v232 offset:2048
	ds_read_b128 v[190:193], v232 offset:3072
	ds_read_b128 v[194:197], v232 offset:4096
	ds_read_b128 v[198:201], v232 offset:5120
	ds_read_b128 v[202:205], v232 offset:6144
	ds_read_b128 v[206:209], v232 offset:7168
	global_load_lds_dwordx4 v184, s[8:9]
	s_add_i32 m0, s74, 0xe000
	s_nop 0
	global_load_lds_dwordx4 v182, s[8:9]
	s_waitcnt vmcnt(8) lgkmcnt(0)
	s_barrier
	s_setprio 1
	v_mfma_f32_16x16x32_bf16 v[124:127], v[128:131], v[160:163], v[124:127]
	v_mfma_f32_16x16x32_bf16 v[120:123], v[136:139], v[160:163], v[120:123]
	v_mfma_f32_16x16x32_bf16 v[108:111], v[128:131], v[186:189], v[108:111]
	v_mfma_f32_16x16x32_bf16 v[104:107], v[136:139], v[186:189], v[104:107]
	v_mfma_f32_16x16x32_bf16 v[92:95], v[128:131], v[194:197], v[92:95]
	v_mfma_f32_16x16x32_bf16 v[88:91], v[136:139], v[194:197], v[88:91]
	v_mfma_f32_16x16x32_bf16 v[76:79], v[128:131], v[202:205], v[76:79]
	v_mfma_f32_16x16x32_bf16 v[72:75], v[136:139], v[202:205], v[72:75]
	v_mfma_f32_16x16x32_bf16 v[124:127], v[132:135], v[164:167], v[124:127]
	v_mfma_f32_16x16x32_bf16 v[120:123], v[140:143], v[164:167], v[120:123]
	v_mfma_f32_16x16x32_bf16 v[108:111], v[132:135], v[190:193], v[108:111]
	v_mfma_f32_16x16x32_bf16 v[104:107], v[140:143], v[190:193], v[104:107]
	v_mfma_f32_16x16x32_bf16 v[92:95], v[132:135], v[198:201], v[92:95]
	v_mfma_f32_16x16x32_bf16 v[88:91], v[140:143], v[198:201], v[88:91]
	v_mfma_f32_16x16x32_bf16 v[76:79], v[132:135], v[206:209], v[76:79]
	v_mfma_f32_16x16x32_bf16 v[72:75], v[140:143], v[206:209], v[72:75]
	v_mfma_f32_16x16x32_bf16 v[116:119], v[144:147], v[160:163], v[116:119]
	v_mfma_f32_16x16x32_bf16 v[112:115], v[152:155], v[160:163], v[112:115]
	v_mfma_f32_16x16x32_bf16 v[100:103], v[144:147], v[186:189], v[100:103]
	v_mfma_f32_16x16x32_bf16 v[96:99], v[152:155], v[186:189], v[96:99]
	v_mfma_f32_16x16x32_bf16 v[84:87], v[144:147], v[194:197], v[84:87]
	v_mfma_f32_16x16x32_bf16 v[80:83], v[152:155], v[194:197], v[80:83]
	v_mfma_f32_16x16x32_bf16 v[68:71], v[144:147], v[202:205], v[68:71]
	v_mfma_f32_16x16x32_bf16 v[64:67], v[152:155], v[202:205], v[64:67]
	v_mfma_f32_16x16x32_bf16 v[116:119], v[148:151], v[164:167], v[116:119]
	v_mfma_f32_16x16x32_bf16 v[112:115], v[156:159], v[164:167], v[112:115]
	v_mfma_f32_16x16x32_bf16 v[100:103], v[148:151], v[190:193], v[100:103]
	v_mfma_f32_16x16x32_bf16 v[96:99], v[156:159], v[190:193], v[96:99]
	s_setprio 2
	s_barrier
	v_mfma_f32_16x16x32_bf16 v[84:87], v[148:151], v[198:201], v[84:87]
	v_mfma_f32_16x16x32_bf16 v[80:83], v[156:159], v[198:201], v[80:83]
	v_mfma_f32_16x16x32_bf16 v[68:71], v[148:151], v[206:209], v[68:71]
	v_mfma_f32_16x16x32_bf16 v[64:67], v[156:159], v[206:209], v[64:67]
	s_setprio 0
	s_add_i32 s8, s65, s72
	s_add_u32 s98, s50, s34
	s_addc_u32 s99, s51, s35
	s_mov_b32 m0, s8
	ds_read_b128 v[160:163], v232 offset:16384
	ds_read_b128 v[164:167], v232 offset:17408
	ds_read_b128 v[186:189], v232 offset:18432
	ds_read_b128 v[190:193], v232 offset:19456
	ds_read_b128 v[194:197], v232 offset:20480
	ds_read_b128 v[198:201], v232 offset:21504
	ds_read_b128 v[202:205], v232 offset:22528
	ds_read_b128 v[206:209], v232 offset:23552
	global_load_lds_dwordx4 v170, s[50:51]
	s_add_i32 m0, s8, 0x2000
	s_add_u32 s8, s50, 0xb0000
	s_addc_u32 s9, s51, 0
	s_add_i32 s65, s66, s72
	global_load_lds_dwordx4 v174, s[50:51]
	s_mov_b32 m0, s65
	s_nop 0
	global_load_lds_dwordx4 v170, s[8:9]
	s_add_i32 m0, s65, 0x2000
	s_nop 0
	global_load_lds_dwordx4 v174, s[8:9]
	s_add_u32 s100, s52, s34
	s_addc_u32 s101, s53, s35
	s_mov_b32 m0, s74
	s_nop 0
	global_load_lds_dwordx4 v168, s[52:53]
	s_waitcnt vmcnt(7) lgkmcnt(0)
	s_barrier
	s_setprio 1
	v_mfma_f32_16x16x32_bf16 v[60:63], v[128:131], v[160:163], v[60:63]
	v_mfma_f32_16x16x32_bf16 v[56:59], v[136:139], v[160:163], v[56:59]
	v_mfma_f32_16x16x32_bf16 v[44:47], v[128:131], v[186:189], v[44:47]
	v_mfma_f32_16x16x32_bf16 v[40:43], v[136:139], v[186:189], v[40:43]
	v_mfma_f32_16x16x32_bf16 v[28:31], v[128:131], v[194:197], v[28:31]
	v_mfma_f32_16x16x32_bf16 v[24:27], v[136:139], v[194:197], v[24:27]
	v_mfma_f32_16x16x32_bf16 v[12:15], v[128:131], v[202:205], v[12:15]
	v_mfma_f32_16x16x32_bf16 v[8:11], v[136:139], v[202:205], v[8:11]
	v_mfma_f32_16x16x32_bf16 v[60:63], v[132:135], v[164:167], v[60:63]
	v_mfma_f32_16x16x32_bf16 v[56:59], v[140:143], v[164:167], v[56:59]
	v_mfma_f32_16x16x32_bf16 v[44:47], v[132:135], v[190:193], v[44:47]
	v_mfma_f32_16x16x32_bf16 v[40:43], v[140:143], v[190:193], v[40:43]
	v_mfma_f32_16x16x32_bf16 v[28:31], v[132:135], v[198:201], v[28:31]
	v_mfma_f32_16x16x32_bf16 v[24:27], v[140:143], v[198:201], v[24:27]
	v_mfma_f32_16x16x32_bf16 v[12:15], v[132:135], v[206:209], v[12:15]
	v_mfma_f32_16x16x32_bf16 v[8:11], v[140:143], v[206:209], v[8:11]
	v_mfma_f32_16x16x32_bf16 v[52:55], v[144:147], v[160:163], v[52:55]
	v_mfma_f32_16x16x32_bf16 v[48:51], v[152:155], v[160:163], v[48:51]
	v_mfma_f32_16x16x32_bf16 v[36:39], v[144:147], v[186:189], v[36:39]
	v_mfma_f32_16x16x32_bf16 v[32:35], v[152:155], v[186:189], v[32:35]
	v_mfma_f32_16x16x32_bf16 v[20:23], v[144:147], v[194:197], v[20:23]
	v_mfma_f32_16x16x32_bf16 v[16:19], v[152:155], v[194:197], v[16:19]
	v_mfma_f32_16x16x32_bf16 v[4:7], v[144:147], v[202:205], v[4:7]
	v_mfma_f32_16x16x32_bf16 v[0:3], v[152:155], v[202:205], v[0:3]
	v_mfma_f32_16x16x32_bf16 v[52:55], v[148:151], v[164:167], v[52:55]
	v_mfma_f32_16x16x32_bf16 v[48:51], v[156:159], v[164:167], v[48:51]
	v_mfma_f32_16x16x32_bf16 v[36:39], v[148:151], v[190:193], v[36:39]
	v_mfma_f32_16x16x32_bf16 v[32:35], v[156:159], v[190:193], v[32:35]
	s_setprio 2
	s_barrier
	v_mfma_f32_16x16x32_bf16 v[20:23], v[148:151], v[198:201], v[20:23]
	v_mfma_f32_16x16x32_bf16 v[16:19], v[156:159], v[198:201], v[16:19]
	v_mfma_f32_16x16x32_bf16 v[4:7], v[148:151], v[206:209], v[4:7]
	v_mfma_f32_16x16x32_bf16 v[0:3], v[156:159], v[206:209], v[0:3]
	s_setprio 0
	s_mov_b32 m0, s75
	s_nop 0
	global_load_lds_dwordx4 v172, s[52:53]
	s_add_i32 s65, 0, 0x18000
	s_add_i32 s66, 0, 0x1c000
	ds_read_b128 v[128:131], v226 offset:32768
	ds_read_b128 v[132:135], v226 offset:33792
	ds_read_b128 v[136:139], v226 offset:34816
	ds_read_b128 v[140:143], v226 offset:35840
	ds_read_b128 v[144:147], v226 offset:49152
	ds_read_b128 v[148:151], v226 offset:50176
	ds_read_b128 v[152:155], v226 offset:51200
	ds_read_b128 v[156:159], v226 offset:52224
	s_add_u32 s8, s52, 0xb0000
	s_addc_u32 s9, s53, 0
	s_mov_b32 m0, s80
	ds_read_b128 v[160:163], v232 offset:32768
	ds_read_b128 v[164:167], v232 offset:33792
	ds_read_b128 v[186:189], v232 offset:34816
	ds_read_b128 v[190:193], v232 offset:35840
	ds_read_b128 v[194:197], v232 offset:36864
	ds_read_b128 v[198:201], v232 offset:37888
	ds_read_b128 v[202:205], v232 offset:38912
	ds_read_b128 v[206:209], v232 offset:39936
	global_load_lds_dwordx4 v168, s[8:9]
	s_mov_b32 m0, s81
	s_nop 0
	global_load_lds_dwordx4 v172, s[8:9]
	s_waitcnt vmcnt(8) lgkmcnt(0)
	s_barrier
	s_setprio 1
	v_mfma_f32_16x16x32_bf16 v[124:127], v[128:131], v[160:163], v[124:127]
	v_mfma_f32_16x16x32_bf16 v[120:123], v[136:139], v[160:163], v[120:123]
	v_mfma_f32_16x16x32_bf16 v[108:111], v[128:131], v[186:189], v[108:111]
	v_mfma_f32_16x16x32_bf16 v[104:107], v[136:139], v[186:189], v[104:107]
	v_mfma_f32_16x16x32_bf16 v[92:95], v[128:131], v[194:197], v[92:95]
	v_mfma_f32_16x16x32_bf16 v[88:91], v[136:139], v[194:197], v[88:91]
	v_mfma_f32_16x16x32_bf16 v[76:79], v[128:131], v[202:205], v[76:79]
	v_mfma_f32_16x16x32_bf16 v[72:75], v[136:139], v[202:205], v[72:75]
	v_mfma_f32_16x16x32_bf16 v[124:127], v[132:135], v[164:167], v[124:127]
	v_mfma_f32_16x16x32_bf16 v[120:123], v[140:143], v[164:167], v[120:123]
	v_mfma_f32_16x16x32_bf16 v[108:111], v[132:135], v[190:193], v[108:111]
	v_mfma_f32_16x16x32_bf16 v[104:107], v[140:143], v[190:193], v[104:107]
	v_mfma_f32_16x16x32_bf16 v[92:95], v[132:135], v[198:201], v[92:95]
	v_mfma_f32_16x16x32_bf16 v[88:91], v[140:143], v[198:201], v[88:91]
	v_mfma_f32_16x16x32_bf16 v[76:79], v[132:135], v[206:209], v[76:79]
	v_mfma_f32_16x16x32_bf16 v[72:75], v[140:143], v[206:209], v[72:75]
	v_mfma_f32_16x16x32_bf16 v[116:119], v[144:147], v[160:163], v[116:119]
	v_mfma_f32_16x16x32_bf16 v[112:115], v[152:155], v[160:163], v[112:115]
	v_mfma_f32_16x16x32_bf16 v[100:103], v[144:147], v[186:189], v[100:103]
	v_mfma_f32_16x16x32_bf16 v[96:99], v[152:155], v[186:189], v[96:99]
	v_mfma_f32_16x16x32_bf16 v[84:87], v[144:147], v[194:197], v[84:87]
	v_mfma_f32_16x16x32_bf16 v[80:83], v[152:155], v[194:197], v[80:83]
	v_mfma_f32_16x16x32_bf16 v[68:71], v[144:147], v[202:205], v[68:71]
	v_mfma_f32_16x16x32_bf16 v[64:67], v[152:155], v[202:205], v[64:67]
	v_mfma_f32_16x16x32_bf16 v[116:119], v[148:151], v[164:167], v[116:119]
	v_mfma_f32_16x16x32_bf16 v[112:115], v[156:159], v[164:167], v[112:115]
	v_mfma_f32_16x16x32_bf16 v[100:103], v[148:151], v[190:193], v[100:103]
	v_mfma_f32_16x16x32_bf16 v[96:99], v[156:159], v[190:193], v[96:99]
	s_setprio 2
	s_barrier
	v_mfma_f32_16x16x32_bf16 v[84:87], v[148:151], v[198:201], v[84:87]
	v_mfma_f32_16x16x32_bf16 v[80:83], v[156:159], v[198:201], v[80:83]
	v_mfma_f32_16x16x32_bf16 v[68:71], v[148:151], v[206:209], v[68:71]
	v_mfma_f32_16x16x32_bf16 v[64:67], v[156:159], v[206:209], v[64:67]
	s_setprio 0
	s_add_i32 s8, s65, s72
	s_mov_b32 m0, s8
	ds_read_b128 v[160:163], v232 offset:49152
	ds_read_b128 v[164:167], v232 offset:50176
	ds_read_b128 v[186:189], v232 offset:51200
	ds_read_b128 v[190:193], v232 offset:52224
	ds_read_b128 v[194:197], v232 offset:53248
	ds_read_b128 v[198:201], v232 offset:54272
	ds_read_b128 v[202:205], v232 offset:55296
	ds_read_b128 v[206:209], v232 offset:56320
	global_load_lds_dwordx4 v170, s[98:99]
	s_add_i32 m0, s8, 0x2000
	s_add_u32 s8, s50, 0xb0080
	s_addc_u32 s9, s51, 0
	s_add_i32 s50, s66, s72
	global_load_lds_dwordx4 v174, s[98:99]
	s_mov_b32 m0, s50
	s_nop 0
	global_load_lds_dwordx4 v170, s[8:9]
	s_add_i32 m0, s50, 0x2000
	s_nop 0
	global_load_lds_dwordx4 v174, s[8:9]
	s_mov_b32 m0, s83
	s_nop 0
	global_load_lds_dwordx4 v168, s[100:101]
	s_mov_b32 m0, s91
	s_nop 0
	global_load_lds_dwordx4 v172, s[100:101]
	s_waitcnt vmcnt(8) lgkmcnt(0)
	s_barrier
	s_setprio 1
	v_mfma_f32_16x16x32_bf16 v[60:63], v[128:131], v[160:163], v[60:63]
	v_mfma_f32_16x16x32_bf16 v[56:59], v[136:139], v[160:163], v[56:59]
	v_mfma_f32_16x16x32_bf16 v[44:47], v[128:131], v[186:189], v[44:47]
	v_mfma_f32_16x16x32_bf16 v[40:43], v[136:139], v[186:189], v[40:43]
	v_mfma_f32_16x16x32_bf16 v[28:31], v[128:131], v[194:197], v[28:31]
	v_mfma_f32_16x16x32_bf16 v[24:27], v[136:139], v[194:197], v[24:27]
	v_mfma_f32_16x16x32_bf16 v[12:15], v[128:131], v[202:205], v[12:15]
	v_mfma_f32_16x16x32_bf16 v[8:11], v[136:139], v[202:205], v[8:11]
	v_mfma_f32_16x16x32_bf16 v[60:63], v[132:135], v[164:167], v[60:63]
	v_mfma_f32_16x16x32_bf16 v[56:59], v[140:143], v[164:167], v[56:59]
	v_mfma_f32_16x16x32_bf16 v[44:47], v[132:135], v[190:193], v[44:47]
	v_mfma_f32_16x16x32_bf16 v[40:43], v[140:143], v[190:193], v[40:43]
	v_mfma_f32_16x16x32_bf16 v[28:31], v[132:135], v[198:201], v[28:31]
	v_mfma_f32_16x16x32_bf16 v[24:27], v[140:143], v[198:201], v[24:27]
	v_mfma_f32_16x16x32_bf16 v[12:15], v[132:135], v[206:209], v[12:15]
	v_mfma_f32_16x16x32_bf16 v[8:11], v[140:143], v[206:209], v[8:11]
	v_mfma_f32_16x16x32_bf16 v[52:55], v[144:147], v[160:163], v[52:55]
	v_mfma_f32_16x16x32_bf16 v[48:51], v[152:155], v[160:163], v[48:51]
	v_mfma_f32_16x16x32_bf16 v[36:39], v[144:147], v[186:189], v[36:39]
	v_mfma_f32_16x16x32_bf16 v[32:35], v[152:155], v[186:189], v[32:35]
	v_mfma_f32_16x16x32_bf16 v[20:23], v[144:147], v[194:197], v[20:23]
	v_mfma_f32_16x16x32_bf16 v[16:19], v[152:155], v[194:197], v[16:19]
	v_mfma_f32_16x16x32_bf16 v[4:7], v[144:147], v[202:205], v[4:7]
	v_mfma_f32_16x16x32_bf16 v[0:3], v[152:155], v[202:205], v[0:3]
	v_mfma_f32_16x16x32_bf16 v[52:55], v[148:151], v[164:167], v[52:55]
	v_mfma_f32_16x16x32_bf16 v[48:51], v[156:159], v[164:167], v[48:51]
	v_mfma_f32_16x16x32_bf16 v[36:39], v[148:151], v[190:193], v[36:39]
	v_mfma_f32_16x16x32_bf16 v[32:35], v[156:159], v[190:193], v[32:35]
	s_setprio 2
	s_barrier
	v_mfma_f32_16x16x32_bf16 v[20:23], v[148:151], v[198:201], v[20:23]
	v_mfma_f32_16x16x32_bf16 v[16:19], v[156:159], v[198:201], v[16:19]
	v_mfma_f32_16x16x32_bf16 v[4:7], v[148:151], v[206:209], v[4:7]
	v_mfma_f32_16x16x32_bf16 v[0:3], v[156:159], v[206:209], v[0:3]
	s_setprio 0
	s_add_u32 vcc_lo, vcc_lo, 0x100
	s_addc_u32 vcc_hi, vcc_hi, 0
	s_cmp_ge_i32 s64, s63
	s_mov_b64 s[8:9], s[40:41]
	s_mov_b32 s50, s64
	s_cbranch_scc0 .LBB0_863

.LBB0_952:
	s_add_u32 s44, s38, 0x180
	s_addc_u32 s53, s39, 0
	s_mov_b32 s83, -2
	v_add_u32_e32 v226, 0x10000, v228
	s_add_u32 s38, s8, 0x180
	s_addc_u32 s39, s9, 0
	s_add_i32 s64, 0, 0x10000
	s_cmp_eq_u32 s83, 12
	s_cselect_b32 s51, s1, s39
	s_cselect_b32 s50, s0, s38
	s_cselect_b32 s41, s29, s53
	s_cselect_b32 s40, s28, s44
	s_add_i32 s65, 0, 0x14000
	ds_read_b128 v[56:59], v226
	ds_read_b128 v[60:63], v226 offset:1024
	ds_read_b128 v[64:67], v226 offset:2048
	ds_read_b128 v[68:71], v226 offset:3072
	ds_read_b128 v[144:147], v226 offset:16384
	ds_read_b128 v[148:151], v226 offset:17408
	ds_read_b128 v[152:155], v226 offset:18432
	ds_read_b128 v[156:159], v226 offset:19456
	s_add_i32 m0, s60, 0xc000
	ds_read_b128 v[160:163], v231
	ds_read_b128 v[164:167], v231 offset:1024
	ds_read_b128 v[168:171], v231 offset:2048
	ds_read_b128 v[172:175], v231 offset:3072
	ds_read_b128 v[194:197], v231 offset:4096
	ds_read_b128 v[198:201], v231 offset:5120
	ds_read_b128 v[202:205], v231 offset:6144
	ds_read_b128 v[206:209], v231 offset:7168
	global_load_lds_dwordx4 v192, s[8:9]
	s_add_i32 m0, s60, 0xe000
	s_nop 0
	global_load_lds_dwordx4 v190, s[8:9]
	s_waitcnt vmcnt(24) lgkmcnt(0)
	s_barrier
	s_setprio 1
	v_mfma_f32_16x16x32_bf16 v[140:143], v[56:59], v[160:163], 0
	v_mfma_f32_16x16x32_bf16 v[136:139], v[64:67], v[160:163], 0
	v_mfma_f32_16x16x32_bf16 v[128:131], v[56:59], v[168:171], 0
	v_mfma_f32_16x16x32_bf16 v[120:123], v[64:67], v[168:171], 0
	v_mfma_f32_16x16x32_bf16 v[108:111], v[56:59], v[194:197], 0
	v_mfma_f32_16x16x32_bf16 v[104:107], v[64:67], v[194:197], 0
	v_mfma_f32_16x16x32_bf16 v[92:95], v[56:59], v[202:205], 0
	v_mfma_f32_16x16x32_bf16 v[88:91], v[64:67], v[202:205], 0
	v_mfma_f32_16x16x32_bf16 v[140:143], v[60:63], v[164:167], v[140:143]
	v_mfma_f32_16x16x32_bf16 v[136:139], v[68:71], v[164:167], v[136:139]
	v_mfma_f32_16x16x32_bf16 v[128:131], v[60:63], v[172:175], v[128:131]
	v_mfma_f32_16x16x32_bf16 v[120:123], v[68:71], v[172:175], v[120:123]
	v_mfma_f32_16x16x32_bf16 v[108:111], v[60:63], v[198:201], v[108:111]
	v_mfma_f32_16x16x32_bf16 v[104:107], v[68:71], v[198:201], v[104:107]
	v_mfma_f32_16x16x32_bf16 v[92:95], v[60:63], v[206:209], v[92:95]
	v_mfma_f32_16x16x32_bf16 v[88:91], v[68:71], v[206:209], v[88:91]
	v_mfma_f32_16x16x32_bf16 v[132:135], v[144:147], v[160:163], 0
	v_mfma_f32_16x16x32_bf16 v[124:127], v[152:155], v[160:163], 0
	v_mfma_f32_16x16x32_bf16 v[116:119], v[144:147], v[168:171], 0
	v_mfma_f32_16x16x32_bf16 v[112:115], v[152:155], v[168:171], 0
	v_mfma_f32_16x16x32_bf16 v[100:103], v[144:147], v[194:197], 0
	v_mfma_f32_16x16x32_bf16 v[96:99], v[152:155], v[194:197], 0
	v_mfma_f32_16x16x32_bf16 v[84:87], v[144:147], v[202:205], 0
	v_mfma_f32_16x16x32_bf16 v[80:83], v[152:155], v[202:205], 0
	v_mfma_f32_16x16x32_bf16 v[132:135], v[148:151], v[164:167], v[132:135]
	v_mfma_f32_16x16x32_bf16 v[124:127], v[156:159], v[164:167], v[124:127]
	v_mfma_f32_16x16x32_bf16 v[116:119], v[148:151], v[172:175], v[116:119]
	v_mfma_f32_16x16x32_bf16 v[112:115], v[156:159], v[172:175], v[112:115]
	s_setprio 2
	s_barrier
	v_mfma_f32_16x16x32_bf16 v[100:103], v[148:151], v[198:201], v[100:103]
	v_mfma_f32_16x16x32_bf16 v[96:99], v[156:159], v[198:201], v[96:99]
	v_mfma_f32_16x16x32_bf16 v[84:87], v[148:151], v[206:209], v[84:87]
	v_mfma_f32_16x16x32_bf16 v[80:83], v[156:159], v[206:209], v[80:83]
	s_setprio 0
	s_add_i32 s8, s64, s37
	s_add_u32 s98, s40, s34
	s_addc_u32 s99, s41, s35
	s_mov_b32 m0, s8
	ds_read_b128 v[160:163], v231 offset:16384
	ds_read_b128 v[164:167], v231 offset:17408
	ds_read_b128 v[168:171], v231 offset:18432
	ds_read_b128 v[172:175], v231 offset:19456
	ds_read_b128 v[194:197], v231 offset:20480
	ds_read_b128 v[198:201], v231 offset:21504
	ds_read_b128 v[202:205], v231 offset:22528
	ds_read_b128 v[206:209], v231 offset:23552
	global_load_lds_dwordx4 v184, s[40:41]
	s_add_i32 m0, s8, 0x2000
	s_add_u32 s8, s40, 0x60000
	s_addc_u32 s9, s41, 0
	s_add_i32 s64, s65, s37
	global_load_lds_dwordx4 v188, s[40:41]
	s_mov_b32 m0, s64
	s_nop 0
	global_load_lds_dwordx4 v184, s[8:9]
	s_add_i32 m0, s64, 0x2000
	s_nop 0
	global_load_lds_dwordx4 v188, s[8:9]
	s_add_u32 s100, s50, s34
	s_addc_u32 s101, s51, s35
	s_mov_b32 m0, s60
	s_nop 0
	global_load_lds_dwordx4 v182, s[50:51]
	s_waitcnt vmcnt(7) lgkmcnt(0)
	s_barrier
	s_setprio 1
	v_mfma_f32_16x16x32_bf16 v[76:79], v[56:59], v[160:163], 0
	v_mfma_f32_16x16x32_bf16 v[72:75], v[64:67], v[160:163], 0
	v_mfma_f32_16x16x32_bf16 v[44:47], v[56:59], v[168:171], 0
	v_mfma_f32_16x16x32_bf16 v[40:43], v[64:67], v[168:171], 0
	v_mfma_f32_16x16x32_bf16 v[28:31], v[56:59], v[194:197], 0
	v_mfma_f32_16x16x32_bf16 v[24:27], v[64:67], v[194:197], 0
	v_mfma_f32_16x16x32_bf16 v[12:15], v[56:59], v[202:205], 0
	v_mfma_f32_16x16x32_bf16 v[8:11], v[64:67], v[202:205], 0
	v_mfma_f32_16x16x32_bf16 v[76:79], v[60:63], v[164:167], v[76:79]
	v_mfma_f32_16x16x32_bf16 v[72:75], v[68:71], v[164:167], v[72:75]
	v_mfma_f32_16x16x32_bf16 v[44:47], v[60:63], v[172:175], v[44:47]
	v_mfma_f32_16x16x32_bf16 v[40:43], v[68:71], v[172:175], v[40:43]
	v_mfma_f32_16x16x32_bf16 v[28:31], v[60:63], v[198:201], v[28:31]
	v_mfma_f32_16x16x32_bf16 v[24:27], v[68:71], v[198:201], v[24:27]
	v_mfma_f32_16x16x32_bf16 v[12:15], v[60:63], v[206:209], v[12:15]
	v_mfma_f32_16x16x32_bf16 v[8:11], v[68:71], v[206:209], v[8:11]
	v_mfma_f32_16x16x32_bf16 v[52:55], v[144:147], v[160:163], 0
	v_mfma_f32_16x16x32_bf16 v[48:51], v[152:155], v[160:163], 0
	v_mfma_f32_16x16x32_bf16 v[36:39], v[144:147], v[168:171], 0
	v_mfma_f32_16x16x32_bf16 v[32:35], v[152:155], v[168:171], 0
	v_mfma_f32_16x16x32_bf16 v[20:23], v[144:147], v[194:197], 0
	v_mfma_f32_16x16x32_bf16 v[16:19], v[152:155], v[194:197], 0
	v_mfma_f32_16x16x32_bf16 v[4:7], v[144:147], v[202:205], 0
	v_mfma_f32_16x16x32_bf16 v[0:3], v[152:155], v[202:205], 0
	v_mfma_f32_16x16x32_bf16 v[52:55], v[148:151], v[164:167], v[52:55]
	v_mfma_f32_16x16x32_bf16 v[48:51], v[156:159], v[164:167], v[48:51]
	v_mfma_f32_16x16x32_bf16 v[36:39], v[148:151], v[172:175], v[36:39]
	v_mfma_f32_16x16x32_bf16 v[32:35], v[156:159], v[172:175], v[32:35]
	s_setprio 2
	s_barrier
	v_mfma_f32_16x16x32_bf16 v[20:23], v[148:151], v[198:201], v[20:23]
	v_mfma_f32_16x16x32_bf16 v[16:19], v[156:159], v[198:201], v[16:19]
	v_mfma_f32_16x16x32_bf16 v[4:7], v[148:151], v[206:209], v[4:7]
	v_mfma_f32_16x16x32_bf16 v[0:3], v[156:159], v[206:209], v[0:3]
	s_setprio 0
	s_mov_b32 m0, s61
	s_nop 0
	global_load_lds_dwordx4 v186, s[50:51]
	s_add_i32 s64, 0, 0x18000
	s_add_i32 s65, 0, 0x1c000
	ds_read_b128 v[56:59], v226 offset:32768
	ds_read_b128 v[60:63], v226 offset:33792
	ds_read_b128 v[64:67], v226 offset:34816
	ds_read_b128 v[68:71], v226 offset:35840
	ds_read_b128 v[144:147], v226 offset:49152
	ds_read_b128 v[148:151], v226 offset:50176
	ds_read_b128 v[152:155], v226 offset:51200
	ds_read_b128 v[156:159], v226 offset:52224
	s_add_u32 s8, s50, 0x60000
	s_addc_u32 s9, s51, 0
	s_mov_b32 m0, s62
	ds_read_b128 v[160:163], v231 offset:32768
	ds_read_b128 v[164:167], v231 offset:33792
	ds_read_b128 v[168:171], v231 offset:34816
	ds_read_b128 v[172:175], v231 offset:35840
	ds_read_b128 v[194:197], v231 offset:36864
	ds_read_b128 v[198:201], v231 offset:37888
	ds_read_b128 v[202:205], v231 offset:38912
	ds_read_b128 v[206:209], v231 offset:39936
	global_load_lds_dwordx4 v182, s[8:9]
	s_mov_b32 m0, s63
	s_nop 0
	global_load_lds_dwordx4 v186, s[8:9]
	s_waitcnt vmcnt(8) lgkmcnt(0)
	s_barrier
	s_setprio 1
	v_mfma_f32_16x16x32_bf16 v[140:143], v[56:59], v[160:163], v[140:143]
	v_mfma_f32_16x16x32_bf16 v[136:139], v[64:67], v[160:163], v[136:139]
	v_mfma_f32_16x16x32_bf16 v[128:131], v[56:59], v[168:171], v[128:131]
	v_mfma_f32_16x16x32_bf16 v[120:123], v[64:67], v[168:171], v[120:123]
	v_mfma_f32_16x16x32_bf16 v[108:111], v[56:59], v[194:197], v[108:111]
	v_mfma_f32_16x16x32_bf16 v[104:107], v[64:67], v[194:197], v[104:107]
	v_mfma_f32_16x16x32_bf16 v[92:95], v[56:59], v[202:205], v[92:95]
	v_mfma_f32_16x16x32_bf16 v[88:91], v[64:67], v[202:205], v[88:91]
	v_mfma_f32_16x16x32_bf16 v[140:143], v[60:63], v[164:167], v[140:143]
	v_mfma_f32_16x16x32_bf16 v[136:139], v[68:71], v[164:167], v[136:139]
	v_mfma_f32_16x16x32_bf16 v[128:131], v[60:63], v[172:175], v[128:131]
	v_mfma_f32_16x16x32_bf16 v[120:123], v[68:71], v[172:175], v[120:123]
	v_mfma_f32_16x16x32_bf16 v[108:111], v[60:63], v[198:201], v[108:111]
	v_mfma_f32_16x16x32_bf16 v[104:107], v[68:71], v[198:201], v[104:107]
	v_mfma_f32_16x16x32_bf16 v[92:95], v[60:63], v[206:209], v[92:95]
	v_mfma_f32_16x16x32_bf16 v[88:91], v[68:71], v[206:209], v[88:91]
	v_mfma_f32_16x16x32_bf16 v[132:135], v[144:147], v[160:163], v[132:135]
	v_mfma_f32_16x16x32_bf16 v[124:127], v[152:155], v[160:163], v[124:127]
	v_mfma_f32_16x16x32_bf16 v[116:119], v[144:147], v[168:171], v[116:119]
	v_mfma_f32_16x16x32_bf16 v[112:115], v[152:155], v[168:171], v[112:115]
	v_mfma_f32_16x16x32_bf16 v[100:103], v[144:147], v[194:197], v[100:103]
	v_mfma_f32_16x16x32_bf16 v[96:99], v[152:155], v[194:197], v[96:99]
	v_mfma_f32_16x16x32_bf16 v[84:87], v[144:147], v[202:205], v[84:87]
	v_mfma_f32_16x16x32_bf16 v[80:83], v[152:155], v[202:205], v[80:83]
	v_mfma_f32_16x16x32_bf16 v[132:135], v[148:151], v[164:167], v[132:135]
	v_mfma_f32_16x16x32_bf16 v[124:127], v[156:159], v[164:167], v[124:127]
	v_mfma_f32_16x16x32_bf16 v[116:119], v[148:151], v[172:175], v[116:119]
	v_mfma_f32_16x16x32_bf16 v[112:115], v[156:159], v[172:175], v[112:115]
	s_setprio 2
	s_barrier
	v_mfma_f32_16x16x32_bf16 v[100:103], v[148:151], v[198:201], v[100:103]
	v_mfma_f32_16x16x32_bf16 v[96:99], v[156:159], v[198:201], v[96:99]
	v_mfma_f32_16x16x32_bf16 v[84:87], v[148:151], v[206:209], v[84:87]
	v_mfma_f32_16x16x32_bf16 v[80:83], v[156:159], v[206:209], v[80:83]
	s_setprio 0
	s_add_i32 s8, s64, s37
	s_mov_b32 m0, s8
	ds_read_b128 v[160:163], v231 offset:49152
	ds_read_b128 v[164:167], v231 offset:50176
	ds_read_b128 v[168:171], v231 offset:51200
	ds_read_b128 v[172:175], v231 offset:52224
	ds_read_b128 v[194:197], v231 offset:53248
	ds_read_b128 v[198:201], v231 offset:54272
	ds_read_b128 v[202:205], v231 offset:55296
	ds_read_b128 v[206:209], v231 offset:56320
	global_load_lds_dwordx4 v184, s[98:99]
	s_add_i32 m0, s8, 0x2000
	s_add_u32 s8, s40, 0x60080
	s_addc_u32 s9, s41, 0
	s_add_i32 s40, s65, s37
	global_load_lds_dwordx4 v188, s[98:99]
	s_mov_b32 m0, s40
	s_nop 0
	global_load_lds_dwordx4 v184, s[8:9]
	s_add_i32 m0, s40, 0x2000
	s_nop 0
	global_load_lds_dwordx4 v188, s[8:9]
	s_mov_b32 m0, s69
	s_nop 0
	global_load_lds_dwordx4 v182, s[100:101]
	s_mov_b32 m0, s72
	s_nop 0
	global_load_lds_dwordx4 v186, s[100:101]
	s_waitcnt vmcnt(8) lgkmcnt(0)
	s_barrier
	s_setprio 1
	v_mfma_f32_16x16x32_bf16 v[76:79], v[56:59], v[160:163], v[76:79]
	v_mfma_f32_16x16x32_bf16 v[72:75], v[64:67], v[160:163], v[72:75]
	v_mfma_f32_16x16x32_bf16 v[44:47], v[56:59], v[168:171], v[44:47]
	v_mfma_f32_16x16x32_bf16 v[40:43], v[64:67], v[168:171], v[40:43]
	v_mfma_f32_16x16x32_bf16 v[28:31], v[56:59], v[194:197], v[28:31]
	v_mfma_f32_16x16x32_bf16 v[24:27], v[64:67], v[194:197], v[24:27]
	v_mfma_f32_16x16x32_bf16 v[12:15], v[56:59], v[202:205], v[12:15]
	v_mfma_f32_16x16x32_bf16 v[8:11], v[64:67], v[202:205], v[8:11]
	v_mfma_f32_16x16x32_bf16 v[76:79], v[60:63], v[164:167], v[76:79]
	v_mfma_f32_16x16x32_bf16 v[72:75], v[68:71], v[164:167], v[72:75]
	v_mfma_f32_16x16x32_bf16 v[44:47], v[60:63], v[172:175], v[44:47]
	v_mfma_f32_16x16x32_bf16 v[40:43], v[68:71], v[172:175], v[40:43]
	v_mfma_f32_16x16x32_bf16 v[28:31], v[60:63], v[198:201], v[28:31]
	v_mfma_f32_16x16x32_bf16 v[24:27], v[68:71], v[198:201], v[24:27]
	v_mfma_f32_16x16x32_bf16 v[12:15], v[60:63], v[206:209], v[12:15]
	v_mfma_f32_16x16x32_bf16 v[8:11], v[68:71], v[206:209], v[8:11]
	v_mfma_f32_16x16x32_bf16 v[52:55], v[144:147], v[160:163], v[52:55]
	v_mfma_f32_16x16x32_bf16 v[48:51], v[152:155], v[160:163], v[48:51]
	v_mfma_f32_16x16x32_bf16 v[36:39], v[144:147], v[168:171], v[36:39]
	v_mfma_f32_16x16x32_bf16 v[32:35], v[152:155], v[168:171], v[32:35]
	v_mfma_f32_16x16x32_bf16 v[20:23], v[144:147], v[194:197], v[20:23]
	v_mfma_f32_16x16x32_bf16 v[16:19], v[152:155], v[194:197], v[16:19]
	v_mfma_f32_16x16x32_bf16 v[4:7], v[144:147], v[202:205], v[4:7]
	v_mfma_f32_16x16x32_bf16 v[0:3], v[152:155], v[202:205], v[0:3]
	v_mfma_f32_16x16x32_bf16 v[52:55], v[148:151], v[164:167], v[52:55]
	v_mfma_f32_16x16x32_bf16 v[48:51], v[156:159], v[164:167], v[48:51]
	v_mfma_f32_16x16x32_bf16 v[36:39], v[148:151], v[172:175], v[36:39]
	v_mfma_f32_16x16x32_bf16 v[32:35], v[156:159], v[172:175], v[32:35]
	s_setprio 2
	s_barrier
	v_mfma_f32_16x16x32_bf16 v[20:23], v[148:151], v[198:201], v[20:23]
	v_mfma_f32_16x16x32_bf16 v[16:19], v[156:159], v[198:201], v[16:19]
	v_mfma_f32_16x16x32_bf16 v[4:7], v[148:151], v[206:209], v[4:7]
	v_mfma_f32_16x16x32_bf16 v[0:3], v[156:159], v[206:209], v[0:3]
	s_setprio 0
	s_add_i32 s83, s83, 2
	s_add_u32 s44, s44, 0x180
	s_addc_u32 s53, s53, 0
	s_cmp_gt_u32 s83, 13
	s_mov_b64 s[8:9], s[38:39]
	s_cbranch_scc1 .Lpeel_exit_4
.LBB0_953:
	s_add_u32 s38, s8, 0x180
	s_addc_u32 s39, s9, 0
	s_add_i32 s64, 0, 0x10000
	s_cmp_eq_u32 s83, 12
	s_cselect_b32 s51, s1, s39
	s_cselect_b32 s50, s0, s38
	s_cselect_b32 s41, s29, s53
	s_cselect_b32 s40, s28, s44
	s_add_i32 s65, 0, 0x14000
	ds_read_b128 v[56:59], v226
	ds_read_b128 v[60:63], v226 offset:1024
	ds_read_b128 v[64:67], v226 offset:2048
	ds_read_b128 v[68:71], v226 offset:3072
	ds_read_b128 v[144:147], v226 offset:16384
	ds_read_b128 v[148:151], v226 offset:17408
	ds_read_b128 v[152:155], v226 offset:18432
	ds_read_b128 v[156:159], v226 offset:19456
	s_add_i32 m0, s60, 0xc000
	ds_read_b128 v[160:163], v231
	ds_read_b128 v[164:167], v231 offset:1024
	ds_read_b128 v[168:171], v231 offset:2048
	ds_read_b128 v[172:175], v231 offset:3072
	ds_read_b128 v[194:197], v231 offset:4096
	ds_read_b128 v[198:201], v231 offset:5120
	ds_read_b128 v[202:205], v231 offset:6144
	ds_read_b128 v[206:209], v231 offset:7168
	global_load_lds_dwordx4 v192, s[8:9]
	s_add_i32 m0, s60, 0xe000
	s_nop 0
	global_load_lds_dwordx4 v190, s[8:9]
	s_waitcnt vmcnt(8) lgkmcnt(0)
	s_barrier
	s_setprio 1
	v_mfma_f32_16x16x32_bf16 v[140:143], v[56:59], v[160:163], v[140:143]
	v_mfma_f32_16x16x32_bf16 v[136:139], v[64:67], v[160:163], v[136:139]
	v_mfma_f32_16x16x32_bf16 v[128:131], v[56:59], v[168:171], v[128:131]
	v_mfma_f32_16x16x32_bf16 v[120:123], v[64:67], v[168:171], v[120:123]
	v_mfma_f32_16x16x32_bf16 v[108:111], v[56:59], v[194:197], v[108:111]
	v_mfma_f32_16x16x32_bf16 v[104:107], v[64:67], v[194:197], v[104:107]
	v_mfma_f32_16x16x32_bf16 v[92:95], v[56:59], v[202:205], v[92:95]
	v_mfma_f32_16x16x32_bf16 v[88:91], v[64:67], v[202:205], v[88:91]
	v_mfma_f32_16x16x32_bf16 v[140:143], v[60:63], v[164:167], v[140:143]
	v_mfma_f32_16x16x32_bf16 v[136:139], v[68:71], v[164:167], v[136:139]
	v_mfma_f32_16x16x32_bf16 v[128:131], v[60:63], v[172:175], v[128:131]
	v_mfma_f32_16x16x32_bf16 v[120:123], v[68:71], v[172:175], v[120:123]
	v_mfma_f32_16x16x32_bf16 v[108:111], v[60:63], v[198:201], v[108:111]
	v_mfma_f32_16x16x32_bf16 v[104:107], v[68:71], v[198:201], v[104:107]
	v_mfma_f32_16x16x32_bf16 v[92:95], v[60:63], v[206:209], v[92:95]
	v_mfma_f32_16x16x32_bf16 v[88:91], v[68:71], v[206:209], v[88:91]
	v_mfma_f32_16x16x32_bf16 v[132:135], v[144:147], v[160:163], v[132:135]
	v_mfma_f32_16x16x32_bf16 v[124:127], v[152:155], v[160:163], v[124:127]
	v_mfma_f32_16x16x32_bf16 v[116:119], v[144:147], v[168:171], v[116:119]
	v_mfma_f32_16x16x32_bf16 v[112:115], v[152:155], v[168:171], v[112:115]
	v_mfma_f32_16x16x32_bf16 v[100:103], v[144:147], v[194:197], v[100:103]
	v_mfma_f32_16x16x32_bf16 v[96:99], v[152:155], v[194:197], v[96:99]
	v_mfma_f32_16x16x32_bf16 v[84:87], v[144:147], v[202:205], v[84:87]
	v_mfma_f32_16x16x32_bf16 v[80:83], v[152:155], v[202:205], v[80:83]
	v_mfma_f32_16x16x32_bf16 v[132:135], v[148:151], v[164:167], v[132:135]
	v_mfma_f32_16x16x32_bf16 v[124:127], v[156:159], v[164:167], v[124:127]
	v_mfma_f32_16x16x32_bf16 v[116:119], v[148:151], v[172:175], v[116:119]
	v_mfma_f32_16x16x32_bf16 v[112:115], v[156:159], v[172:175], v[112:115]
	s_setprio 2
	s_barrier
	v_mfma_f32_16x16x32_bf16 v[100:103], v[148:151], v[198:201], v[100:103]
	v_mfma_f32_16x16x32_bf16 v[96:99], v[156:159], v[198:201], v[96:99]
	v_mfma_f32_16x16x32_bf16 v[84:87], v[148:151], v[206:209], v[84:87]
	v_mfma_f32_16x16x32_bf16 v[80:83], v[156:159], v[206:209], v[80:83]
	s_setprio 0
	s_add_i32 s8, s64, s37
	s_add_u32 s98, s40, s34
	s_addc_u32 s99, s41, s35
	s_mov_b32 m0, s8
	ds_read_b128 v[160:163], v231 offset:16384
	ds_read_b128 v[164:167], v231 offset:17408
	ds_read_b128 v[168:171], v231 offset:18432
	ds_read_b128 v[172:175], v231 offset:19456
	ds_read_b128 v[194:197], v231 offset:20480
	ds_read_b128 v[198:201], v231 offset:21504
	ds_read_b128 v[202:205], v231 offset:22528
	ds_read_b128 v[206:209], v231 offset:23552
	global_load_lds_dwordx4 v184, s[40:41]
	s_add_i32 m0, s8, 0x2000
	s_add_u32 s8, s40, 0x60000
	s_addc_u32 s9, s41, 0
	s_add_i32 s64, s65, s37
	global_load_lds_dwordx4 v188, s[40:41]
	s_mov_b32 m0, s64
	s_nop 0
	global_load_lds_dwordx4 v184, s[8:9]
	s_add_i32 m0, s64, 0x2000
	s_nop 0
	global_load_lds_dwordx4 v188, s[8:9]
	s_add_u32 s100, s50, s34
	s_addc_u32 s101, s51, s35
	s_mov_b32 m0, s60
	s_nop 0
	global_load_lds_dwordx4 v182, s[50:51]
	s_waitcnt vmcnt(7) lgkmcnt(0)
	s_barrier
	s_setprio 1
	v_mfma_f32_16x16x32_bf16 v[76:79], v[56:59], v[160:163], v[76:79]
	v_mfma_f32_16x16x32_bf16 v[72:75], v[64:67], v[160:163], v[72:75]
	v_mfma_f32_16x16x32_bf16 v[44:47], v[56:59], v[168:171], v[44:47]
	v_mfma_f32_16x16x32_bf16 v[40:43], v[64:67], v[168:171], v[40:43]
	v_mfma_f32_16x16x32_bf16 v[28:31], v[56:59], v[194:197], v[28:31]
	v_mfma_f32_16x16x32_bf16 v[24:27], v[64:67], v[194:197], v[24:27]
	v_mfma_f32_16x16x32_bf16 v[12:15], v[56:59], v[202:205], v[12:15]
	v_mfma_f32_16x16x32_bf16 v[8:11], v[64:67], v[202:205], v[8:11]
	v_mfma_f32_16x16x32_bf16 v[76:79], v[60:63], v[164:167], v[76:79]
	v_mfma_f32_16x16x32_bf16 v[72:75], v[68:71], v[164:167], v[72:75]
	v_mfma_f32_16x16x32_bf16 v[44:47], v[60:63], v[172:175], v[44:47]
	v_mfma_f32_16x16x32_bf16 v[40:43], v[68:71], v[172:175], v[40:43]
	v_mfma_f32_16x16x32_bf16 v[28:31], v[60:63], v[198:201], v[28:31]
	v_mfma_f32_16x16x32_bf16 v[24:27], v[68:71], v[198:201], v[24:27]
	v_mfma_f32_16x16x32_bf16 v[12:15], v[60:63], v[206:209], v[12:15]
	v_mfma_f32_16x16x32_bf16 v[8:11], v[68:71], v[206:209], v[8:11]
	v_mfma_f32_16x16x32_bf16 v[52:55], v[144:147], v[160:163], v[52:55]
	v_mfma_f32_16x16x32_bf16 v[48:51], v[152:155], v[160:163], v[48:51]
	v_mfma_f32_16x16x32_bf16 v[36:39], v[144:147], v[168:171], v[36:39]
	v_mfma_f32_16x16x32_bf16 v[32:35], v[152:155], v[168:171], v[32:35]
	v_mfma_f32_16x16x32_bf16 v[20:23], v[144:147], v[194:197], v[20:23]
	v_mfma_f32_16x16x32_bf16 v[16:19], v[152:155], v[194:197], v[16:19]
	v_mfma_f32_16x16x32_bf16 v[4:7], v[144:147], v[202:205], v[4:7]
	v_mfma_f32_16x16x32_bf16 v[0:3], v[152:155], v[202:205], v[0:3]
	v_mfma_f32_16x16x32_bf16 v[52:55], v[148:151], v[164:167], v[52:55]
	v_mfma_f32_16x16x32_bf16 v[48:51], v[156:159], v[164:167], v[48:51]
	v_mfma_f32_16x16x32_bf16 v[36:39], v[148:151], v[172:175], v[36:39]
	v_mfma_f32_16x16x32_bf16 v[32:35], v[156:159], v[172:175], v[32:35]
	s_setprio 2
	s_barrier
	v_mfma_f32_16x16x32_bf16 v[20:23], v[148:151], v[198:201], v[20:23]
	v_mfma_f32_16x16x32_bf16 v[16:19], v[156:159], v[198:201], v[16:19]
	v_mfma_f32_16x16x32_bf16 v[4:7], v[148:151], v[206:209], v[4:7]
	v_mfma_f32_16x16x32_bf16 v[0:3], v[156:159], v[206:209], v[0:3]
	s_setprio 0
	s_mov_b32 m0, s61
	s_nop 0
	global_load_lds_dwordx4 v186, s[50:51]
	s_add_i32 s64, 0, 0x18000
	s_add_i32 s65, 0, 0x1c000
	ds_read_b128 v[56:59], v226 offset:32768
	ds_read_b128 v[60:63], v226 offset:33792
	ds_read_b128 v[64:67], v226 offset:34816
	ds_read_b128 v[68:71], v226 offset:35840
	ds_read_b128 v[144:147], v226 offset:49152
	ds_read_b128 v[148:151], v226 offset:50176
	ds_read_b128 v[152:155], v226 offset:51200
	ds_read_b128 v[156:159], v226 offset:52224
	s_add_u32 s8, s50, 0x60000
	s_addc_u32 s9, s51, 0
	s_mov_b32 m0, s62
	ds_read_b128 v[160:163], v231 offset:32768
	ds_read_b128 v[164:167], v231 offset:33792
	ds_read_b128 v[168:171], v231 offset:34816
	ds_read_b128 v[172:175], v231 offset:35840
	ds_read_b128 v[194:197], v231 offset:36864
	ds_read_b128 v[198:201], v231 offset:37888
	ds_read_b128 v[202:205], v231 offset:38912
	ds_read_b128 v[206:209], v231 offset:39936
	global_load_lds_dwordx4 v182, s[8:9]
	s_mov_b32 m0, s63
	s_nop 0
	global_load_lds_dwordx4 v186, s[8:9]
	s_waitcnt vmcnt(8) lgkmcnt(0)
	s_barrier
	s_setprio 1
	v_mfma_f32_16x16x32_bf16 v[140:143], v[56:59], v[160:163], v[140:143]
	v_mfma_f32_16x16x32_bf16 v[136:139], v[64:67], v[160:163], v[136:139]
	v_mfma_f32_16x16x32_bf16 v[128:131], v[56:59], v[168:171], v[128:131]
	v_mfma_f32_16x16x32_bf16 v[120:123], v[64:67], v[168:171], v[120:123]
	v_mfma_f32_16x16x32_bf16 v[108:111], v[56:59], v[194:197], v[108:111]
	v_mfma_f32_16x16x32_bf16 v[104:107], v[64:67], v[194:197], v[104:107]
	v_mfma_f32_16x16x32_bf16 v[92:95], v[56:59], v[202:205], v[92:95]
	v_mfma_f32_16x16x32_bf16 v[88:91], v[64:67], v[202:205], v[88:91]
	v_mfma_f32_16x16x32_bf16 v[140:143], v[60:63], v[164:167], v[140:143]
	v_mfma_f32_16x16x32_bf16 v[136:139], v[68:71], v[164:167], v[136:139]
	v_mfma_f32_16x16x32_bf16 v[128:131], v[60:63], v[172:175], v[128:131]
	v_mfma_f32_16x16x32_bf16 v[120:123], v[68:71], v[172:175], v[120:123]
	v_mfma_f32_16x16x32_bf16 v[108:111], v[60:63], v[198:201], v[108:111]
	v_mfma_f32_16x16x32_bf16 v[104:107], v[68:71], v[198:201], v[104:107]
	v_mfma_f32_16x16x32_bf16 v[92:95], v[60:63], v[206:209], v[92:95]
	v_mfma_f32_16x16x32_bf16 v[88:91], v[68:71], v[206:209], v[88:91]
	v_mfma_f32_16x16x32_bf16 v[132:135], v[144:147], v[160:163], v[132:135]
	v_mfma_f32_16x16x32_bf16 v[124:127], v[152:155], v[160:163], v[124:127]
	v_mfma_f32_16x16x32_bf16 v[116:119], v[144:147], v[168:171], v[116:119]
	v_mfma_f32_16x16x32_bf16 v[112:115], v[152:155], v[168:171], v[112:115]
	v_mfma_f32_16x16x32_bf16 v[100:103], v[144:147], v[194:197], v[100:103]
	v_mfma_f32_16x16x32_bf16 v[96:99], v[152:155], v[194:197], v[96:99]
	v_mfma_f32_16x16x32_bf16 v[84:87], v[144:147], v[202:205], v[84:87]
	v_mfma_f32_16x16x32_bf16 v[80:83], v[152:155], v[202:205], v[80:83]
	v_mfma_f32_16x16x32_bf16 v[132:135], v[148:151], v[164:167], v[132:135]
	v_mfma_f32_16x16x32_bf16 v[124:127], v[156:159], v[164:167], v[124:127]
	v_mfma_f32_16x16x32_bf16 v[116:119], v[148:151], v[172:175], v[116:119]
	v_mfma_f32_16x16x32_bf16 v[112:115], v[156:159], v[172:175], v[112:115]
	s_setprio 2
	s_barrier
	v_mfma_f32_16x16x32_bf16 v[100:103], v[148:151], v[198:201], v[100:103]
	v_mfma_f32_16x16x32_bf16 v[96:99], v[156:159], v[198:201], v[96:99]
	v_mfma_f32_16x16x32_bf16 v[84:87], v[148:151], v[206:209], v[84:87]
	v_mfma_f32_16x16x32_bf16 v[80:83], v[156:159], v[206:209], v[80:83]
	s_setprio 0
	s_add_i32 s8, s64, s37
	s_mov_b32 m0, s8
	ds_read_b128 v[160:163], v231 offset:49152
	ds_read_b128 v[164:167], v231 offset:50176
	ds_read_b128 v[168:171], v231 offset:51200
	ds_read_b128 v[172:175], v231 offset:52224
	ds_read_b128 v[194:197], v231 offset:53248
	ds_read_b128 v[198:201], v231 offset:54272
	ds_read_b128 v[202:205], v231 offset:55296
	ds_read_b128 v[206:209], v231 offset:56320
	global_load_lds_dwordx4 v184, s[98:99]
	s_add_i32 m0, s8, 0x2000
	s_add_u32 s8, s40, 0x60080
	s_addc_u32 s9, s41, 0
	s_add_i32 s40, s65, s37
	global_load_lds_dwordx4 v188, s[98:99]
	s_mov_b32 m0, s40
	s_nop 0
	global_load_lds_dwordx4 v184, s[8:9]
	s_add_i32 m0, s40, 0x2000
	s_nop 0
	global_load_lds_dwordx4 v188, s[8:9]
	s_mov_b32 m0, s69
	s_nop 0
	global_load_lds_dwordx4 v182, s[100:101]
	s_mov_b32 m0, s72
	s_nop 0
	global_load_lds_dwordx4 v186, s[100:101]
	s_waitcnt vmcnt(8) lgkmcnt(0)
	s_barrier
	s_setprio 1
	v_mfma_f32_16x16x32_bf16 v[76:79], v[56:59], v[160:163], v[76:79]
	v_mfma_f32_16x16x32_bf16 v[72:75], v[64:67], v[160:163], v[72:75]
	v_mfma_f32_16x16x32_bf16 v[44:47], v[56:59], v[168:171], v[44:47]
	v_mfma_f32_16x16x32_bf16 v[40:43], v[64:67], v[168:171], v[40:43]
	v_mfma_f32_16x16x32_bf16 v[28:31], v[56:59], v[194:197], v[28:31]
	v_mfma_f32_16x16x32_bf16 v[24:27], v[64:67], v[194:197], v[24:27]
	v_mfma_f32_16x16x32_bf16 v[12:15], v[56:59], v[202:205], v[12:15]
	v_mfma_f32_16x16x32_bf16 v[8:11], v[64:67], v[202:205], v[8:11]
	v_mfma_f32_16x16x32_bf16 v[76:79], v[60:63], v[164:167], v[76:79]
	v_mfma_f32_16x16x32_bf16 v[72:75], v[68:71], v[164:167], v[72:75]
	v_mfma_f32_16x16x32_bf16 v[44:47], v[60:63], v[172:175], v[44:47]
	v_mfma_f32_16x16x32_bf16 v[40:43], v[68:71], v[172:175], v[40:43]
	v_mfma_f32_16x16x32_bf16 v[28:31], v[60:63], v[198:201], v[28:31]
	v_mfma_f32_16x16x32_bf16 v[24:27], v[68:71], v[198:201], v[24:27]
	v_mfma_f32_16x16x32_bf16 v[12:15], v[60:63], v[206:209], v[12:15]
	v_mfma_f32_16x16x32_bf16 v[8:11], v[68:71], v[206:209], v[8:11]
	v_mfma_f32_16x16x32_bf16 v[52:55], v[144:147], v[160:163], v[52:55]
	v_mfma_f32_16x16x32_bf16 v[48:51], v[152:155], v[160:163], v[48:51]
	v_mfma_f32_16x16x32_bf16 v[36:39], v[144:147], v[168:171], v[36:39]
	v_mfma_f32_16x16x32_bf16 v[32:35], v[152:155], v[168:171], v[32:35]
	v_mfma_f32_16x16x32_bf16 v[20:23], v[144:147], v[194:197], v[20:23]
	v_mfma_f32_16x16x32_bf16 v[16:19], v[152:155], v[194:197], v[16:19]
	v_mfma_f32_16x16x32_bf16 v[4:7], v[144:147], v[202:205], v[4:7]
	v_mfma_f32_16x16x32_bf16 v[0:3], v[152:155], v[202:205], v[0:3]
	v_mfma_f32_16x16x32_bf16 v[52:55], v[148:151], v[164:167], v[52:55]
	v_mfma_f32_16x16x32_bf16 v[48:51], v[156:159], v[164:167], v[48:51]
	v_mfma_f32_16x16x32_bf16 v[36:39], v[148:151], v[172:175], v[36:39]
	v_mfma_f32_16x16x32_bf16 v[32:35], v[156:159], v[172:175], v[32:35]
	s_setprio 2
	s_barrier
	v_mfma_f32_16x16x32_bf16 v[20:23], v[148:151], v[198:201], v[20:23]
	v_mfma_f32_16x16x32_bf16 v[16:19], v[156:159], v[198:201], v[16:19]
	v_mfma_f32_16x16x32_bf16 v[4:7], v[148:151], v[206:209], v[4:7]
	v_mfma_f32_16x16x32_bf16 v[0:3], v[156:159], v[206:209], v[0:3]
	s_setprio 0
	s_add_i32 s83, s83, 2
	s_add_u32 s44, s44, 0x180
	s_addc_u32 s53, s53, 0
	s_cmp_gt_u32 s83, 13
	s_mov_b64 s[8:9], s[38:39]
	s_cbranch_scc0 .LBB0_953

.LBB0_1045:
	s_add_i32 s25, s63, -2
	s_add_u32 s93, s38, 0x180
	s_addc_u32 s94, s39, 0
	s_mov_b32 s40, 0
	v_add_u32_e32 v226, 0x10000, v228
	s_add_i32 s64, s40, 2
	s_add_u32 s38, s8, 0x180
	s_addc_u32 s39, s9, 0
	s_add_i32 s65, 0, 0x10000
	s_cmp_eq_u32 s25, s40
	s_cselect_b32 s51, s27, s39
	s_cselect_b32 s50, s26, s38
	s_cselect_b32 s41, s29, s94
	s_cselect_b32 s40, s28, s93
	s_add_i32 s66, 0, 0x14000
	ds_read_b128 v[88:91], v226
	ds_read_b128 v[92:95], v226 offset:1024
	ds_read_b128 v[104:107], v226 offset:2048
	ds_read_b128 v[108:111], v226 offset:3072
	ds_read_b128 v[144:147], v226 offset:16384
	ds_read_b128 v[148:151], v226 offset:17408
	ds_read_b128 v[152:155], v226 offset:18432
	ds_read_b128 v[156:159], v226 offset:19456
	s_add_i32 m0, s72, 0xc000
	ds_read_b128 v[160:163], v232
	ds_read_b128 v[164:167], v232 offset:1024
	ds_read_b128 v[168:171], v232 offset:2048
	ds_read_b128 v[172:175], v232 offset:3072
	ds_read_b128 v[194:197], v232 offset:4096
	ds_read_b128 v[198:201], v232 offset:5120
	ds_read_b128 v[202:205], v232 offset:6144
	ds_read_b128 v[206:209], v232 offset:7168
	global_load_lds_dwordx4 v192, s[8:9]
	s_add_i32 m0, s72, 0xe000
	s_nop 0
	global_load_lds_dwordx4 v190, s[8:9]
	s_waitcnt vmcnt(24) lgkmcnt(0)
	s_barrier
	s_setprio 1
	v_mfma_f32_16x16x32_bf16 v[140:143], v[88:91], v[160:163], 0
	v_mfma_f32_16x16x32_bf16 v[136:139], v[104:107], v[160:163], 0
	v_mfma_f32_16x16x32_bf16 v[124:127], v[88:91], v[168:171], 0
	v_mfma_f32_16x16x32_bf16 v[120:123], v[104:107], v[168:171], 0
	v_mfma_f32_16x16x32_bf16 v[100:103], v[88:91], v[194:197], 0
	v_mfma_f32_16x16x32_bf16 v[96:99], v[104:107], v[194:197], 0
	v_mfma_f32_16x16x32_bf16 v[76:79], v[88:91], v[202:205], 0
	v_mfma_f32_16x16x32_bf16 v[72:75], v[104:107], v[202:205], 0
	v_mfma_f32_16x16x32_bf16 v[140:143], v[92:95], v[164:167], v[140:143]
	v_mfma_f32_16x16x32_bf16 v[136:139], v[108:111], v[164:167], v[136:139]
	v_mfma_f32_16x16x32_bf16 v[124:127], v[92:95], v[172:175], v[124:127]
	v_mfma_f32_16x16x32_bf16 v[120:123], v[108:111], v[172:175], v[120:123]
	v_mfma_f32_16x16x32_bf16 v[100:103], v[92:95], v[198:201], v[100:103]
	v_mfma_f32_16x16x32_bf16 v[96:99], v[108:111], v[198:201], v[96:99]
	v_mfma_f32_16x16x32_bf16 v[76:79], v[92:95], v[206:209], v[76:79]
	v_mfma_f32_16x16x32_bf16 v[72:75], v[108:111], v[206:209], v[72:75]
	v_mfma_f32_16x16x32_bf16 v[132:135], v[144:147], v[160:163], 0
	v_mfma_f32_16x16x32_bf16 v[128:131], v[152:155], v[160:163], 0
	v_mfma_f32_16x16x32_bf16 v[116:119], v[144:147], v[168:171], 0
	v_mfma_f32_16x16x32_bf16 v[112:115], v[152:155], v[168:171], 0
	v_mfma_f32_16x16x32_bf16 v[84:87], v[144:147], v[194:197], 0
	v_mfma_f32_16x16x32_bf16 v[80:83], v[152:155], v[194:197], 0
	v_mfma_f32_16x16x32_bf16 v[68:71], v[144:147], v[202:205], 0
	v_mfma_f32_16x16x32_bf16 v[64:67], v[152:155], v[202:205], 0
	v_mfma_f32_16x16x32_bf16 v[132:135], v[148:151], v[164:167], v[132:135]
	v_mfma_f32_16x16x32_bf16 v[128:131], v[156:159], v[164:167], v[128:131]
	v_mfma_f32_16x16x32_bf16 v[116:119], v[148:151], v[172:175], v[116:119]
	v_mfma_f32_16x16x32_bf16 v[112:115], v[156:159], v[172:175], v[112:115]
	s_setprio 2
	s_barrier
	v_mfma_f32_16x16x32_bf16 v[84:87], v[148:151], v[198:201], v[84:87]
	v_mfma_f32_16x16x32_bf16 v[80:83], v[156:159], v[198:201], v[80:83]
	v_mfma_f32_16x16x32_bf16 v[68:71], v[148:151], v[206:209], v[68:71]
	v_mfma_f32_16x16x32_bf16 v[64:67], v[156:159], v[206:209], v[64:67]
	s_setprio 0
	s_add_i32 s8, s65, s68
	s_add_u32 s98, s40, s34
	s_addc_u32 s99, s41, s35
	s_mov_b32 m0, s8
	ds_read_b128 v[160:163], v232 offset:16384
	ds_read_b128 v[164:167], v232 offset:17408
	ds_read_b128 v[168:171], v232 offset:18432
	ds_read_b128 v[172:175], v232 offset:19456
	ds_read_b128 v[194:197], v232 offset:20480
	ds_read_b128 v[198:201], v232 offset:21504
	ds_read_b128 v[202:205], v232 offset:22528
	ds_read_b128 v[206:209], v232 offset:23552
	global_load_lds_dwordx4 v184, s[40:41]
	s_add_i32 m0, s8, 0x2000
	s_add_u32 s8, s40, 0x60000
	s_addc_u32 s9, s41, 0
	s_add_i32 s65, s66, s68
	global_load_lds_dwordx4 v188, s[40:41]
	s_mov_b32 m0, s65
	s_nop 0
	global_load_lds_dwordx4 v184, s[8:9]
	s_add_i32 m0, s65, 0x2000
	s_nop 0
	global_load_lds_dwordx4 v188, s[8:9]
	s_add_u32 s100, s50, s34
	s_addc_u32 s101, s51, s35
	s_mov_b32 m0, s72
	s_nop 0
	global_load_lds_dwordx4 v182, s[50:51]
	s_waitcnt vmcnt(7) lgkmcnt(0)
	s_barrier
	s_setprio 1
	v_mfma_f32_16x16x32_bf16 v[60:63], v[88:91], v[160:163], 0
	v_mfma_f32_16x16x32_bf16 v[56:59], v[104:107], v[160:163], 0
	v_mfma_f32_16x16x32_bf16 v[44:47], v[88:91], v[168:171], 0
	v_mfma_f32_16x16x32_bf16 v[40:43], v[104:107], v[168:171], 0
	v_mfma_f32_16x16x32_bf16 v[28:31], v[88:91], v[194:197], 0
	v_mfma_f32_16x16x32_bf16 v[24:27], v[104:107], v[194:197], 0
	v_mfma_f32_16x16x32_bf16 v[12:15], v[88:91], v[202:205], 0
	v_mfma_f32_16x16x32_bf16 v[8:11], v[104:107], v[202:205], 0
	v_mfma_f32_16x16x32_bf16 v[60:63], v[92:95], v[164:167], v[60:63]
	v_mfma_f32_16x16x32_bf16 v[56:59], v[108:111], v[164:167], v[56:59]
	v_mfma_f32_16x16x32_bf16 v[44:47], v[92:95], v[172:175], v[44:47]
	v_mfma_f32_16x16x32_bf16 v[40:43], v[108:111], v[172:175], v[40:43]
	v_mfma_f32_16x16x32_bf16 v[28:31], v[92:95], v[198:201], v[28:31]
	v_mfma_f32_16x16x32_bf16 v[24:27], v[108:111], v[198:201], v[24:27]
	v_mfma_f32_16x16x32_bf16 v[12:15], v[92:95], v[206:209], v[12:15]
	v_mfma_f32_16x16x32_bf16 v[8:11], v[108:111], v[206:209], v[8:11]
	v_mfma_f32_16x16x32_bf16 v[52:55], v[144:147], v[160:163], 0
	v_mfma_f32_16x16x32_bf16 v[48:51], v[152:155], v[160:163], 0
	v_mfma_f32_16x16x32_bf16 v[36:39], v[144:147], v[168:171], 0
	v_mfma_f32_16x16x32_bf16 v[32:35], v[152:155], v[168:171], 0
	v_mfma_f32_16x16x32_bf16 v[20:23], v[144:147], v[194:197], 0
	v_mfma_f32_16x16x32_bf16 v[16:19], v[152:155], v[194:197], 0
	v_mfma_f32_16x16x32_bf16 v[4:7], v[144:147], v[202:205], 0
	v_mfma_f32_16x16x32_bf16 v[0:3], v[152:155], v[202:205], 0
	v_mfma_f32_16x16x32_bf16 v[52:55], v[148:151], v[164:167], v[52:55]
	v_mfma_f32_16x16x32_bf16 v[48:51], v[156:159], v[164:167], v[48:51]
	v_mfma_f32_16x16x32_bf16 v[36:39], v[148:151], v[172:175], v[36:39]
	v_mfma_f32_16x16x32_bf16 v[32:35], v[156:159], v[172:175], v[32:35]
	s_setprio 2
	s_barrier
	v_mfma_f32_16x16x32_bf16 v[20:23], v[148:151], v[198:201], v[20:23]
	v_mfma_f32_16x16x32_bf16 v[16:19], v[156:159], v[198:201], v[16:19]
	v_mfma_f32_16x16x32_bf16 v[4:7], v[148:151], v[206:209], v[4:7]
	v_mfma_f32_16x16x32_bf16 v[0:3], v[156:159], v[206:209], v[0:3]
	s_setprio 0
	s_mov_b32 m0, s73
	s_nop 0
	global_load_lds_dwordx4 v186, s[50:51]
	s_add_i32 s65, 0, 0x18000
	s_add_i32 s66, 0, 0x1c000
	ds_read_b128 v[88:91], v226 offset:32768
	ds_read_b128 v[92:95], v226 offset:33792
	ds_read_b128 v[104:107], v226 offset:34816
	ds_read_b128 v[108:111], v226 offset:35840
	ds_read_b128 v[144:147], v226 offset:49152
	ds_read_b128 v[148:151], v226 offset:50176
	ds_read_b128 v[152:155], v226 offset:51200
	ds_read_b128 v[156:159], v226 offset:52224
	s_add_u32 s8, s50, 0x60000
	s_addc_u32 s9, s51, 0
	s_mov_b32 m0, s74
	ds_read_b128 v[160:163], v232 offset:32768
	ds_read_b128 v[164:167], v232 offset:33792
	ds_read_b128 v[168:171], v232 offset:34816
	ds_read_b128 v[172:175], v232 offset:35840
	ds_read_b128 v[194:197], v232 offset:36864
	ds_read_b128 v[198:201], v232 offset:37888
	ds_read_b128 v[202:205], v232 offset:38912
	ds_read_b128 v[206:209], v232 offset:39936
	global_load_lds_dwordx4 v182, s[8:9]
	s_mov_b32 m0, s75
	s_nop 0
	global_load_lds_dwordx4 v186, s[8:9]
	s_waitcnt vmcnt(8) lgkmcnt(0)
	s_barrier
	s_setprio 1
	v_mfma_f32_16x16x32_bf16 v[140:143], v[88:91], v[160:163], v[140:143]
	v_mfma_f32_16x16x32_bf16 v[136:139], v[104:107], v[160:163], v[136:139]
	v_mfma_f32_16x16x32_bf16 v[124:127], v[88:91], v[168:171], v[124:127]
	v_mfma_f32_16x16x32_bf16 v[120:123], v[104:107], v[168:171], v[120:123]
	v_mfma_f32_16x16x32_bf16 v[100:103], v[88:91], v[194:197], v[100:103]
	v_mfma_f32_16x16x32_bf16 v[96:99], v[104:107], v[194:197], v[96:99]
	v_mfma_f32_16x16x32_bf16 v[76:79], v[88:91], v[202:205], v[76:79]
	v_mfma_f32_16x16x32_bf16 v[72:75], v[104:107], v[202:205], v[72:75]
	v_mfma_f32_16x16x32_bf16 v[140:143], v[92:95], v[164:167], v[140:143]
	v_mfma_f32_16x16x32_bf16 v[136:139], v[108:111], v[164:167], v[136:139]
	v_mfma_f32_16x16x32_bf16 v[124:127], v[92:95], v[172:175], v[124:127]
	v_mfma_f32_16x16x32_bf16 v[120:123], v[108:111], v[172:175], v[120:123]
	v_mfma_f32_16x16x32_bf16 v[100:103], v[92:95], v[198:201], v[100:103]
	v_mfma_f32_16x16x32_bf16 v[96:99], v[108:111], v[198:201], v[96:99]
	v_mfma_f32_16x16x32_bf16 v[76:79], v[92:95], v[206:209], v[76:79]
	v_mfma_f32_16x16x32_bf16 v[72:75], v[108:111], v[206:209], v[72:75]
	v_mfma_f32_16x16x32_bf16 v[132:135], v[144:147], v[160:163], v[132:135]
	v_mfma_f32_16x16x32_bf16 v[128:131], v[152:155], v[160:163], v[128:131]
	v_mfma_f32_16x16x32_bf16 v[116:119], v[144:147], v[168:171], v[116:119]
	v_mfma_f32_16x16x32_bf16 v[112:115], v[152:155], v[168:171], v[112:115]
	v_mfma_f32_16x16x32_bf16 v[84:87], v[144:147], v[194:197], v[84:87]
	v_mfma_f32_16x16x32_bf16 v[80:83], v[152:155], v[194:197], v[80:83]
	v_mfma_f32_16x16x32_bf16 v[68:71], v[144:147], v[202:205], v[68:71]
	v_mfma_f32_16x16x32_bf16 v[64:67], v[152:155], v[202:205], v[64:67]
	v_mfma_f32_16x16x32_bf16 v[132:135], v[148:151], v[164:167], v[132:135]
	v_mfma_f32_16x16x32_bf16 v[128:131], v[156:159], v[164:167], v[128:131]
	v_mfma_f32_16x16x32_bf16 v[116:119], v[148:151], v[172:175], v[116:119]
	v_mfma_f32_16x16x32_bf16 v[112:115], v[156:159], v[172:175], v[112:115]
	s_setprio 2
	s_barrier
	v_mfma_f32_16x16x32_bf16 v[84:87], v[148:151], v[198:201], v[84:87]
	v_mfma_f32_16x16x32_bf16 v[80:83], v[156:159], v[198:201], v[80:83]
	v_mfma_f32_16x16x32_bf16 v[68:71], v[148:151], v[206:209], v[68:71]
	v_mfma_f32_16x16x32_bf16 v[64:67], v[156:159], v[206:209], v[64:67]
	s_setprio 0
	s_add_i32 s8, s65, s68
	s_mov_b32 m0, s8
	ds_read_b128 v[160:163], v232 offset:49152
	ds_read_b128 v[164:167], v232 offset:50176
	ds_read_b128 v[168:171], v232 offset:51200
	ds_read_b128 v[172:175], v232 offset:52224
	ds_read_b128 v[194:197], v232 offset:53248
	ds_read_b128 v[198:201], v232 offset:54272
	ds_read_b128 v[202:205], v232 offset:55296
	ds_read_b128 v[206:209], v232 offset:56320
	global_load_lds_dwordx4 v184, s[98:99]
	s_add_i32 m0, s8, 0x2000
	s_add_u32 s8, s40, 0x60080
	s_addc_u32 s9, s41, 0
	s_add_i32 s40, s66, s68
	global_load_lds_dwordx4 v188, s[98:99]
	s_mov_b32 m0, s40
	s_nop 0
	global_load_lds_dwordx4 v184, s[8:9]
	s_add_i32 m0, s40, 0x2000
	s_nop 0
	global_load_lds_dwordx4 v188, s[8:9]
	s_mov_b32 m0, s81
	s_nop 0
	global_load_lds_dwordx4 v182, s[100:101]
	s_mov_b32 m0, s82
	s_nop 0
	global_load_lds_dwordx4 v186, s[100:101]
	s_waitcnt vmcnt(8) lgkmcnt(0)
	s_barrier
	s_setprio 1
	v_mfma_f32_16x16x32_bf16 v[60:63], v[88:91], v[160:163], v[60:63]
	v_mfma_f32_16x16x32_bf16 v[56:59], v[104:107], v[160:163], v[56:59]
	v_mfma_f32_16x16x32_bf16 v[44:47], v[88:91], v[168:171], v[44:47]
	v_mfma_f32_16x16x32_bf16 v[40:43], v[104:107], v[168:171], v[40:43]
	v_mfma_f32_16x16x32_bf16 v[28:31], v[88:91], v[194:197], v[28:31]
	v_mfma_f32_16x16x32_bf16 v[24:27], v[104:107], v[194:197], v[24:27]
	v_mfma_f32_16x16x32_bf16 v[12:15], v[88:91], v[202:205], v[12:15]
	v_mfma_f32_16x16x32_bf16 v[8:11], v[104:107], v[202:205], v[8:11]
	v_mfma_f32_16x16x32_bf16 v[60:63], v[92:95], v[164:167], v[60:63]
	v_mfma_f32_16x16x32_bf16 v[56:59], v[108:111], v[164:167], v[56:59]
	v_mfma_f32_16x16x32_bf16 v[44:47], v[92:95], v[172:175], v[44:47]
	v_mfma_f32_16x16x32_bf16 v[40:43], v[108:111], v[172:175], v[40:43]
	v_mfma_f32_16x16x32_bf16 v[28:31], v[92:95], v[198:201], v[28:31]
	v_mfma_f32_16x16x32_bf16 v[24:27], v[108:111], v[198:201], v[24:27]
	v_mfma_f32_16x16x32_bf16 v[12:15], v[92:95], v[206:209], v[12:15]
	v_mfma_f32_16x16x32_bf16 v[8:11], v[108:111], v[206:209], v[8:11]
	v_mfma_f32_16x16x32_bf16 v[52:55], v[144:147], v[160:163], v[52:55]
	v_mfma_f32_16x16x32_bf16 v[48:51], v[152:155], v[160:163], v[48:51]
	v_mfma_f32_16x16x32_bf16 v[36:39], v[144:147], v[168:171], v[36:39]
	v_mfma_f32_16x16x32_bf16 v[32:35], v[152:155], v[168:171], v[32:35]
	v_mfma_f32_16x16x32_bf16 v[20:23], v[144:147], v[194:197], v[20:23]
	v_mfma_f32_16x16x32_bf16 v[16:19], v[152:155], v[194:197], v[16:19]
	v_mfma_f32_16x16x32_bf16 v[4:7], v[144:147], v[202:205], v[4:7]
	v_mfma_f32_16x16x32_bf16 v[0:3], v[152:155], v[202:205], v[0:3]
	v_mfma_f32_16x16x32_bf16 v[52:55], v[148:151], v[164:167], v[52:55]
	v_mfma_f32_16x16x32_bf16 v[48:51], v[156:159], v[164:167], v[48:51]
	v_mfma_f32_16x16x32_bf16 v[36:39], v[148:151], v[172:175], v[36:39]
	v_mfma_f32_16x16x32_bf16 v[32:35], v[156:159], v[172:175], v[32:35]
	s_setprio 2
	s_barrier
	v_mfma_f32_16x16x32_bf16 v[20:23], v[148:151], v[198:201], v[20:23]
	v_mfma_f32_16x16x32_bf16 v[16:19], v[156:159], v[198:201], v[16:19]
	v_mfma_f32_16x16x32_bf16 v[4:7], v[148:151], v[206:209], v[4:7]
	v_mfma_f32_16x16x32_bf16 v[0:3], v[156:159], v[206:209], v[0:3]
	s_setprio 0
	s_add_u32 s93, s93, 0x180
	s_addc_u32 s94, s94, 0
	s_cmp_ge_i32 s64, s63
	s_mov_b64 s[8:9], s[38:39]
	s_mov_b32 s40, s64
	s_cbranch_scc1 .Lpeel_exit_5
.LBB0_1046:
	s_add_i32 s64, s40, 2
	s_add_u32 s38, s8, 0x180
	s_addc_u32 s39, s9, 0
	s_add_i32 s65, 0, 0x10000
	s_cmp_eq_u32 s25, s40
	s_cselect_b32 s51, s27, s39
	s_cselect_b32 s50, s26, s38
	s_cselect_b32 s41, s29, s94
	s_cselect_b32 s40, s28, s93
	s_add_i32 s66, 0, 0x14000
	ds_read_b128 v[88:91], v226
	ds_read_b128 v[92:95], v226 offset:1024
	ds_read_b128 v[104:107], v226 offset:2048
	ds_read_b128 v[108:111], v226 offset:3072
	ds_read_b128 v[144:147], v226 offset:16384
	ds_read_b128 v[148:151], v226 offset:17408
	ds_read_b128 v[152:155], v226 offset:18432
	ds_read_b128 v[156:159], v226 offset:19456
	s_add_i32 m0, s72, 0xc000
	ds_read_b128 v[160:163], v232
	ds_read_b128 v[164:167], v232 offset:1024
	ds_read_b128 v[168:171], v232 offset:2048
	ds_read_b128 v[172:175], v232 offset:3072
	ds_read_b128 v[194:197], v232 offset:4096
	ds_read_b128 v[198:201], v232 offset:5120
	ds_read_b128 v[202:205], v232 offset:6144
	ds_read_b128 v[206:209], v232 offset:7168
	global_load_lds_dwordx4 v192, s[8:9]
	s_add_i32 m0, s72, 0xe000
	s_nop 0
	global_load_lds_dwordx4 v190, s[8:9]
	s_waitcnt vmcnt(8) lgkmcnt(0)
	s_barrier
	s_setprio 1
	v_mfma_f32_16x16x32_bf16 v[140:143], v[88:91], v[160:163], v[140:143]
	v_mfma_f32_16x16x32_bf16 v[136:139], v[104:107], v[160:163], v[136:139]
	v_mfma_f32_16x16x32_bf16 v[124:127], v[88:91], v[168:171], v[124:127]
	v_mfma_f32_16x16x32_bf16 v[120:123], v[104:107], v[168:171], v[120:123]
	v_mfma_f32_16x16x32_bf16 v[100:103], v[88:91], v[194:197], v[100:103]
	v_mfma_f32_16x16x32_bf16 v[96:99], v[104:107], v[194:197], v[96:99]
	v_mfma_f32_16x16x32_bf16 v[76:79], v[88:91], v[202:205], v[76:79]
	v_mfma_f32_16x16x32_bf16 v[72:75], v[104:107], v[202:205], v[72:75]
	v_mfma_f32_16x16x32_bf16 v[140:143], v[92:95], v[164:167], v[140:143]
	v_mfma_f32_16x16x32_bf16 v[136:139], v[108:111], v[164:167], v[136:139]
	v_mfma_f32_16x16x32_bf16 v[124:127], v[92:95], v[172:175], v[124:127]
	v_mfma_f32_16x16x32_bf16 v[120:123], v[108:111], v[172:175], v[120:123]
	v_mfma_f32_16x16x32_bf16 v[100:103], v[92:95], v[198:201], v[100:103]
	v_mfma_f32_16x16x32_bf16 v[96:99], v[108:111], v[198:201], v[96:99]
	v_mfma_f32_16x16x32_bf16 v[76:79], v[92:95], v[206:209], v[76:79]
	v_mfma_f32_16x16x32_bf16 v[72:75], v[108:111], v[206:209], v[72:75]
	v_mfma_f32_16x16x32_bf16 v[132:135], v[144:147], v[160:163], v[132:135]
	v_mfma_f32_16x16x32_bf16 v[128:131], v[152:155], v[160:163], v[128:131]
	v_mfma_f32_16x16x32_bf16 v[116:119], v[144:147], v[168:171], v[116:119]
	v_mfma_f32_16x16x32_bf16 v[112:115], v[152:155], v[168:171], v[112:115]
	v_mfma_f32_16x16x32_bf16 v[84:87], v[144:147], v[194:197], v[84:87]
	v_mfma_f32_16x16x32_bf16 v[80:83], v[152:155], v[194:197], v[80:83]
	v_mfma_f32_16x16x32_bf16 v[68:71], v[144:147], v[202:205], v[68:71]
	v_mfma_f32_16x16x32_bf16 v[64:67], v[152:155], v[202:205], v[64:67]
	v_mfma_f32_16x16x32_bf16 v[132:135], v[148:151], v[164:167], v[132:135]
	v_mfma_f32_16x16x32_bf16 v[128:131], v[156:159], v[164:167], v[128:131]
	v_mfma_f32_16x16x32_bf16 v[116:119], v[148:151], v[172:175], v[116:119]
	v_mfma_f32_16x16x32_bf16 v[112:115], v[156:159], v[172:175], v[112:115]
	s_setprio 2
	s_barrier
	v_mfma_f32_16x16x32_bf16 v[84:87], v[148:151], v[198:201], v[84:87]
	v_mfma_f32_16x16x32_bf16 v[80:83], v[156:159], v[198:201], v[80:83]
	v_mfma_f32_16x16x32_bf16 v[68:71], v[148:151], v[206:209], v[68:71]
	v_mfma_f32_16x16x32_bf16 v[64:67], v[156:159], v[206:209], v[64:67]
	s_setprio 0
	s_add_i32 s8, s65, s68
	s_add_u32 s98, s40, s34
	s_addc_u32 s99, s41, s35
	s_mov_b32 m0, s8
	ds_read_b128 v[160:163], v232 offset:16384
	ds_read_b128 v[164:167], v232 offset:17408
	ds_read_b128 v[168:171], v232 offset:18432
	ds_read_b128 v[172:175], v232 offset:19456
	ds_read_b128 v[194:197], v232 offset:20480
	ds_read_b128 v[198:201], v232 offset:21504
	ds_read_b128 v[202:205], v232 offset:22528
	ds_read_b128 v[206:209], v232 offset:23552
	global_load_lds_dwordx4 v184, s[40:41]
	s_add_i32 m0, s8, 0x2000
	s_add_u32 s8, s40, 0x60000
	s_addc_u32 s9, s41, 0
	s_add_i32 s65, s66, s68
	global_load_lds_dwordx4 v188, s[40:41]
	s_mov_b32 m0, s65
	s_nop 0
	global_load_lds_dwordx4 v184, s[8:9]
	s_add_i32 m0, s65, 0x2000
	s_nop 0
	global_load_lds_dwordx4 v188, s[8:9]
	s_add_u32 s100, s50, s34
	s_addc_u32 s101, s51, s35
	s_mov_b32 m0, s72
	s_nop 0
	global_load_lds_dwordx4 v182, s[50:51]
	s_waitcnt vmcnt(7) lgkmcnt(0)
	s_barrier
	s_setprio 1
	v_mfma_f32_16x16x32_bf16 v[60:63], v[88:91], v[160:163], v[60:63]
	v_mfma_f32_16x16x32_bf16 v[56:59], v[104:107], v[160:163], v[56:59]
	v_mfma_f32_16x16x32_bf16 v[44:47], v[88:91], v[168:171], v[44:47]
	v_mfma_f32_16x16x32_bf16 v[40:43], v[104:107], v[168:171], v[40:43]
	v_mfma_f32_16x16x32_bf16 v[28:31], v[88:91], v[194:197], v[28:31]
	v_mfma_f32_16x16x32_bf16 v[24:27], v[104:107], v[194:197], v[24:27]
	v_mfma_f32_16x16x32_bf16 v[12:15], v[88:91], v[202:205], v[12:15]
	v_mfma_f32_16x16x32_bf16 v[8:11], v[104:107], v[202:205], v[8:11]
	v_mfma_f32_16x16x32_bf16 v[60:63], v[92:95], v[164:167], v[60:63]
	v_mfma_f32_16x16x32_bf16 v[56:59], v[108:111], v[164:167], v[56:59]
	v_mfma_f32_16x16x32_bf16 v[44:47], v[92:95], v[172:175], v[44:47]
	v_mfma_f32_16x16x32_bf16 v[40:43], v[108:111], v[172:175], v[40:43]
	v_mfma_f32_16x16x32_bf16 v[28:31], v[92:95], v[198:201], v[28:31]
	v_mfma_f32_16x16x32_bf16 v[24:27], v[108:111], v[198:201], v[24:27]
	v_mfma_f32_16x16x32_bf16 v[12:15], v[92:95], v[206:209], v[12:15]
	v_mfma_f32_16x16x32_bf16 v[8:11], v[108:111], v[206:209], v[8:11]
	v_mfma_f32_16x16x32_bf16 v[52:55], v[144:147], v[160:163], v[52:55]
	v_mfma_f32_16x16x32_bf16 v[48:51], v[152:155], v[160:163], v[48:51]
	v_mfma_f32_16x16x32_bf16 v[36:39], v[144:147], v[168:171], v[36:39]
	v_mfma_f32_16x16x32_bf16 v[32:35], v[152:155], v[168:171], v[32:35]
	v_mfma_f32_16x16x32_bf16 v[20:23], v[144:147], v[194:197], v[20:23]
	v_mfma_f32_16x16x32_bf16 v[16:19], v[152:155], v[194:197], v[16:19]
	v_mfma_f32_16x16x32_bf16 v[4:7], v[144:147], v[202:205], v[4:7]
	v_mfma_f32_16x16x32_bf16 v[0:3], v[152:155], v[202:205], v[0:3]
	v_mfma_f32_16x16x32_bf16 v[52:55], v[148:151], v[164:167], v[52:55]
	v_mfma_f32_16x16x32_bf16 v[48:51], v[156:159], v[164:167], v[48:51]
	v_mfma_f32_16x16x32_bf16 v[36:39], v[148:151], v[172:175], v[36:39]
	v_mfma_f32_16x16x32_bf16 v[32:35], v[156:159], v[172:175], v[32:35]
	s_setprio 2
	s_barrier
	v_mfma_f32_16x16x32_bf16 v[20:23], v[148:151], v[198:201], v[20:23]
	v_mfma_f32_16x16x32_bf16 v[16:19], v[156:159], v[198:201], v[16:19]
	v_mfma_f32_16x16x32_bf16 v[4:7], v[148:151], v[206:209], v[4:7]
	v_mfma_f32_16x16x32_bf16 v[0:3], v[156:159], v[206:209], v[0:3]
	s_setprio 0
	s_mov_b32 m0, s73
	s_nop 0
	global_load_lds_dwordx4 v186, s[50:51]
	s_add_i32 s65, 0, 0x18000
	s_add_i32 s66, 0, 0x1c000
	ds_read_b128 v[88:91], v226 offset:32768
	ds_read_b128 v[92:95], v226 offset:33792
	ds_read_b128 v[104:107], v226 offset:34816
	ds_read_b128 v[108:111], v226 offset:35840
	ds_read_b128 v[144:147], v226 offset:49152
	ds_read_b128 v[148:151], v226 offset:50176
	ds_read_b128 v[152:155], v226 offset:51200
	ds_read_b128 v[156:159], v226 offset:52224
	s_add_u32 s8, s50, 0x60000
	s_addc_u32 s9, s51, 0
	s_mov_b32 m0, s74
	ds_read_b128 v[160:163], v232 offset:32768
	ds_read_b128 v[164:167], v232 offset:33792
	ds_read_b128 v[168:171], v232 offset:34816
	ds_read_b128 v[172:175], v232 offset:35840
	ds_read_b128 v[194:197], v232 offset:36864
	ds_read_b128 v[198:201], v232 offset:37888
	ds_read_b128 v[202:205], v232 offset:38912
	ds_read_b128 v[206:209], v232 offset:39936
	global_load_lds_dwordx4 v182, s[8:9]
	s_mov_b32 m0, s75
	s_nop 0
	global_load_lds_dwordx4 v186, s[8:9]
	s_waitcnt vmcnt(8) lgkmcnt(0)
	s_barrier
	s_setprio 1
	v_mfma_f32_16x16x32_bf16 v[140:143], v[88:91], v[160:163], v[140:143]
	v_mfma_f32_16x16x32_bf16 v[136:139], v[104:107], v[160:163], v[136:139]
	v_mfma_f32_16x16x32_bf16 v[124:127], v[88:91], v[168:171], v[124:127]
	v_mfma_f32_16x16x32_bf16 v[120:123], v[104:107], v[168:171], v[120:123]
	v_mfma_f32_16x16x32_bf16 v[100:103], v[88:91], v[194:197], v[100:103]
	v_mfma_f32_16x16x32_bf16 v[96:99], v[104:107], v[194:197], v[96:99]
	v_mfma_f32_16x16x32_bf16 v[76:79], v[88:91], v[202:205], v[76:79]
	v_mfma_f32_16x16x32_bf16 v[72:75], v[104:107], v[202:205], v[72:75]
	v_mfma_f32_16x16x32_bf16 v[140:143], v[92:95], v[164:167], v[140:143]
	v_mfma_f32_16x16x32_bf16 v[136:139], v[108:111], v[164:167], v[136:139]
	v_mfma_f32_16x16x32_bf16 v[124:127], v[92:95], v[172:175], v[124:127]
	v_mfma_f32_16x16x32_bf16 v[120:123], v[108:111], v[172:175], v[120:123]
	v_mfma_f32_16x16x32_bf16 v[100:103], v[92:95], v[198:201], v[100:103]
	v_mfma_f32_16x16x32_bf16 v[96:99], v[108:111], v[198:201], v[96:99]
	v_mfma_f32_16x16x32_bf16 v[76:79], v[92:95], v[206:209], v[76:79]
	v_mfma_f32_16x16x32_bf16 v[72:75], v[108:111], v[206:209], v[72:75]
	v_mfma_f32_16x16x32_bf16 v[132:135], v[144:147], v[160:163], v[132:135]
	v_mfma_f32_16x16x32_bf16 v[128:131], v[152:155], v[160:163], v[128:131]
	v_mfma_f32_16x16x32_bf16 v[116:119], v[144:147], v[168:171], v[116:119]
	v_mfma_f32_16x16x32_bf16 v[112:115], v[152:155], v[168:171], v[112:115]
	v_mfma_f32_16x16x32_bf16 v[84:87], v[144:147], v[194:197], v[84:87]
	v_mfma_f32_16x16x32_bf16 v[80:83], v[152:155], v[194:197], v[80:83]
	v_mfma_f32_16x16x32_bf16 v[68:71], v[144:147], v[202:205], v[68:71]
	v_mfma_f32_16x16x32_bf16 v[64:67], v[152:155], v[202:205], v[64:67]
	v_mfma_f32_16x16x32_bf16 v[132:135], v[148:151], v[164:167], v[132:135]
	v_mfma_f32_16x16x32_bf16 v[128:131], v[156:159], v[164:167], v[128:131]
	v_mfma_f32_16x16x32_bf16 v[116:119], v[148:151], v[172:175], v[116:119]
	v_mfma_f32_16x16x32_bf16 v[112:115], v[156:159], v[172:175], v[112:115]
	s_setprio 2
	s_barrier
	v_mfma_f32_16x16x32_bf16 v[84:87], v[148:151], v[198:201], v[84:87]
	v_mfma_f32_16x16x32_bf16 v[80:83], v[156:159], v[198:201], v[80:83]
	v_mfma_f32_16x16x32_bf16 v[68:71], v[148:151], v[206:209], v[68:71]
	v_mfma_f32_16x16x32_bf16 v[64:67], v[156:159], v[206:209], v[64:67]
	s_setprio 0
	s_add_i32 s8, s65, s68
	s_mov_b32 m0, s8
	ds_read_b128 v[160:163], v232 offset:49152
	ds_read_b128 v[164:167], v232 offset:50176
	ds_read_b128 v[168:171], v232 offset:51200
	ds_read_b128 v[172:175], v232 offset:52224
	ds_read_b128 v[194:197], v232 offset:53248
	ds_read_b128 v[198:201], v232 offset:54272
	ds_read_b128 v[202:205], v232 offset:55296
	ds_read_b128 v[206:209], v232 offset:56320
	global_load_lds_dwordx4 v184, s[98:99]
	s_add_i32 m0, s8, 0x2000
	s_add_u32 s8, s40, 0x60080
	s_addc_u32 s9, s41, 0
	s_add_i32 s40, s66, s68
	global_load_lds_dwordx4 v188, s[98:99]
	s_mov_b32 m0, s40
	s_nop 0
	global_load_lds_dwordx4 v184, s[8:9]
	s_add_i32 m0, s40, 0x2000
	s_nop 0
	global_load_lds_dwordx4 v188, s[8:9]
	s_mov_b32 m0, s81
	s_nop 0
	global_load_lds_dwordx4 v182, s[100:101]
	s_mov_b32 m0, s82
	s_nop 0
	global_load_lds_dwordx4 v186, s[100:101]
	s_waitcnt vmcnt(8) lgkmcnt(0)
	s_barrier
	s_setprio 1
	v_mfma_f32_16x16x32_bf16 v[60:63], v[88:91], v[160:163], v[60:63]
	v_mfma_f32_16x16x32_bf16 v[56:59], v[104:107], v[160:163], v[56:59]
	v_mfma_f32_16x16x32_bf16 v[44:47], v[88:91], v[168:171], v[44:47]
	v_mfma_f32_16x16x32_bf16 v[40:43], v[104:107], v[168:171], v[40:43]
	v_mfma_f32_16x16x32_bf16 v[28:31], v[88:91], v[194:197], v[28:31]
	v_mfma_f32_16x16x32_bf16 v[24:27], v[104:107], v[194:197], v[24:27]
	v_mfma_f32_16x16x32_bf16 v[12:15], v[88:91], v[202:205], v[12:15]
	v_mfma_f32_16x16x32_bf16 v[8:11], v[104:107], v[202:205], v[8:11]
	v_mfma_f32_16x16x32_bf16 v[60:63], v[92:95], v[164:167], v[60:63]
	v_mfma_f32_16x16x32_bf16 v[56:59], v[108:111], v[164:167], v[56:59]
	v_mfma_f32_16x16x32_bf16 v[44:47], v[92:95], v[172:175], v[44:47]
	v_mfma_f32_16x16x32_bf16 v[40:43], v[108:111], v[172:175], v[40:43]
	v_mfma_f32_16x16x32_bf16 v[28:31], v[92:95], v[198:201], v[28:31]
	v_mfma_f32_16x16x32_bf16 v[24:27], v[108:111], v[198:201], v[24:27]
	v_mfma_f32_16x16x32_bf16 v[12:15], v[92:95], v[206:209], v[12:15]
	v_mfma_f32_16x16x32_bf16 v[8:11], v[108:111], v[206:209], v[8:11]
	v_mfma_f32_16x16x32_bf16 v[52:55], v[144:147], v[160:163], v[52:55]
	v_mfma_f32_16x16x32_bf16 v[48:51], v[152:155], v[160:163], v[48:51]
	v_mfma_f32_16x16x32_bf16 v[36:39], v[144:147], v[168:171], v[36:39]
	v_mfma_f32_16x16x32_bf16 v[32:35], v[152:155], v[168:171], v[32:35]
	v_mfma_f32_16x16x32_bf16 v[20:23], v[144:147], v[194:197], v[20:23]
	v_mfma_f32_16x16x32_bf16 v[16:19], v[152:155], v[194:197], v[16:19]
	v_mfma_f32_16x16x32_bf16 v[4:7], v[144:147], v[202:205], v[4:7]
	v_mfma_f32_16x16x32_bf16 v[0:3], v[152:155], v[202:205], v[0:3]
	v_mfma_f32_16x16x32_bf16 v[52:55], v[148:151], v[164:167], v[52:55]
	v_mfma_f32_16x16x32_bf16 v[48:51], v[156:159], v[164:167], v[48:51]
	v_mfma_f32_16x16x32_bf16 v[36:39], v[148:151], v[172:175], v[36:39]
	v_mfma_f32_16x16x32_bf16 v[32:35], v[156:159], v[172:175], v[32:35]
	s_setprio 2
	s_barrier
	v_mfma_f32_16x16x32_bf16 v[20:23], v[148:151], v[198:201], v[20:23]
	v_mfma_f32_16x16x32_bf16 v[16:19], v[156:159], v[198:201], v[16:19]
	v_mfma_f32_16x16x32_bf16 v[4:7], v[148:151], v[206:209], v[4:7]
	v_mfma_f32_16x16x32_bf16 v[0:3], v[156:159], v[206:209], v[0:3]
	s_setprio 0
	s_add_u32 s93, s93, 0x180
	s_addc_u32 s94, s94, 0
	s_cmp_ge_i32 s64, s63
	s_mov_b64 s[8:9], s[38:39]
	s_mov_b32 s40, s64
	s_cbranch_scc0 .LBB0_1046

.LBB0_1220:
	s_ashr_i32 s21, s20, 31
	s_lshl_b64 s[28:29], s[20:21], 19
	s_add_u32 s21, s54, s28
	s_addc_u32 s23, s55, s29
	s_ashr_i32 s27, s26, 31
	s_lshl_b64 s[38:39], s[26:27], 7
	s_add_u32 s28, s21, s38
	s_addc_u32 s29, s23, s39
	s_ashr_i32 s23, s22, 31
	s_lshl_b64 s[50:51], s[22:23], 19
	s_add_u32 s21, s58, s50
	s_addc_u32 s23, s59, s51
	s_add_u32 s38, s21, s38
	s_addc_u32 s39, s23, s39
	s_cmp_lt_i32 s52, 1
	s_cbranch_scc1 .LBB0_1227
	s_and_b64 s[50:51], s[24:25], exec
	s_cselect_b32 s21, s29, s43
	s_cselect_b32 s23, s28, s42
	s_cselect_b32 s27, s39, s5
	s_cselect_b32 s53, s38, s4
	s_add_i32 s63, s52, -2
	s_add_u32 s95, s4, 0x100
	s_addc_u32 vcc_lo, s5, 0
	s_add_u32 s4, s42, 0x40080
	s_addc_u32 s5, s43, 0
	s_mov_b32 s42, 0
	v_add_u32_e32 v226, 0x10000, v228
	s_add_i32 vcc_hi, s42, 2
	s_add_u32 s43, s4, 0xfffc0080
	s_addc_u32 s50, s5, -1
	s_add_i32 s64, 0, 0x10000
	s_cmp_eq_u32 s63, s42
	s_cselect_b32 s51, s21, s50
	s_cselect_b32 s50, s23, s43
	s_cselect_b32 s43, s27, vcc_lo
	s_cselect_b32 s42, s53, s95
	s_add_i32 s66, 0, 0x14000
	ds_read_b128 v[88:91], v226
	ds_read_b128 v[92:95], v226 offset:1024
	ds_read_b128 v[104:107], v226 offset:2048
	ds_read_b128 v[108:111], v226 offset:3072
	ds_read_b128 v[144:147], v226 offset:16384
	ds_read_b128 v[148:151], v226 offset:17408
	ds_read_b128 v[152:155], v226 offset:18432
	ds_read_b128 v[156:159], v226 offset:19456
	s_add_i32 m0, s7, 0xc000
	ds_read_b128 v[160:163], v232
	ds_read_b128 v[164:167], v232 offset:1024
	ds_read_b128 v[168:171], v232 offset:2048
	ds_read_b128 v[172:175], v232 offset:3072
	ds_read_b128 v[194:197], v232 offset:4096
	ds_read_b128 v[198:201], v232 offset:5120
	ds_read_b128 v[202:205], v232 offset:6144
	ds_read_b128 v[206:209], v232 offset:7168
	global_load_lds_dwordx4 v192, s[4:5]
	s_add_i32 m0, s7, 0xe000
	s_nop 0
	global_load_lds_dwordx4 v190, s[4:5]
	s_waitcnt vmcnt(24) lgkmcnt(0)
	s_barrier
	s_setprio 1
	v_mfma_f32_16x16x32_bf16 v[140:143], v[88:91], v[160:163], 0
	v_mfma_f32_16x16x32_bf16 v[136:139], v[104:107], v[160:163], 0
	v_mfma_f32_16x16x32_bf16 v[124:127], v[88:91], v[168:171], 0
	v_mfma_f32_16x16x32_bf16 v[120:123], v[104:107], v[168:171], 0
	v_mfma_f32_16x16x32_bf16 v[100:103], v[88:91], v[194:197], 0
	v_mfma_f32_16x16x32_bf16 v[96:99], v[104:107], v[194:197], 0
	v_mfma_f32_16x16x32_bf16 v[76:79], v[88:91], v[202:205], 0
	v_mfma_f32_16x16x32_bf16 v[72:75], v[104:107], v[202:205], 0
	v_mfma_f32_16x16x32_bf16 v[140:143], v[92:95], v[164:167], v[140:143]
	v_mfma_f32_16x16x32_bf16 v[136:139], v[108:111], v[164:167], v[136:139]
	v_mfma_f32_16x16x32_bf16 v[124:127], v[92:95], v[172:175], v[124:127]
	v_mfma_f32_16x16x32_bf16 v[120:123], v[108:111], v[172:175], v[120:123]
	v_mfma_f32_16x16x32_bf16 v[100:103], v[92:95], v[198:201], v[100:103]
	v_mfma_f32_16x16x32_bf16 v[96:99], v[108:111], v[198:201], v[96:99]
	v_mfma_f32_16x16x32_bf16 v[76:79], v[92:95], v[206:209], v[76:79]
	v_mfma_f32_16x16x32_bf16 v[72:75], v[108:111], v[206:209], v[72:75]
	v_mfma_f32_16x16x32_bf16 v[132:135], v[144:147], v[160:163], 0
	v_mfma_f32_16x16x32_bf16 v[128:131], v[152:155], v[160:163], 0
	v_mfma_f32_16x16x32_bf16 v[116:119], v[144:147], v[168:171], 0
	v_mfma_f32_16x16x32_bf16 v[112:115], v[152:155], v[168:171], 0
	v_mfma_f32_16x16x32_bf16 v[84:87], v[144:147], v[194:197], 0
	v_mfma_f32_16x16x32_bf16 v[80:83], v[152:155], v[194:197], 0
	v_mfma_f32_16x16x32_bf16 v[68:71], v[144:147], v[202:205], 0
	v_mfma_f32_16x16x32_bf16 v[64:67], v[152:155], v[202:205], 0
	v_mfma_f32_16x16x32_bf16 v[132:135], v[148:151], v[164:167], v[132:135]
	v_mfma_f32_16x16x32_bf16 v[128:131], v[156:159], v[164:167], v[128:131]
	v_mfma_f32_16x16x32_bf16 v[116:119], v[148:151], v[172:175], v[116:119]
	v_mfma_f32_16x16x32_bf16 v[112:115], v[156:159], v[172:175], v[112:115]
	s_setprio 2
	s_barrier
	v_mfma_f32_16x16x32_bf16 v[84:87], v[148:151], v[198:201], v[84:87]
	v_mfma_f32_16x16x32_bf16 v[80:83], v[156:159], v[198:201], v[80:83]
	v_mfma_f32_16x16x32_bf16 v[68:71], v[148:151], v[206:209], v[68:71]
	v_mfma_f32_16x16x32_bf16 v[64:67], v[156:159], v[206:209], v[64:67]
	s_setprio 0
	s_add_i32 s64, s64, s72
	s_add_u32 s98, s42, s34
	s_addc_u32 s99, s43, s35
	s_mov_b32 m0, s64
	ds_read_b128 v[160:163], v232 offset:16384
	ds_read_b128 v[164:167], v232 offset:17408
	ds_read_b128 v[168:171], v232 offset:18432
	ds_read_b128 v[172:175], v232 offset:19456
	ds_read_b128 v[194:197], v232 offset:20480
	ds_read_b128 v[198:201], v232 offset:21504
	ds_read_b128 v[202:205], v232 offset:22528
	ds_read_b128 v[206:209], v232 offset:23552
	global_load_lds_dwordx4 v184, s[42:43]
	s_add_i32 m0, s64, 0x2000
	s_add_u32 s64, s42, 0x40000
	s_addc_u32 s65, s43, 0
	s_add_i32 s66, s66, s72
	global_load_lds_dwordx4 v188, s[42:43]
	s_mov_b32 m0, s66
	s_nop 0
	global_load_lds_dwordx4 v184, s[64:65]
	s_add_i32 m0, s66, 0x2000
	s_nop 0
	global_load_lds_dwordx4 v188, s[64:65]
	s_add_u32 s100, s50, s34
	s_addc_u32 s101, s51, s35
	s_mov_b32 m0, s7
	s_nop 0
	global_load_lds_dwordx4 v182, s[50:51]
	s_waitcnt vmcnt(7) lgkmcnt(0)
	s_barrier
	s_setprio 1
	v_mfma_f32_16x16x32_bf16 v[60:63], v[88:91], v[160:163], 0
	v_mfma_f32_16x16x32_bf16 v[56:59], v[104:107], v[160:163], 0
	v_mfma_f32_16x16x32_bf16 v[44:47], v[88:91], v[168:171], 0
	v_mfma_f32_16x16x32_bf16 v[40:43], v[104:107], v[168:171], 0
	v_mfma_f32_16x16x32_bf16 v[28:31], v[88:91], v[194:197], 0
	v_mfma_f32_16x16x32_bf16 v[24:27], v[104:107], v[194:197], 0
	v_mfma_f32_16x16x32_bf16 v[12:15], v[88:91], v[202:205], 0
	v_mfma_f32_16x16x32_bf16 v[8:11], v[104:107], v[202:205], 0
	v_mfma_f32_16x16x32_bf16 v[60:63], v[92:95], v[164:167], v[60:63]
	v_mfma_f32_16x16x32_bf16 v[56:59], v[108:111], v[164:167], v[56:59]
	v_mfma_f32_16x16x32_bf16 v[44:47], v[92:95], v[172:175], v[44:47]
	v_mfma_f32_16x16x32_bf16 v[40:43], v[108:111], v[172:175], v[40:43]
	v_mfma_f32_16x16x32_bf16 v[28:31], v[92:95], v[198:201], v[28:31]
	v_mfma_f32_16x16x32_bf16 v[24:27], v[108:111], v[198:201], v[24:27]
	v_mfma_f32_16x16x32_bf16 v[12:15], v[92:95], v[206:209], v[12:15]
	v_mfma_f32_16x16x32_bf16 v[8:11], v[108:111], v[206:209], v[8:11]
	v_mfma_f32_16x16x32_bf16 v[52:55], v[144:147], v[160:163], 0
	v_mfma_f32_16x16x32_bf16 v[48:51], v[152:155], v[160:163], 0
	v_mfma_f32_16x16x32_bf16 v[36:39], v[144:147], v[168:171], 0
	v_mfma_f32_16x16x32_bf16 v[32:35], v[152:155], v[168:171], 0
	v_mfma_f32_16x16x32_bf16 v[20:23], v[144:147], v[194:197], 0
	v_mfma_f32_16x16x32_bf16 v[16:19], v[152:155], v[194:197], 0
	v_mfma_f32_16x16x32_bf16 v[4:7], v[144:147], v[202:205], 0
	v_mfma_f32_16x16x32_bf16 v[0:3], v[152:155], v[202:205], 0
	v_mfma_f32_16x16x32_bf16 v[52:55], v[148:151], v[164:167], v[52:55]
	v_mfma_f32_16x16x32_bf16 v[48:51], v[156:159], v[164:167], v[48:51]
	v_mfma_f32_16x16x32_bf16 v[36:39], v[148:151], v[172:175], v[36:39]
	v_mfma_f32_16x16x32_bf16 v[32:35], v[156:159], v[172:175], v[32:35]
	s_setprio 2
	s_barrier
	v_mfma_f32_16x16x32_bf16 v[20:23], v[148:151], v[198:201], v[20:23]
	v_mfma_f32_16x16x32_bf16 v[16:19], v[156:159], v[198:201], v[16:19]
	v_mfma_f32_16x16x32_bf16 v[4:7], v[148:151], v[206:209], v[4:7]
	v_mfma_f32_16x16x32_bf16 v[0:3], v[156:159], v[206:209], v[0:3]
	s_setprio 0
	s_mov_b32 m0, s73
	s_nop 0
	global_load_lds_dwordx4 v186, s[50:51]
	s_add_i32 s64, 0, 0x18000
	s_add_i32 s65, 0, 0x1c000
	ds_read_b128 v[88:91], v226 offset:32768
	ds_read_b128 v[92:95], v226 offset:33792
	ds_read_b128 v[104:107], v226 offset:34816
	ds_read_b128 v[108:111], v226 offset:35840
	ds_read_b128 v[144:147], v226 offset:49152
	ds_read_b128 v[148:151], v226 offset:50176
	ds_read_b128 v[152:155], v226 offset:51200
	ds_read_b128 v[156:159], v226 offset:52224
	s_add_u32 s50, s50, 0x40000
	s_addc_u32 s51, s51, 0
	s_mov_b32 m0, s74
	ds_read_b128 v[160:163], v232 offset:32768
	ds_read_b128 v[164:167], v232 offset:33792
	ds_read_b128 v[168:171], v232 offset:34816
	ds_read_b128 v[172:175], v232 offset:35840
	ds_read_b128 v[194:197], v232 offset:36864
	ds_read_b128 v[198:201], v232 offset:37888
	ds_read_b128 v[202:205], v232 offset:38912
	ds_read_b128 v[206:209], v232 offset:39936
	global_load_lds_dwordx4 v182, s[50:51]
	s_mov_b32 m0, s75
	s_nop 0
	global_load_lds_dwordx4 v186, s[50:51]
	s_waitcnt vmcnt(8) lgkmcnt(0)
	s_barrier
	s_setprio 1
	v_mfma_f32_16x16x32_bf16 v[140:143], v[88:91], v[160:163], v[140:143]
	v_mfma_f32_16x16x32_bf16 v[136:139], v[104:107], v[160:163], v[136:139]
	v_mfma_f32_16x16x32_bf16 v[124:127], v[88:91], v[168:171], v[124:127]
	v_mfma_f32_16x16x32_bf16 v[120:123], v[104:107], v[168:171], v[120:123]
	v_mfma_f32_16x16x32_bf16 v[100:103], v[88:91], v[194:197], v[100:103]
	v_mfma_f32_16x16x32_bf16 v[96:99], v[104:107], v[194:197], v[96:99]
	v_mfma_f32_16x16x32_bf16 v[76:79], v[88:91], v[202:205], v[76:79]
	v_mfma_f32_16x16x32_bf16 v[72:75], v[104:107], v[202:205], v[72:75]
	v_mfma_f32_16x16x32_bf16 v[140:143], v[92:95], v[164:167], v[140:143]
	v_mfma_f32_16x16x32_bf16 v[136:139], v[108:111], v[164:167], v[136:139]
	v_mfma_f32_16x16x32_bf16 v[124:127], v[92:95], v[172:175], v[124:127]
	v_mfma_f32_16x16x32_bf16 v[120:123], v[108:111], v[172:175], v[120:123]
	v_mfma_f32_16x16x32_bf16 v[100:103], v[92:95], v[198:201], v[100:103]
	v_mfma_f32_16x16x32_bf16 v[96:99], v[108:111], v[198:201], v[96:99]
	v_mfma_f32_16x16x32_bf16 v[76:79], v[92:95], v[206:209], v[76:79]
	v_mfma_f32_16x16x32_bf16 v[72:75], v[108:111], v[206:209], v[72:75]
	v_mfma_f32_16x16x32_bf16 v[132:135], v[144:147], v[160:163], v[132:135]
	v_mfma_f32_16x16x32_bf16 v[128:131], v[152:155], v[160:163], v[128:131]
	v_mfma_f32_16x16x32_bf16 v[116:119], v[144:147], v[168:171], v[116:119]
	v_mfma_f32_16x16x32_bf16 v[112:115], v[152:155], v[168:171], v[112:115]
	v_mfma_f32_16x16x32_bf16 v[84:87], v[144:147], v[194:197], v[84:87]
	v_mfma_f32_16x16x32_bf16 v[80:83], v[152:155], v[194:197], v[80:83]
	v_mfma_f32_16x16x32_bf16 v[68:71], v[144:147], v[202:205], v[68:71]
	v_mfma_f32_16x16x32_bf16 v[64:67], v[152:155], v[202:205], v[64:67]
	v_mfma_f32_16x16x32_bf16 v[132:135], v[148:151], v[164:167], v[132:135]
	v_mfma_f32_16x16x32_bf16 v[128:131], v[156:159], v[164:167], v[128:131]
	v_mfma_f32_16x16x32_bf16 v[116:119], v[148:151], v[172:175], v[116:119]
	v_mfma_f32_16x16x32_bf16 v[112:115], v[156:159], v[172:175], v[112:115]
	s_setprio 2
	s_barrier
	v_mfma_f32_16x16x32_bf16 v[84:87], v[148:151], v[198:201], v[84:87]
	v_mfma_f32_16x16x32_bf16 v[80:83], v[156:159], v[198:201], v[80:83]
	v_mfma_f32_16x16x32_bf16 v[68:71], v[148:151], v[206:209], v[68:71]
	v_mfma_f32_16x16x32_bf16 v[64:67], v[156:159], v[206:209], v[64:67]
	s_setprio 0
	s_add_i32 s50, s64, s72
	s_mov_b32 m0, s50
	ds_read_b128 v[160:163], v232 offset:49152
	ds_read_b128 v[164:167], v232 offset:50176
	ds_read_b128 v[168:171], v232 offset:51200
	ds_read_b128 v[172:175], v232 offset:52224
	ds_read_b128 v[194:197], v232 offset:53248
	ds_read_b128 v[198:201], v232 offset:54272
	ds_read_b128 v[202:205], v232 offset:55296
	ds_read_b128 v[206:209], v232 offset:56320
	global_load_lds_dwordx4 v184, s[98:99]
	s_add_i32 m0, s50, 0x2000
	s_add_u32 s42, s42, 0x40080
	s_addc_u32 s43, s43, 0
	s_add_i32 s50, s65, s72
	global_load_lds_dwordx4 v188, s[98:99]
	s_mov_b32 m0, s50
	s_nop 0
	global_load_lds_dwordx4 v184, s[42:43]
	s_add_i32 m0, s50, 0x2000
	s_nop 0
	global_load_lds_dwordx4 v188, s[42:43]
	s_mov_b32 m0, s81
	s_nop 0
	global_load_lds_dwordx4 v182, s[100:101]
	s_mov_b32 m0, s82
	s_nop 0
	global_load_lds_dwordx4 v186, s[100:101]
	s_waitcnt vmcnt(8) lgkmcnt(0)
	s_barrier
	s_setprio 1
	v_mfma_f32_16x16x32_bf16 v[60:63], v[88:91], v[160:163], v[60:63]
	v_mfma_f32_16x16x32_bf16 v[56:59], v[104:107], v[160:163], v[56:59]
	v_mfma_f32_16x16x32_bf16 v[44:47], v[88:91], v[168:171], v[44:47]
	v_mfma_f32_16x16x32_bf16 v[40:43], v[104:107], v[168:171], v[40:43]
	v_mfma_f32_16x16x32_bf16 v[28:31], v[88:91], v[194:197], v[28:31]
	v_mfma_f32_16x16x32_bf16 v[24:27], v[104:107], v[194:197], v[24:27]
	v_mfma_f32_16x16x32_bf16 v[12:15], v[88:91], v[202:205], v[12:15]
	v_mfma_f32_16x16x32_bf16 v[8:11], v[104:107], v[202:205], v[8:11]
	v_mfma_f32_16x16x32_bf16 v[60:63], v[92:95], v[164:167], v[60:63]
	v_mfma_f32_16x16x32_bf16 v[56:59], v[108:111], v[164:167], v[56:59]
	v_mfma_f32_16x16x32_bf16 v[44:47], v[92:95], v[172:175], v[44:47]
	v_mfma_f32_16x16x32_bf16 v[40:43], v[108:111], v[172:175], v[40:43]
	v_mfma_f32_16x16x32_bf16 v[28:31], v[92:95], v[198:201], v[28:31]
	v_mfma_f32_16x16x32_bf16 v[24:27], v[108:111], v[198:201], v[24:27]
	v_mfma_f32_16x16x32_bf16 v[12:15], v[92:95], v[206:209], v[12:15]
	v_mfma_f32_16x16x32_bf16 v[8:11], v[108:111], v[206:209], v[8:11]
	v_mfma_f32_16x16x32_bf16 v[52:55], v[144:147], v[160:163], v[52:55]
	v_mfma_f32_16x16x32_bf16 v[48:51], v[152:155], v[160:163], v[48:51]
	v_mfma_f32_16x16x32_bf16 v[36:39], v[144:147], v[168:171], v[36:39]
	v_mfma_f32_16x16x32_bf16 v[32:35], v[152:155], v[168:171], v[32:35]
	v_mfma_f32_16x16x32_bf16 v[20:23], v[144:147], v[194:197], v[20:23]
	v_mfma_f32_16x16x32_bf16 v[16:19], v[152:155], v[194:197], v[16:19]
	v_mfma_f32_16x16x32_bf16 v[4:7], v[144:147], v[202:205], v[4:7]
	v_mfma_f32_16x16x32_bf16 v[0:3], v[152:155], v[202:205], v[0:3]
	v_mfma_f32_16x16x32_bf16 v[52:55], v[148:151], v[164:167], v[52:55]
	v_mfma_f32_16x16x32_bf16 v[48:51], v[156:159], v[164:167], v[48:51]
	v_mfma_f32_16x16x32_bf16 v[36:39], v[148:151], v[172:175], v[36:39]
	v_mfma_f32_16x16x32_bf16 v[32:35], v[156:159], v[172:175], v[32:35]
	s_setprio 2
	s_barrier
	v_mfma_f32_16x16x32_bf16 v[20:23], v[148:151], v[198:201], v[20:23]
	v_mfma_f32_16x16x32_bf16 v[16:19], v[156:159], v[198:201], v[16:19]
	v_mfma_f32_16x16x32_bf16 v[4:7], v[148:151], v[206:209], v[4:7]
	v_mfma_f32_16x16x32_bf16 v[0:3], v[156:159], v[206:209], v[0:3]
	s_setprio 0
	s_add_u32 s95, s95, 0x100
	s_addc_u32 vcc_lo, vcc_lo, 0
	s_add_u32 s4, s4, 0x100
	s_addc_u32 s5, s5, 0
	s_cmp_ge_i32 vcc_hi, s52
	s_mov_b32 s42, vcc_hi
	s_cbranch_scc1 .Lpeel_exit_6
.LBB0_1222:
	s_add_i32 vcc_hi, s42, 2
	s_add_u32 s43, s4, 0xfffc0080
	s_addc_u32 s50, s5, -1
	s_add_i32 s64, 0, 0x10000
	s_cmp_eq_u32 s63, s42
	s_cselect_b32 s51, s21, s50
	s_cselect_b32 s50, s23, s43
	s_cselect_b32 s43, s27, vcc_lo
	s_cselect_b32 s42, s53, s95
	s_add_i32 s66, 0, 0x14000
	ds_read_b128 v[88:91], v226
	ds_read_b128 v[92:95], v226 offset:1024
	ds_read_b128 v[104:107], v226 offset:2048
	ds_read_b128 v[108:111], v226 offset:3072
	ds_read_b128 v[144:147], v226 offset:16384
	ds_read_b128 v[148:151], v226 offset:17408
	ds_read_b128 v[152:155], v226 offset:18432
	ds_read_b128 v[156:159], v226 offset:19456
	s_add_i32 m0, s7, 0xc000
	ds_read_b128 v[160:163], v232
	ds_read_b128 v[164:167], v232 offset:1024
	ds_read_b128 v[168:171], v232 offset:2048
	ds_read_b128 v[172:175], v232 offset:3072
	ds_read_b128 v[194:197], v232 offset:4096
	ds_read_b128 v[198:201], v232 offset:5120
	ds_read_b128 v[202:205], v232 offset:6144
	ds_read_b128 v[206:209], v232 offset:7168
	global_load_lds_dwordx4 v192, s[4:5]
	s_add_i32 m0, s7, 0xe000
	s_nop 0
	global_load_lds_dwordx4 v190, s[4:5]
	s_waitcnt vmcnt(8) lgkmcnt(0)
	s_barrier
	s_setprio 1
	v_mfma_f32_16x16x32_bf16 v[140:143], v[88:91], v[160:163], v[140:143]
	v_mfma_f32_16x16x32_bf16 v[136:139], v[104:107], v[160:163], v[136:139]
	v_mfma_f32_16x16x32_bf16 v[124:127], v[88:91], v[168:171], v[124:127]
	v_mfma_f32_16x16x32_bf16 v[120:123], v[104:107], v[168:171], v[120:123]
	v_mfma_f32_16x16x32_bf16 v[100:103], v[88:91], v[194:197], v[100:103]
	v_mfma_f32_16x16x32_bf16 v[96:99], v[104:107], v[194:197], v[96:99]
	v_mfma_f32_16x16x32_bf16 v[76:79], v[88:91], v[202:205], v[76:79]
	v_mfma_f32_16x16x32_bf16 v[72:75], v[104:107], v[202:205], v[72:75]
	v_mfma_f32_16x16x32_bf16 v[140:143], v[92:95], v[164:167], v[140:143]
	v_mfma_f32_16x16x32_bf16 v[136:139], v[108:111], v[164:167], v[136:139]
	v_mfma_f32_16x16x32_bf16 v[124:127], v[92:95], v[172:175], v[124:127]
	v_mfma_f32_16x16x32_bf16 v[120:123], v[108:111], v[172:175], v[120:123]
	v_mfma_f32_16x16x32_bf16 v[100:103], v[92:95], v[198:201], v[100:103]
	v_mfma_f32_16x16x32_bf16 v[96:99], v[108:111], v[198:201], v[96:99]
	v_mfma_f32_16x16x32_bf16 v[76:79], v[92:95], v[206:209], v[76:79]
	v_mfma_f32_16x16x32_bf16 v[72:75], v[108:111], v[206:209], v[72:75]
	v_mfma_f32_16x16x32_bf16 v[132:135], v[144:147], v[160:163], v[132:135]
	v_mfma_f32_16x16x32_bf16 v[128:131], v[152:155], v[160:163], v[128:131]
	v_mfma_f32_16x16x32_bf16 v[116:119], v[144:147], v[168:171], v[116:119]
	v_mfma_f32_16x16x32_bf16 v[112:115], v[152:155], v[168:171], v[112:115]
	v_mfma_f32_16x16x32_bf16 v[84:87], v[144:147], v[194:197], v[84:87]
	v_mfma_f32_16x16x32_bf16 v[80:83], v[152:155], v[194:197], v[80:83]
	v_mfma_f32_16x16x32_bf16 v[68:71], v[144:147], v[202:205], v[68:71]
	v_mfma_f32_16x16x32_bf16 v[64:67], v[152:155], v[202:205], v[64:67]
	v_mfma_f32_16x16x32_bf16 v[132:135], v[148:151], v[164:167], v[132:135]
	v_mfma_f32_16x16x32_bf16 v[128:131], v[156:159], v[164:167], v[128:131]
	v_mfma_f32_16x16x32_bf16 v[116:119], v[148:151], v[172:175], v[116:119]
	v_mfma_f32_16x16x32_bf16 v[112:115], v[156:159], v[172:175], v[112:115]
	s_setprio 2
	s_barrier
	v_mfma_f32_16x16x32_bf16 v[84:87], v[148:151], v[198:201], v[84:87]
	v_mfma_f32_16x16x32_bf16 v[80:83], v[156:159], v[198:201], v[80:83]
	v_mfma_f32_16x16x32_bf16 v[68:71], v[148:151], v[206:209], v[68:71]
	v_mfma_f32_16x16x32_bf16 v[64:67], v[156:159], v[206:209], v[64:67]
	s_setprio 0
	s_add_i32 s64, s64, s72
	s_add_u32 s98, s42, s34
	s_addc_u32 s99, s43, s35
	s_mov_b32 m0, s64
	ds_read_b128 v[160:163], v232 offset:16384
	ds_read_b128 v[164:167], v232 offset:17408
	ds_read_b128 v[168:171], v232 offset:18432
	ds_read_b128 v[172:175], v232 offset:19456
	ds_read_b128 v[194:197], v232 offset:20480
	ds_read_b128 v[198:201], v232 offset:21504
	ds_read_b128 v[202:205], v232 offset:22528
	ds_read_b128 v[206:209], v232 offset:23552
	global_load_lds_dwordx4 v184, s[42:43]
	s_add_i32 m0, s64, 0x2000
	s_add_u32 s64, s42, 0x40000
	s_addc_u32 s65, s43, 0
	s_add_i32 s66, s66, s72
	global_load_lds_dwordx4 v188, s[42:43]
	s_mov_b32 m0, s66
	s_nop 0
	global_load_lds_dwordx4 v184, s[64:65]
	s_add_i32 m0, s66, 0x2000
	s_nop 0
	global_load_lds_dwordx4 v188, s[64:65]
	s_add_u32 s100, s50, s34
	s_addc_u32 s101, s51, s35
	s_mov_b32 m0, s7
	s_nop 0
	global_load_lds_dwordx4 v182, s[50:51]
	s_waitcnt vmcnt(7) lgkmcnt(0)
	s_barrier
	s_setprio 1
	v_mfma_f32_16x16x32_bf16 v[60:63], v[88:91], v[160:163], v[60:63]
	v_mfma_f32_16x16x32_bf16 v[56:59], v[104:107], v[160:163], v[56:59]
	v_mfma_f32_16x16x32_bf16 v[44:47], v[88:91], v[168:171], v[44:47]
	v_mfma_f32_16x16x32_bf16 v[40:43], v[104:107], v[168:171], v[40:43]
	v_mfma_f32_16x16x32_bf16 v[28:31], v[88:91], v[194:197], v[28:31]
	v_mfma_f32_16x16x32_bf16 v[24:27], v[104:107], v[194:197], v[24:27]
	v_mfma_f32_16x16x32_bf16 v[12:15], v[88:91], v[202:205], v[12:15]
	v_mfma_f32_16x16x32_bf16 v[8:11], v[104:107], v[202:205], v[8:11]
	v_mfma_f32_16x16x32_bf16 v[60:63], v[92:95], v[164:167], v[60:63]
	v_mfma_f32_16x16x32_bf16 v[56:59], v[108:111], v[164:167], v[56:59]
	v_mfma_f32_16x16x32_bf16 v[44:47], v[92:95], v[172:175], v[44:47]
	v_mfma_f32_16x16x32_bf16 v[40:43], v[108:111], v[172:175], v[40:43]
	v_mfma_f32_16x16x32_bf16 v[28:31], v[92:95], v[198:201], v[28:31]
	v_mfma_f32_16x16x32_bf16 v[24:27], v[108:111], v[198:201], v[24:27]
	v_mfma_f32_16x16x32_bf16 v[12:15], v[92:95], v[206:209], v[12:15]
	v_mfma_f32_16x16x32_bf16 v[8:11], v[108:111], v[206:209], v[8:11]
	v_mfma_f32_16x16x32_bf16 v[52:55], v[144:147], v[160:163], v[52:55]
	v_mfma_f32_16x16x32_bf16 v[48:51], v[152:155], v[160:163], v[48:51]
	v_mfma_f32_16x16x32_bf16 v[36:39], v[144:147], v[168:171], v[36:39]
	v_mfma_f32_16x16x32_bf16 v[32:35], v[152:155], v[168:171], v[32:35]
	v_mfma_f32_16x16x32_bf16 v[20:23], v[144:147], v[194:197], v[20:23]
	v_mfma_f32_16x16x32_bf16 v[16:19], v[152:155], v[194:197], v[16:19]
	v_mfma_f32_16x16x32_bf16 v[4:7], v[144:147], v[202:205], v[4:7]
	v_mfma_f32_16x16x32_bf16 v[0:3], v[152:155], v[202:205], v[0:3]
	v_mfma_f32_16x16x32_bf16 v[52:55], v[148:151], v[164:167], v[52:55]
	v_mfma_f32_16x16x32_bf16 v[48:51], v[156:159], v[164:167], v[48:51]
	v_mfma_f32_16x16x32_bf16 v[36:39], v[148:151], v[172:175], v[36:39]
	v_mfma_f32_16x16x32_bf16 v[32:35], v[156:159], v[172:175], v[32:35]
	s_setprio 2
	s_barrier
	v_mfma_f32_16x16x32_bf16 v[20:23], v[148:151], v[198:201], v[20:23]
	v_mfma_f32_16x16x32_bf16 v[16:19], v[156:159], v[198:201], v[16:19]
	v_mfma_f32_16x16x32_bf16 v[4:7], v[148:151], v[206:209], v[4:7]
	v_mfma_f32_16x16x32_bf16 v[0:3], v[156:159], v[206:209], v[0:3]
	s_setprio 0
	s_mov_b32 m0, s73
	s_nop 0
	global_load_lds_dwordx4 v186, s[50:51]
	s_add_i32 s64, 0, 0x18000
	s_add_i32 s65, 0, 0x1c000
	ds_read_b128 v[88:91], v226 offset:32768
	ds_read_b128 v[92:95], v226 offset:33792
	ds_read_b128 v[104:107], v226 offset:34816
	ds_read_b128 v[108:111], v226 offset:35840
	ds_read_b128 v[144:147], v226 offset:49152
	ds_read_b128 v[148:151], v226 offset:50176
	ds_read_b128 v[152:155], v226 offset:51200
	ds_read_b128 v[156:159], v226 offset:52224
	s_add_u32 s50, s50, 0x40000
	s_addc_u32 s51, s51, 0
	s_mov_b32 m0, s74
	ds_read_b128 v[160:163], v232 offset:32768
	ds_read_b128 v[164:167], v232 offset:33792
	ds_read_b128 v[168:171], v232 offset:34816
	ds_read_b128 v[172:175], v232 offset:35840
	ds_read_b128 v[194:197], v232 offset:36864
	ds_read_b128 v[198:201], v232 offset:37888
	ds_read_b128 v[202:205], v232 offset:38912
	ds_read_b128 v[206:209], v232 offset:39936
	global_load_lds_dwordx4 v182, s[50:51]
	s_mov_b32 m0, s75
	s_nop 0
	global_load_lds_dwordx4 v186, s[50:51]
	s_waitcnt vmcnt(8) lgkmcnt(0)
	s_barrier
	s_setprio 1
	v_mfma_f32_16x16x32_bf16 v[140:143], v[88:91], v[160:163], v[140:143]
	v_mfma_f32_16x16x32_bf16 v[136:139], v[104:107], v[160:163], v[136:139]
	v_mfma_f32_16x16x32_bf16 v[124:127], v[88:91], v[168:171], v[124:127]
	v_mfma_f32_16x16x32_bf16 v[120:123], v[104:107], v[168:171], v[120:123]
	v_mfma_f32_16x16x32_bf16 v[100:103], v[88:91], v[194:197], v[100:103]
	v_mfma_f32_16x16x32_bf16 v[96:99], v[104:107], v[194:197], v[96:99]
	v_mfma_f32_16x16x32_bf16 v[76:79], v[88:91], v[202:205], v[76:79]
	v_mfma_f32_16x16x32_bf16 v[72:75], v[104:107], v[202:205], v[72:75]
	v_mfma_f32_16x16x32_bf16 v[140:143], v[92:95], v[164:167], v[140:143]
	v_mfma_f32_16x16x32_bf16 v[136:139], v[108:111], v[164:167], v[136:139]
	v_mfma_f32_16x16x32_bf16 v[124:127], v[92:95], v[172:175], v[124:127]
	v_mfma_f32_16x16x32_bf16 v[120:123], v[108:111], v[172:175], v[120:123]
	v_mfma_f32_16x16x32_bf16 v[100:103], v[92:95], v[198:201], v[100:103]
	v_mfma_f32_16x16x32_bf16 v[96:99], v[108:111], v[198:201], v[96:99]
	v_mfma_f32_16x16x32_bf16 v[76:79], v[92:95], v[206:209], v[76:79]
	v_mfma_f32_16x16x32_bf16 v[72:75], v[108:111], v[206:209], v[72:75]
	v_mfma_f32_16x16x32_bf16 v[132:135], v[144:147], v[160:163], v[132:135]
	v_mfma_f32_16x16x32_bf16 v[128:131], v[152:155], v[160:163], v[128:131]
	v_mfma_f32_16x16x32_bf16 v[116:119], v[144:147], v[168:171], v[116:119]
	v_mfma_f32_16x16x32_bf16 v[112:115], v[152:155], v[168:171], v[112:115]
	v_mfma_f32_16x16x32_bf16 v[84:87], v[144:147], v[194:197], v[84:87]
	v_mfma_f32_16x16x32_bf16 v[80:83], v[152:155], v[194:197], v[80:83]
	v_mfma_f32_16x16x32_bf16 v[68:71], v[144:147], v[202:205], v[68:71]
	v_mfma_f32_16x16x32_bf16 v[64:67], v[152:155], v[202:205], v[64:67]
	v_mfma_f32_16x16x32_bf16 v[132:135], v[148:151], v[164:167], v[132:135]
	v_mfma_f32_16x16x32_bf16 v[128:131], v[156:159], v[164:167], v[128:131]
	v_mfma_f32_16x16x32_bf16 v[116:119], v[148:151], v[172:175], v[116:119]
	v_mfma_f32_16x16x32_bf16 v[112:115], v[156:159], v[172:175], v[112:115]
	s_setprio 2
	s_barrier
	v_mfma_f32_16x16x32_bf16 v[84:87], v[148:151], v[198:201], v[84:87]
	v_mfma_f32_16x16x32_bf16 v[80:83], v[156:159], v[198:201], v[80:83]
	v_mfma_f32_16x16x32_bf16 v[68:71], v[148:151], v[206:209], v[68:71]
	v_mfma_f32_16x16x32_bf16 v[64:67], v[156:159], v[206:209], v[64:67]
	s_setprio 0
	s_add_i32 s50, s64, s72
	s_mov_b32 m0, s50
	ds_read_b128 v[160:163], v232 offset:49152
	ds_read_b128 v[164:167], v232 offset:50176
	ds_read_b128 v[168:171], v232 offset:51200
	ds_read_b128 v[172:175], v232 offset:52224
	ds_read_b128 v[194:197], v232 offset:53248
	ds_read_b128 v[198:201], v232 offset:54272
	ds_read_b128 v[202:205], v232 offset:55296
	ds_read_b128 v[206:209], v232 offset:56320
	global_load_lds_dwordx4 v184, s[98:99]
	s_add_i32 m0, s50, 0x2000
	s_add_u32 s42, s42, 0x40080
	s_addc_u32 s43, s43, 0
	s_add_i32 s50, s65, s72
	global_load_lds_dwordx4 v188, s[98:99]
	s_mov_b32 m0, s50
	s_nop 0
	global_load_lds_dwordx4 v184, s[42:43]
	s_add_i32 m0, s50, 0x2000
	s_nop 0
	global_load_lds_dwordx4 v188, s[42:43]
	s_mov_b32 m0, s81
	s_nop 0
	global_load_lds_dwordx4 v182, s[100:101]
	s_mov_b32 m0, s82
	s_nop 0
	global_load_lds_dwordx4 v186, s[100:101]
	s_waitcnt vmcnt(8) lgkmcnt(0)
	s_barrier
	s_setprio 1
	v_mfma_f32_16x16x32_bf16 v[60:63], v[88:91], v[160:163], v[60:63]
	v_mfma_f32_16x16x32_bf16 v[56:59], v[104:107], v[160:163], v[56:59]
	v_mfma_f32_16x16x32_bf16 v[44:47], v[88:91], v[168:171], v[44:47]
	v_mfma_f32_16x16x32_bf16 v[40:43], v[104:107], v[168:171], v[40:43]
	v_mfma_f32_16x16x32_bf16 v[28:31], v[88:91], v[194:197], v[28:31]
	v_mfma_f32_16x16x32_bf16 v[24:27], v[104:107], v[194:197], v[24:27]
	v_mfma_f32_16x16x32_bf16 v[12:15], v[88:91], v[202:205], v[12:15]
	v_mfma_f32_16x16x32_bf16 v[8:11], v[104:107], v[202:205], v[8:11]
	v_mfma_f32_16x16x32_bf16 v[60:63], v[92:95], v[164:167], v[60:63]
	v_mfma_f32_16x16x32_bf16 v[56:59], v[108:111], v[164:167], v[56:59]
	v_mfma_f32_16x16x32_bf16 v[44:47], v[92:95], v[172:175], v[44:47]
	v_mfma_f32_16x16x32_bf16 v[40:43], v[108:111], v[172:175], v[40:43]
	v_mfma_f32_16x16x32_bf16 v[28:31], v[92:95], v[198:201], v[28:31]
	v_mfma_f32_16x16x32_bf16 v[24:27], v[108:111], v[198:201], v[24:27]
	v_mfma_f32_16x16x32_bf16 v[12:15], v[92:95], v[206:209], v[12:15]
	v_mfma_f32_16x16x32_bf16 v[8:11], v[108:111], v[206:209], v[8:11]
	v_mfma_f32_16x16x32_bf16 v[52:55], v[144:147], v[160:163], v[52:55]
	v_mfma_f32_16x16x32_bf16 v[48:51], v[152:155], v[160:163], v[48:51]
	v_mfma_f32_16x16x32_bf16 v[36:39], v[144:147], v[168:171], v[36:39]
	v_mfma_f32_16x16x32_bf16 v[32:35], v[152:155], v[168:171], v[32:35]
	v_mfma_f32_16x16x32_bf16 v[20:23], v[144:147], v[194:197], v[20:23]
	v_mfma_f32_16x16x32_bf16 v[16:19], v[152:155], v[194:197], v[16:19]
	v_mfma_f32_16x16x32_bf16 v[4:7], v[144:147], v[202:205], v[4:7]
	v_mfma_f32_16x16x32_bf16 v[0:3], v[152:155], v[202:205], v[0:3]
	v_mfma_f32_16x16x32_bf16 v[52:55], v[148:151], v[164:167], v[52:55]
	v_mfma_f32_16x16x32_bf16 v[48:51], v[156:159], v[164:167], v[48:51]
	v_mfma_f32_16x16x32_bf16 v[36:39], v[148:151], v[172:175], v[36:39]
	v_mfma_f32_16x16x32_bf16 v[32:35], v[156:159], v[172:175], v[32:35]
	s_setprio 2
	s_barrier
	v_mfma_f32_16x16x32_bf16 v[20:23], v[148:151], v[198:201], v[20:23]
	v_mfma_f32_16x16x32_bf16 v[16:19], v[156:159], v[198:201], v[16:19]
	v_mfma_f32_16x16x32_bf16 v[4:7], v[148:151], v[206:209], v[4:7]
	v_mfma_f32_16x16x32_bf16 v[0:3], v[156:159], v[206:209], v[0:3]
	s_setprio 0
	s_add_u32 s95, s95, 0x100
	s_addc_u32 vcc_lo, vcc_lo, 0
	s_add_u32 s4, s4, 0x100
	s_addc_u32 s5, s5, 0
	s_cmp_ge_i32 vcc_hi, s52
	s_mov_b32 s42, vcc_hi
	s_cbranch_scc0 .LBB0_1222
